# GEMM K-loops: per-segment s_setprio flips deleted, one static s_setprio 1 for waves 4-7 before each K-loop (reset after)
# baseline (speedup 1.0000x reference)
; #define PG8_STAGE(bufoff, gbase, voff) do { _Pragma("unroll") for (int _i = 0; _i < 2; ++_i) \
;         __builtin_amdgcn_global_load_lds((const unsigned*)((const char*)(gbase) + (voff)[_i]), (PG8_LAS unsigned*)(lds + (bufoff) + ldsw + _i * 8192), 16, 0, 0); } while (0)
; #define PG8_LDA(dst, b, h) do { _Pragma("unroll") for (int m = 0; m < 4; ++m) _Pragma("unroll") for (int k = 0; k < 2; ++k) dst[m][k] = *(const PG8_LAS bf16x8*)(lds + PG8_SA(b, h) + aoff + m * 2048 + k * 1024); } while (0)
; #define PG8_LDB(dst, b, h) do { _Pragma("unroll") for (int n = 0; n < 2; ++n) _Pragma("unroll") for (int k = 0; k < 2; ++k) dst[n][k] = *(const PG8_LAS bf16x8*)(lds + PG8_SB(b, h) + boff + n * 2048 + k * 1024); } while (0)
; #define PG8_SCHED __builtin_amdgcn_sched_barrier(0)
; template <class Epi, class Sched, bool ALIGN_EPI = false, bool SP2 = false>
; __device__ __forceinline__ void gemm_phase(PG8_LAS unsigned char* lds, const Gemm g, const Sched& S, const Epi& E) {
;     ...
;         const char* nA = has_next ? (const char*)g.A + (size_t)nxt.pm * tstepA + (size_t)((nxt.pn / g.kdiv) * g.kmul) * 2 : cA; const char* nB = has_next ? (const char*)g.Bt + (size_t)nxt.pn * tstepB : cB;
; #pragma nounroll
;         for (int t = 0; t < nt; t += 2) {
;             const bool last = (t == nt - 2);
;             const char* a1 = cA + (size_t)(t + 1) * kstep;
;             const char* a2 = last ? nA : cA + (size_t)(t + 2) * kstep; const char* b2 = last ? nB : cB + (size_t)(t + 2) * kstep;
;             const char* a3 = a2 + kstep; const char* b3 = b2 + kstep;
;             if (last && has_next) S.a_ready(nxt);
;             if constexpr (SP2) {
;             PG8_LDB(B0, 0, 0); PG8_LDB(B1, 0, 1); PG8_SCHED; PG8_LDA(At, 0, 0); PG8_STAGE(PG8_SA(1, 1), a1 + hstepA, voffA);
;     ...
; #pragma unroll
;         for (int a = 0; a < 2; ++a)
; #pragma unroll
;             for (int b = 0; b < 2; ++b)
; #pragma unroll
;                 for (int m = 0; m < 4; ++m)
; #pragma unroll
;                     for (int n = 0; n < 2; ++n) acc[a][b][m][n] = (f32x4){0.f, 0.f, 0.f, 0.f};
;         cur = nxt; cA = nA; cB = nB; ++ui;
.LBB0_170:
	s_ashr_i32 s37, s36, 31
	s_lshl_b64 s[46:47], s[36:37], 19
	s_add_u32 s46, s84, s46
	s_addc_u32 s47, s85, s47
	s_and_b64 s[48:49], s[6:7], exec
	s_cselect_b32 s11, s47, s9
	s_cselect_b32 s37, s46, s8
	s_ashr_i32 s35, s34, 31
	s_lshl_b64 s[48:49], s[34:35], 19
	s_add_u32 s48, s92, s48
	s_addc_u32 s49, s93, s49
	s_and_b64 s[52:53], s[6:7], exec
	s_cselect_b32 s35, s49, s51
	s_cselect_b32 s54, s48, s50
	s_add_u32 s8, s8, 0x40080
	s_addc_u32 s9, s9, 0
	s_add_u32 s55, s50, 0x100
	v_mov_b32_e32 v0, 0
	s_addc_u32 s58, s51, 0
	s_mov_b32 s59, -2
	v_mov_b32_e32 v1, v0
	v_mov_b32_e32 v2, v0
	v_mov_b32_e32 v3, v0
	v_mov_b32_e32 v4, v0
	v_mov_b32_e32 v5, v0
	v_mov_b32_e32 v6, v0
	v_mov_b32_e32 v7, v0
	v_mov_b32_e32 v16, v0
	v_mov_b32_e32 v17, v0
	v_mov_b32_e32 v18, v0
	v_mov_b32_e32 v19, v0
	v_mov_b32_e32 v20, v0
	v_mov_b32_e32 v21, v0
	v_mov_b32_e32 v22, v0
	v_mov_b32_e32 v23, v0
	v_mov_b32_e32 v32, v0
	v_mov_b32_e32 v33, v0
	v_mov_b32_e32 v34, v0
	v_mov_b32_e32 v35, v0
	v_mov_b32_e32 v36, v0
	v_mov_b32_e32 v37, v0
	v_mov_b32_e32 v38, v0
	v_mov_b32_e32 v39, v0
	v_mov_b32_e32 v48, v0
	v_mov_b32_e32 v49, v0
	v_mov_b32_e32 v50, v0
	v_mov_b32_e32 v51, v0
	v_mov_b32_e32 v52, v0
	v_mov_b32_e32 v53, v0
	v_mov_b32_e32 v54, v0
	v_mov_b32_e32 v55, v0
	v_mov_b32_e32 v8, v0
	v_mov_b32_e32 v9, v0
	v_mov_b32_e32 v10, v0
	v_mov_b32_e32 v11, v0
	v_mov_b32_e32 v12, v0
	v_mov_b32_e32 v13, v0
	v_mov_b32_e32 v14, v0
	v_mov_b32_e32 v15, v0
	v_mov_b32_e32 v24, v0
	v_mov_b32_e32 v25, v0
	v_mov_b32_e32 v26, v0
	v_mov_b32_e32 v27, v0
	v_mov_b32_e32 v28, v0
	v_mov_b32_e32 v29, v0
	v_mov_b32_e32 v30, v0
	v_mov_b32_e32 v31, v0
	v_mov_b32_e32 v40, v0
	v_mov_b32_e32 v41, v0
	v_mov_b32_e32 v42, v0
	v_mov_b32_e32 v43, v0
	v_mov_b32_e32 v44, v0
	v_mov_b32_e32 v45, v0
	v_mov_b32_e32 v46, v0
	v_mov_b32_e32 v47, v0
	v_mov_b32_e32 v56, v0
	v_mov_b32_e32 v57, v0
	v_mov_b32_e32 v58, v0
	v_mov_b32_e32 v59, v0
	v_mov_b32_e32 v60, v0
	v_mov_b32_e32 v61, v0
	v_mov_b32_e32 v62, v0
	v_mov_b32_e32 v63, v0
	v_mov_b32_e32 v80, v0
	v_mov_b32_e32 v81, v0
	v_mov_b32_e32 v82, v0
	v_mov_b32_e32 v83, v0
	v_mov_b32_e32 v84, v0
	v_mov_b32_e32 v85, v0
	v_mov_b32_e32 v86, v0
	v_mov_b32_e32 v87, v0
	v_mov_b32_e32 v96, v0
	v_mov_b32_e32 v97, v0
	v_mov_b32_e32 v98, v0
	v_mov_b32_e32 v99, v0
	v_mov_b32_e32 v100, v0
	v_mov_b32_e32 v101, v0
	v_mov_b32_e32 v102, v0
	v_mov_b32_e32 v103, v0
	v_mov_b32_e32 v112, v0
	v_mov_b32_e32 v113, v0
	v_mov_b32_e32 v114, v0
	v_mov_b32_e32 v115, v0
	v_mov_b32_e32 v116, v0
	v_mov_b32_e32 v117, v0
	v_mov_b32_e32 v118, v0
	v_mov_b32_e32 v119, v0
	v_mov_b32_e32 v128, v0
	v_mov_b32_e32 v129, v0
	v_mov_b32_e32 v130, v0
	v_mov_b32_e32 v131, v0
	v_mov_b32_e32 v132, v0
	v_mov_b32_e32 v133, v0
	v_mov_b32_e32 v134, v0
	v_mov_b32_e32 v135, v0
	v_mov_b32_e32 v88, v0
	v_mov_b32_e32 v89, v0
	v_mov_b32_e32 v90, v0
	v_mov_b32_e32 v91, v0
	v_mov_b32_e32 v92, v0
	v_mov_b32_e32 v93, v0
	v_mov_b32_e32 v94, v0
	v_mov_b32_e32 v95, v0
	v_mov_b32_e32 v104, v0
	v_mov_b32_e32 v105, v0
	v_mov_b32_e32 v106, v0
	v_mov_b32_e32 v107, v0
	v_mov_b32_e32 v108, v0
	v_mov_b32_e32 v109, v0
	v_mov_b32_e32 v110, v0
	v_mov_b32_e32 v111, v0
	v_mov_b32_e32 v120, v0
	v_mov_b32_e32 v121, v0
	v_mov_b32_e32 v122, v0
	v_mov_b32_e32 v123, v0
	v_mov_b32_e32 v124, v0
	v_mov_b32_e32 v125, v0
	v_mov_b32_e32 v126, v0
	v_mov_b32_e32 v127, v0
	v_mov_b32_e32 v136, v0
	v_mov_b32_e32 v137, v0
	v_mov_b32_e32 v138, v0
	v_mov_b32_e32 v139, v0
	v_mov_b32_e32 v140, v0
	v_mov_b32_e32 v141, v0
	v_mov_b32_e32 v142, v0
	v_mov_b32_e32 v143, v0
	v_readfirstlane_b32 s100, v198
	s_nop 3
	s_bitcmp1_b32 s100, 8
	s_cbranch_scc0 .Lgprio_0_skip
	s_setprio 1
.Lgprio_0_skip:
.LBB0_171:
	v_add_u32_e32 v76, 0x10000, v162
	v_add_u32_e32 v158, 0x14000, v162
	ds_read_b128 v[64:67], v76
	ds_read_b128 v[68:71], v76 offset:1024
	ds_read_b128 v[72:75], v76 offset:2048
	ds_read_b128 v[76:79], v76 offset:3072
	ds_read_b128 v[154:157], v158
	ds_read_b128 v[164:167], v158 offset:1024
	ds_read_b128 v[168:171], v158 offset:2048
	ds_read_b128 v[172:175], v158 offset:3072
	ds_read_b128 v[176:179], v163
	ds_read_b128 v[180:183], v163 offset:1024
	ds_read_b128 v[184:187], v163 offset:2048
	ds_read_b128 v[194:197], v163 offset:3072
	ds_read_b128 v[230:233], v163 offset:4096
	ds_read_b128 v[234:237], v163 offset:5120
	ds_read_b128 v[238:241], v163 offset:6144
	ds_read_b128 v[242:245], v163 offset:7168
	s_add_u32 s50, s8, 0xfffc0080
	s_addc_u32 s51, s9, -1
	s_add_i32 s60, 0, 0x10000
	s_cmp_eq_u32 s59, 12
	s_cselect_b32 s53, s11, s51
	s_cselect_b32 s52, s37, s50
	s_cselect_b32 s51, s35, s58
	s_cselect_b32 s50, s54, s55
	s_add_i32 s62, 0, 0x14000
	s_add_i32 m0, s57, 0xc000
	v_lshl_add_u64 v[158:159], s[8:9], 0, v[150:151]
	global_load_lds_dwordx4 v[158:159], off
	s_add_i32 m0, s57, 0xe000
	v_lshl_add_u64 v[158:159], s[8:9], 0, v[152:153]
	global_load_lds_dwordx4 v[158:159], off
	s_waitcnt vmcnt(8)
	s_waitcnt lgkmcnt(0)
	s_barrier
; #define PG8_STAGE(bufoff, gbase, voff) do { _Pragma("unroll") for (int _i = 0; _i < 2; ++_i) \
;         __builtin_amdgcn_global_load_lds((const unsigned*)((const char*)(gbase) + (voff)[_i]), (PG8_LAS unsigned*)(lds + (bufoff) + ldsw + _i * 8192), 16, 0, 0); } while (0)
; #define PG8_LDA(dst, b, h) do { _Pragma("unroll") for (int m = 0; m < 4; ++m) _Pragma("unroll") for (int k = 0; k < 2; ++k) dst[m][k] = *(const PG8_LAS bf16x8*)(lds + PG8_SA(b, h) + aoff + m * 2048 + k * 1024); } while (0)
; #define PG8_MMA(ai, bj, At, Bt) do { __builtin_amdgcn_s_setprio(1); _Pragma("unroll") for (int m = 0; m < 4; ++m) _Pragma("unroll") for (int n = 0; n < 2; ++n) _Pragma("unroll") for (int k = 0; k < 2; ++k) \
;         acc[ai][bj][m][n] = __builtin_amdgcn_mfma_f32_16x16x32_bf16(Bt[n][k], At[m][k], acc[ai][bj][m][n], 0, 0, 0); __builtin_amdgcn_s_setprio(0); } while (0)
; #define PG8_WAIT_V(n) asm volatile("s_waitcnt vmcnt(" #n ")" ::: "memory")
; #define PG8_WAIT_L(n) asm volatile("s_waitcnt lgkmcnt(" #n ")" ::: "memory")
; #define PG8_BAR __builtin_amdgcn_s_barrier()
; #define PG8_SCHED __builtin_amdgcn_sched_barrier(0)
; template <class Epi, class Sched, bool ALIGN_EPI = false, bool SP2 = false>
; __device__ __forceinline__ void gemm_phase(PG8_LAS unsigned char* lds, const Gemm g, const Sched& S, const Epi& E) {
;     ...
;             PG8_WAIT_V(8); PG8_WAIT_L(0); PG8_BAR; PG8_MMA(0, 0, At, B0); PG8_MMA(0, 1, At, B1); PG8_BAR; PG8_SCHED;
;             PG8_LDA(At, 0, 1); PG8_STAGE(PG8_SB(0, 0), b2, voffB); PG8_STAGE(PG8_SB(0, 1), b2 + hstepB, voffB); PG8_STAGE(PG8_SA(0, 0), a2, voffA);
;             PG8_WAIT_V(8); PG8_WAIT_L(0); PG8_BAR; PG8_MMA(1, 0, At, B0); PG8_MMA(1, 1, At, B1); PG8_BAR; PG8_SCHED;
	s_waitcnt lgkmcnt(0)
	v_mfma_f32_16x16x32_bf16 v[140:143], v[64:67], v[176:179], v[140:143]
	v_mfma_f32_16x16x32_bf16 v[136:139], v[72:75], v[176:179], v[136:139]
	v_mfma_f32_16x16x32_bf16 v[124:127], v[64:67], v[184:187], v[124:127]
	v_mfma_f32_16x16x32_bf16 v[120:123], v[72:75], v[184:187], v[120:123]
	v_mfma_f32_16x16x32_bf16 v[108:111], v[64:67], v[230:233], v[108:111]
	v_mfma_f32_16x16x32_bf16 v[104:107], v[72:75], v[230:233], v[104:107]
	v_mfma_f32_16x16x32_bf16 v[92:95], v[64:67], v[238:241], v[92:95]
	v_mfma_f32_16x16x32_bf16 v[88:91], v[72:75], v[238:241], v[88:91]
	v_mfma_f32_16x16x32_bf16 v[140:143], v[68:71], v[180:183], v[140:143]
	v_mfma_f32_16x16x32_bf16 v[136:139], v[76:79], v[180:183], v[136:139]
	v_mfma_f32_16x16x32_bf16 v[124:127], v[68:71], v[194:197], v[124:127]
	v_mfma_f32_16x16x32_bf16 v[120:123], v[76:79], v[194:197], v[120:123]
	v_mfma_f32_16x16x32_bf16 v[108:111], v[68:71], v[234:237], v[108:111]
	v_mfma_f32_16x16x32_bf16 v[104:107], v[76:79], v[234:237], v[104:107]
	v_mfma_f32_16x16x32_bf16 v[92:95], v[68:71], v[242:245], v[92:95]
	v_mfma_f32_16x16x32_bf16 v[88:91], v[76:79], v[242:245], v[88:91]
	v_mfma_f32_16x16x32_bf16 v[132:135], v[154:157], v[176:179], v[132:135]
	v_mfma_f32_16x16x32_bf16 v[128:131], v[168:171], v[176:179], v[128:131]
	v_mfma_f32_16x16x32_bf16 v[116:119], v[154:157], v[184:187], v[116:119]
	v_mfma_f32_16x16x32_bf16 v[112:115], v[168:171], v[184:187], v[112:115]
	v_mfma_f32_16x16x32_bf16 v[100:103], v[154:157], v[230:233], v[100:103]
	v_mfma_f32_16x16x32_bf16 v[96:99], v[168:171], v[230:233], v[96:99]
	v_mfma_f32_16x16x32_bf16 v[84:87], v[154:157], v[238:241], v[84:87]
	v_mfma_f32_16x16x32_bf16 v[80:83], v[168:171], v[238:241], v[80:83]
	v_mfma_f32_16x16x32_bf16 v[132:135], v[164:167], v[180:183], v[132:135]
	v_mfma_f32_16x16x32_bf16 v[128:131], v[172:175], v[180:183], v[128:131]
	v_mfma_f32_16x16x32_bf16 v[116:119], v[164:167], v[194:197], v[116:119]
	v_mfma_f32_16x16x32_bf16 v[112:115], v[172:175], v[194:197], v[112:115]
	v_mfma_f32_16x16x32_bf16 v[100:103], v[164:167], v[234:237], v[100:103]
	v_mfma_f32_16x16x32_bf16 v[96:99], v[172:175], v[234:237], v[96:99]
	v_mfma_f32_16x16x32_bf16 v[84:87], v[164:167], v[242:245], v[84:87]
	v_mfma_f32_16x16x32_bf16 v[80:83], v[172:175], v[242:245], v[80:83]
	s_barrier
	ds_read_b128 v[176:179], v163 offset:16384
	ds_read_b128 v[180:183], v163 offset:17408
	ds_read_b128 v[184:187], v163 offset:18432
	ds_read_b128 v[194:197], v163 offset:19456
	ds_read_b128 v[230:233], v163 offset:20480
	ds_read_b128 v[234:237], v163 offset:21504
	ds_read_b128 v[238:241], v163 offset:22528
	ds_read_b128 v[242:245], v163 offset:23552
	s_add_i32 s60, s60, s69
	s_mov_b32 m0, s60
	v_lshl_add_u64 v[158:159], s[50:51], 0, v[188:189]
	global_load_lds_dwordx4 v[158:159], off
	s_add_i32 m0, s60, 0x2000
	s_add_u32 s60, s50, 0x40000
	v_lshl_add_u64 v[246:247], s[50:51], 0, v[148:149]
	s_addc_u32 s61, s51, 0
	s_add_i32 s62, s62, s69
	global_load_lds_dwordx4 v[246:247], off
	v_lshl_add_u64 v[248:249], s[60:61], 0, v[188:189]
	s_mov_b32 m0, s62
	v_lshl_add_u64 v[250:251], s[52:53], 0, v[146:147]
	global_load_lds_dwordx4 v[248:249], off
	s_add_i32 m0, s62, 0x2000
	v_lshl_add_u64 v[248:249], s[60:61], 0, v[148:149]
	global_load_lds_dwordx4 v[248:249], off
	s_mov_b32 m0, s57
	v_lshl_add_u64 v[248:249], s[52:53], 0, v[144:145]
	global_load_lds_dwordx4 v[248:249], off
	s_mov_b32 m0, s78
	s_nop 0
	global_load_lds_dwordx4 v[250:251], off
	s_waitcnt vmcnt(8)
	s_waitcnt lgkmcnt(0)
	s_barrier
	s_waitcnt lgkmcnt(0)
	v_mfma_f32_16x16x32_bf16 v[60:63], v[64:67], v[176:179], v[60:63]
	v_mfma_f32_16x16x32_bf16 v[56:59], v[72:75], v[176:179], v[56:59]
	v_mfma_f32_16x16x32_bf16 v[44:47], v[64:67], v[184:187], v[44:47]
	v_mfma_f32_16x16x32_bf16 v[40:43], v[72:75], v[184:187], v[40:43]
	v_mfma_f32_16x16x32_bf16 v[28:31], v[64:67], v[230:233], v[28:31]
	v_mfma_f32_16x16x32_bf16 v[24:27], v[72:75], v[230:233], v[24:27]
	v_mfma_f32_16x16x32_bf16 v[12:15], v[64:67], v[238:241], v[12:15]
	v_mfma_f32_16x16x32_bf16 v[8:11], v[72:75], v[238:241], v[8:11]
	v_mfma_f32_16x16x32_bf16 v[60:63], v[68:71], v[180:183], v[60:63]
	v_mfma_f32_16x16x32_bf16 v[56:59], v[76:79], v[180:183], v[56:59]
	v_mfma_f32_16x16x32_bf16 v[44:47], v[68:71], v[194:197], v[44:47]
	v_mfma_f32_16x16x32_bf16 v[40:43], v[76:79], v[194:197], v[40:43]
	v_mfma_f32_16x16x32_bf16 v[28:31], v[68:71], v[234:237], v[28:31]
	v_mfma_f32_16x16x32_bf16 v[24:27], v[76:79], v[234:237], v[24:27]
	v_mfma_f32_16x16x32_bf16 v[12:15], v[68:71], v[242:245], v[12:15]
	v_mfma_f32_16x16x32_bf16 v[8:11], v[76:79], v[242:245], v[8:11]
	v_mfma_f32_16x16x32_bf16 v[52:55], v[154:157], v[176:179], v[52:55]
	v_mfma_f32_16x16x32_bf16 v[48:51], v[168:171], v[176:179], v[48:51]
	v_mfma_f32_16x16x32_bf16 v[36:39], v[154:157], v[184:187], v[36:39]
	v_mfma_f32_16x16x32_bf16 v[32:35], v[168:171], v[184:187], v[32:35]
	v_mfma_f32_16x16x32_bf16 v[20:23], v[154:157], v[230:233], v[20:23]
	v_mfma_f32_16x16x32_bf16 v[16:19], v[168:171], v[230:233], v[16:19]
	v_mfma_f32_16x16x32_bf16 v[4:7], v[154:157], v[238:241], v[4:7]
	v_mfma_f32_16x16x32_bf16 v[0:3], v[168:171], v[238:241], v[0:3]
	v_mfma_f32_16x16x32_bf16 v[52:55], v[164:167], v[180:183], v[52:55]
	v_mfma_f32_16x16x32_bf16 v[48:51], v[172:175], v[180:183], v[48:51]
	v_mfma_f32_16x16x32_bf16 v[36:39], v[164:167], v[194:197], v[36:39]
	v_mfma_f32_16x16x32_bf16 v[32:35], v[172:175], v[194:197], v[32:35]
	v_mfma_f32_16x16x32_bf16 v[20:23], v[164:167], v[234:237], v[20:23]
	v_mfma_f32_16x16x32_bf16 v[16:19], v[172:175], v[234:237], v[16:19]
	v_mfma_f32_16x16x32_bf16 v[4:7], v[164:167], v[242:245], v[4:7]
	v_mfma_f32_16x16x32_bf16 v[0:3], v[172:175], v[242:245], v[0:3]
	s_barrier
; #define PG8_STAGE(bufoff, gbase, voff) do { _Pragma("unroll") for (int _i = 0; _i < 2; ++_i) \
;         __builtin_amdgcn_global_load_lds((const unsigned*)((const char*)(gbase) + (voff)[_i]), (PG8_LAS unsigned*)(lds + (bufoff) + ldsw + _i * 8192), 16, 0, 0); } while (0)
; #define PG8_LDA(dst, b, h) do { _Pragma("unroll") for (int m = 0; m < 4; ++m) _Pragma("unroll") for (int k = 0; k < 2; ++k) dst[m][k] = *(const PG8_LAS bf16x8*)(lds + PG8_SA(b, h) + aoff + m * 2048 + k * 1024); } while (0)
; #define PG8_LDB(dst, b, h) do { _Pragma("unroll") for (int n = 0; n < 2; ++n) _Pragma("unroll") for (int k = 0; k < 2; ++k) dst[n][k] = *(const PG8_LAS bf16x8*)(lds + PG8_SB(b, h) + boff + n * 2048 + k * 1024); } while (0)
; #define PG8_MMA(ai, bj, At, Bt) do { __builtin_amdgcn_s_setprio(1); _Pragma("unroll") for (int m = 0; m < 4; ++m) _Pragma("unroll") for (int n = 0; n < 2; ++n) _Pragma("unroll") for (int k = 0; k < 2; ++k) \
;         acc[ai][bj][m][n] = __builtin_amdgcn_mfma_f32_16x16x32_bf16(Bt[n][k], At[m][k], acc[ai][bj][m][n], 0, 0, 0); __builtin_amdgcn_s_setprio(0); } while (0)
; #define PG8_WAIT_V(n) asm volatile("s_waitcnt vmcnt(" #n ")" ::: "memory")
; #define PG8_WAIT_L(n) asm volatile("s_waitcnt lgkmcnt(" #n ")" ::: "memory")
; #define PG8_BAR __builtin_amdgcn_s_barrier()
; #define PG8_SCHED __builtin_amdgcn_sched_barrier(0)
; template <class Epi, class Sched, bool ALIGN_EPI = false, bool SP2 = false>
; __device__ __forceinline__ void gemm_phase(PG8_LAS unsigned char* lds, const Gemm g, const Sched& S, const Epi& E) {
;     ...
;             PG8_LDB(B0, 1, 0); PG8_LDB(B1, 1, 1); PG8_SCHED; PG8_LDA(At, 1, 0); PG8_STAGE(PG8_SA(0, 1), a2 + hstepA, voffA);
;             PG8_WAIT_V(8); PG8_WAIT_L(0); PG8_BAR; PG8_MMA(0, 0, At, B0); PG8_MMA(0, 1, At, B1); PG8_BAR; PG8_SCHED;
;             PG8_LDA(At, 1, 1); PG8_STAGE(PG8_SB(1, 0), b3, voffB); PG8_STAGE(PG8_SB(1, 1), b3 + hstepB, voffB); PG8_STAGE(PG8_SA(1, 0), a3, voffA);
;             PG8_WAIT_V(8); PG8_WAIT_L(0); PG8_BAR; PG8_MMA(1, 0, At, B0); PG8_MMA(1, 1, At, B1); PG8_BAR; PG8_SCHED;
	v_add_u32_e32 v76, 0x18000, v162
	v_add_u32_e32 v172, 0x1c000, v162
	ds_read_b128 v[64:67], v76
	ds_read_b128 v[68:71], v76 offset:1024
	ds_read_b128 v[72:75], v76 offset:2048
	ds_read_b128 v[76:79], v76 offset:3072
	ds_read_b128 v[154:157], v172
	ds_read_b128 v[164:167], v172 offset:1024
	ds_read_b128 v[168:171], v172 offset:2048
	ds_read_b128 v[172:175], v172 offset:3072
	ds_read_b128 v[176:179], v163 offset:32768
	ds_read_b128 v[180:183], v163 offset:33792
	ds_read_b128 v[184:187], v163 offset:34816
	ds_read_b128 v[194:197], v163 offset:35840
	ds_read_b128 v[230:233], v163 offset:36864
	ds_read_b128 v[234:237], v163 offset:37888
	ds_read_b128 v[238:241], v163 offset:38912
	ds_read_b128 v[242:245], v163 offset:39936
	s_add_i32 s60, 0, 0x18000
	s_add_i32 s61, 0, 0x1c000
	s_add_u32 s52, s52, 0x40000
	s_addc_u32 s53, s53, 0
	s_mov_b32 m0, s81
	v_lshl_add_u64 v[252:253], s[52:53], 0, v[144:145]
	global_load_lds_dwordx4 v[252:253], off
	s_mov_b32 m0, s80
	v_lshl_add_u64 v[252:253], s[52:53], 0, v[146:147]
	global_load_lds_dwordx4 v[252:253], off
	s_waitcnt vmcnt(8)
	s_waitcnt lgkmcnt(0)
	s_barrier
	s_waitcnt lgkmcnt(0)
	v_mfma_f32_16x16x32_bf16 v[140:143], v[64:67], v[176:179], v[140:143]
	v_mfma_f32_16x16x32_bf16 v[136:139], v[72:75], v[176:179], v[136:139]
	v_mfma_f32_16x16x32_bf16 v[124:127], v[64:67], v[184:187], v[124:127]
	v_mfma_f32_16x16x32_bf16 v[120:123], v[72:75], v[184:187], v[120:123]
	v_mfma_f32_16x16x32_bf16 v[108:111], v[64:67], v[230:233], v[108:111]
	v_mfma_f32_16x16x32_bf16 v[104:107], v[72:75], v[230:233], v[104:107]
	v_mfma_f32_16x16x32_bf16 v[92:95], v[64:67], v[238:241], v[92:95]
	v_mfma_f32_16x16x32_bf16 v[88:91], v[72:75], v[238:241], v[88:91]
	v_mfma_f32_16x16x32_bf16 v[140:143], v[68:71], v[180:183], v[140:143]
	v_mfma_f32_16x16x32_bf16 v[136:139], v[76:79], v[180:183], v[136:139]
	v_mfma_f32_16x16x32_bf16 v[124:127], v[68:71], v[194:197], v[124:127]
	v_mfma_f32_16x16x32_bf16 v[120:123], v[76:79], v[194:197], v[120:123]
	v_mfma_f32_16x16x32_bf16 v[108:111], v[68:71], v[234:237], v[108:111]
	v_mfma_f32_16x16x32_bf16 v[104:107], v[76:79], v[234:237], v[104:107]
	v_mfma_f32_16x16x32_bf16 v[92:95], v[68:71], v[242:245], v[92:95]
	v_mfma_f32_16x16x32_bf16 v[88:91], v[76:79], v[242:245], v[88:91]
	v_mfma_f32_16x16x32_bf16 v[132:135], v[154:157], v[176:179], v[132:135]
	v_mfma_f32_16x16x32_bf16 v[128:131], v[168:171], v[176:179], v[128:131]
	v_mfma_f32_16x16x32_bf16 v[116:119], v[154:157], v[184:187], v[116:119]
	v_mfma_f32_16x16x32_bf16 v[112:115], v[168:171], v[184:187], v[112:115]
	v_mfma_f32_16x16x32_bf16 v[100:103], v[154:157], v[230:233], v[100:103]
	v_mfma_f32_16x16x32_bf16 v[96:99], v[168:171], v[230:233], v[96:99]
	v_mfma_f32_16x16x32_bf16 v[84:87], v[154:157], v[238:241], v[84:87]
	v_mfma_f32_16x16x32_bf16 v[80:83], v[168:171], v[238:241], v[80:83]
	v_mfma_f32_16x16x32_bf16 v[132:135], v[164:167], v[180:183], v[132:135]
	v_mfma_f32_16x16x32_bf16 v[128:131], v[172:175], v[180:183], v[128:131]
	v_mfma_f32_16x16x32_bf16 v[116:119], v[164:167], v[194:197], v[116:119]
	v_mfma_f32_16x16x32_bf16 v[112:115], v[172:175], v[194:197], v[112:115]
	v_mfma_f32_16x16x32_bf16 v[100:103], v[164:167], v[234:237], v[100:103]
	v_mfma_f32_16x16x32_bf16 v[96:99], v[172:175], v[234:237], v[96:99]
	v_mfma_f32_16x16x32_bf16 v[84:87], v[164:167], v[242:245], v[84:87]
	v_mfma_f32_16x16x32_bf16 v[80:83], v[172:175], v[242:245], v[80:83]
	s_barrier
	ds_read_b128 v[176:179], v163 offset:49152
	ds_read_b128 v[180:183], v163 offset:50176
	ds_read_b128 v[184:187], v163 offset:51200
	ds_read_b128 v[194:197], v163 offset:52224
	ds_read_b128 v[230:233], v163 offset:53248
	ds_read_b128 v[234:237], v163 offset:54272
	ds_read_b128 v[238:241], v163 offset:55296
	ds_read_b128 v[242:245], v163 offset:56320
	s_add_i32 s52, s60, s69
	s_mov_b32 m0, s52
	v_lshl_add_u64 v[158:159], v[158:159], 0, s[94:95]
	global_load_lds_dwordx4 v[158:159], off
	s_add_i32 m0, s52, 0x2000
	s_add_u32 s50, s50, 0x40080
	v_lshl_add_u64 v[158:159], v[246:247], 0, s[94:95]
	s_addc_u32 s51, s51, 0
	s_add_i32 s52, s61, s69
	global_load_lds_dwordx4 v[158:159], off
	s_mov_b32 m0, s52
	v_lshl_add_u64 v[158:159], s[50:51], 0, v[188:189]
	global_load_lds_dwordx4 v[158:159], off
	s_add_i32 m0, s52, 0x2000
	v_lshl_add_u64 v[158:159], s[50:51], 0, v[148:149]
	global_load_lds_dwordx4 v[158:159], off
	s_mov_b32 m0, s2
	v_lshl_add_u64 v[158:159], v[248:249], 0, s[94:95]
	global_load_lds_dwordx4 v[158:159], off
	s_mov_b32 m0, s4
	v_lshl_add_u64 v[158:159], v[250:251], 0, s[94:95]
	global_load_lds_dwordx4 v[158:159], off
	s_waitcnt vmcnt(8)
	s_waitcnt lgkmcnt(0)
	s_barrier
	s_waitcnt lgkmcnt(0)
	v_mfma_f32_16x16x32_bf16 v[60:63], v[64:67], v[176:179], v[60:63]
	v_mfma_f32_16x16x32_bf16 v[56:59], v[72:75], v[176:179], v[56:59]
	v_mfma_f32_16x16x32_bf16 v[44:47], v[64:67], v[184:187], v[44:47]
	v_mfma_f32_16x16x32_bf16 v[40:43], v[72:75], v[184:187], v[40:43]
	v_mfma_f32_16x16x32_bf16 v[28:31], v[64:67], v[230:233], v[28:31]
	v_mfma_f32_16x16x32_bf16 v[24:27], v[72:75], v[230:233], v[24:27]
	v_mfma_f32_16x16x32_bf16 v[12:15], v[64:67], v[238:241], v[12:15]
	v_mfma_f32_16x16x32_bf16 v[8:11], v[72:75], v[238:241], v[8:11]
	v_mfma_f32_16x16x32_bf16 v[60:63], v[68:71], v[180:183], v[60:63]
	v_mfma_f32_16x16x32_bf16 v[56:59], v[76:79], v[180:183], v[56:59]
	v_mfma_f32_16x16x32_bf16 v[44:47], v[68:71], v[194:197], v[44:47]
	v_mfma_f32_16x16x32_bf16 v[40:43], v[76:79], v[194:197], v[40:43]
	v_mfma_f32_16x16x32_bf16 v[28:31], v[68:71], v[234:237], v[28:31]
	v_mfma_f32_16x16x32_bf16 v[24:27], v[76:79], v[234:237], v[24:27]
	v_mfma_f32_16x16x32_bf16 v[12:15], v[68:71], v[242:245], v[12:15]
	v_mfma_f32_16x16x32_bf16 v[8:11], v[76:79], v[242:245], v[8:11]
	v_mfma_f32_16x16x32_bf16 v[52:55], v[154:157], v[176:179], v[52:55]
	v_mfma_f32_16x16x32_bf16 v[48:51], v[168:171], v[176:179], v[48:51]
	v_mfma_f32_16x16x32_bf16 v[36:39], v[154:157], v[184:187], v[36:39]
	v_mfma_f32_16x16x32_bf16 v[32:35], v[168:171], v[184:187], v[32:35]
	v_mfma_f32_16x16x32_bf16 v[20:23], v[154:157], v[230:233], v[20:23]
	v_mfma_f32_16x16x32_bf16 v[16:19], v[168:171], v[230:233], v[16:19]
	v_mfma_f32_16x16x32_bf16 v[4:7], v[154:157], v[238:241], v[4:7]
	v_mfma_f32_16x16x32_bf16 v[0:3], v[168:171], v[238:241], v[0:3]
	v_mfma_f32_16x16x32_bf16 v[52:55], v[164:167], v[180:183], v[52:55]
	v_mfma_f32_16x16x32_bf16 v[48:51], v[172:175], v[180:183], v[48:51]
	v_mfma_f32_16x16x32_bf16 v[36:39], v[164:167], v[194:197], v[36:39]
	v_mfma_f32_16x16x32_bf16 v[32:35], v[172:175], v[194:197], v[32:35]
	v_mfma_f32_16x16x32_bf16 v[20:23], v[164:167], v[234:237], v[20:23]
	v_mfma_f32_16x16x32_bf16 v[16:19], v[172:175], v[234:237], v[16:19]
	v_mfma_f32_16x16x32_bf16 v[4:7], v[164:167], v[242:245], v[4:7]
	v_mfma_f32_16x16x32_bf16 v[0:3], v[172:175], v[242:245], v[0:3]
	s_barrier
	s_add_i32 s59, s59, 2
	s_add_u32 s8, s8, 0x100
	s_addc_u32 s9, s9, 0
	s_add_u32 s55, s55, 0x100
	s_addc_u32 s58, s58, 0
	s_cmp_gt_u32 s59, 13
	s_cbranch_scc0 .LBB0_171
	s_setprio 0
	s_and_b64 vcc, exec, s[30:31]
	s_cbranch_vccz .LBB0_174
	s_barrier

; #define PG8_STAGE(bufoff, gbase, voff) do { _Pragma("unroll") for (int _i = 0; _i < 2; ++_i) \
;         __builtin_amdgcn_global_load_lds((const unsigned*)((const char*)(gbase) + (voff)[_i]), (PG8_LAS unsigned*)(lds + (bufoff) + ldsw + _i * 8192), 16, 0, 0); } while (0)
; #define PG8_LDA(dst, b, h) do { _Pragma("unroll") for (int m = 0; m < 4; ++m) _Pragma("unroll") for (int k = 0; k < 2; ++k) dst[m][k] = *(const PG8_LAS bf16x8*)(lds + PG8_SA(b, h) + aoff + m * 2048 + k * 1024); } while (0)
; #define PG8_LDB(dst, b, h) do { _Pragma("unroll") for (int n = 0; n < 2; ++n) _Pragma("unroll") for (int k = 0; k < 2; ++k) dst[n][k] = *(const PG8_LAS bf16x8*)(lds + PG8_SB(b, h) + boff + n * 2048 + k * 1024); } while (0)
; #define PG8_SCHED __builtin_amdgcn_sched_barrier(0)
; template <class Epi, class Sched, bool ALIGN_EPI = false, bool SP2 = false>
; __device__ __forceinline__ void gemm_phase(PG8_LAS unsigned char* lds, const Gemm g, const Sched& S, const Epi& E) {
;     ...
;         const char* nA = has_next ? (const char*)g.A + (size_t)nxt.pm * tstepA + (size_t)((nxt.pn / g.kdiv) * g.kmul) * 2 : cA; const char* nB = has_next ? (const char*)g.Bt + (size_t)nxt.pn * tstepB : cB;
; #pragma nounroll
;         for (int t = 0; t < nt; t += 2) {
;             const bool last = (t == nt - 2);
;             const char* a1 = cA + (size_t)(t + 1) * kstep;
;             const char* a2 = last ? nA : cA + (size_t)(t + 2) * kstep; const char* b2 = last ? nB : cB + (size_t)(t + 2) * kstep;
;             const char* a3 = a2 + kstep; const char* b3 = b2 + kstep;
;             if (last && has_next) S.a_ready(nxt);
;             if constexpr (SP2) {
;             PG8_LDB(B0, 0, 0); PG8_LDB(B1, 0, 1); PG8_SCHED; PG8_LDA(At, 0, 0); PG8_STAGE(PG8_SA(1, 1), a1 + hstepA, voffA);
;     ...
; #pragma unroll
;         for (int a = 0; a < 2; ++a)
; #pragma unroll
;             for (int b = 0; b < 2; ++b)
; #pragma unroll
;                 for (int m = 0; m < 4; ++m)
; #pragma unroll
;                     for (int n = 0; n < 2; ++n) acc[a][b][m][n] = (f32x4){0.f, 0.f, 0.f, 0.f};
;         cur = nxt; cA = nA; cB = nB; ++ui;
.LBB0_711:
	s_ashr_i32 s19, s18, 31
	s_lshl_b64 s[2:3], s[18:19], 19
	s_add_u32 s20, s35, s2
	s_addc_u32 s21, s36, s3
	s_and_b64 s[2:3], s[6:7], exec
	s_cselect_b32 s1, s21, s27
	s_cselect_b32 s2, s20, s26
	s_ashr_i32 s17, s16, 31
	s_lshl_b64 s[22:23], s[16:17], 19
	s_add_u32 s22, s37, s22
	s_addc_u32 s23, s38, s23
	s_and_b64 s[30:31], s[6:7], exec
	s_cselect_b32 s3, s23, s29
	s_cselect_b32 s4, s22, s28
	s_add_u32 s26, s26, 0x40080
	s_addc_u32 s27, s27, 0
	s_add_u32 s9, s28, 0x100
	v_mov_b32_e32 v0, 0
	s_addc_u32 s17, s29, 0
	s_mov_b32 s19, -2
	v_mov_b32_e32 v1, v0
	v_mov_b32_e32 v2, v0
	v_mov_b32_e32 v3, v0
	v_mov_b32_e32 v4, v0
	v_mov_b32_e32 v5, v0
	v_mov_b32_e32 v6, v0
	v_mov_b32_e32 v7, v0
	v_mov_b32_e32 v16, v0
	v_mov_b32_e32 v17, v0
	v_mov_b32_e32 v18, v0
	v_mov_b32_e32 v19, v0
	v_mov_b32_e32 v20, v0
	v_mov_b32_e32 v21, v0
	v_mov_b32_e32 v22, v0
	v_mov_b32_e32 v23, v0
	v_mov_b32_e32 v32, v0
	v_mov_b32_e32 v33, v0
	v_mov_b32_e32 v34, v0
	v_mov_b32_e32 v35, v0
	v_mov_b32_e32 v36, v0
	v_mov_b32_e32 v37, v0
	v_mov_b32_e32 v38, v0
	v_mov_b32_e32 v39, v0
	v_mov_b32_e32 v48, v0
	v_mov_b32_e32 v49, v0
	v_mov_b32_e32 v50, v0
	v_mov_b32_e32 v51, v0
	v_mov_b32_e32 v52, v0
	v_mov_b32_e32 v53, v0
	v_mov_b32_e32 v54, v0
	v_mov_b32_e32 v55, v0
	v_mov_b32_e32 v8, v0
	v_mov_b32_e32 v9, v0
	v_mov_b32_e32 v10, v0
	v_mov_b32_e32 v11, v0
	v_mov_b32_e32 v12, v0
	v_mov_b32_e32 v13, v0
	v_mov_b32_e32 v14, v0
	v_mov_b32_e32 v15, v0
	v_mov_b32_e32 v24, v0
	v_mov_b32_e32 v25, v0
	v_mov_b32_e32 v26, v0
	v_mov_b32_e32 v27, v0
	v_mov_b32_e32 v28, v0
	v_mov_b32_e32 v29, v0
	v_mov_b32_e32 v30, v0
	v_mov_b32_e32 v31, v0
	v_mov_b32_e32 v40, v0
	v_mov_b32_e32 v41, v0
	v_mov_b32_e32 v42, v0
	v_mov_b32_e32 v43, v0
	v_mov_b32_e32 v44, v0
	v_mov_b32_e32 v45, v0
	v_mov_b32_e32 v46, v0
	v_mov_b32_e32 v47, v0
	v_mov_b32_e32 v56, v0
	v_mov_b32_e32 v57, v0
	v_mov_b32_e32 v58, v0
	v_mov_b32_e32 v59, v0
	v_mov_b32_e32 v60, v0
	v_mov_b32_e32 v61, v0
	v_mov_b32_e32 v62, v0
	v_mov_b32_e32 v63, v0
	v_mov_b32_e32 v64, v0
	v_mov_b32_e32 v65, v0
	v_mov_b32_e32 v66, v0
	v_mov_b32_e32 v67, v0
	v_mov_b32_e32 v68, v0
	v_mov_b32_e32 v69, v0
	v_mov_b32_e32 v70, v0
	v_mov_b32_e32 v71, v0
	v_mov_b32_e32 v80, v0
	v_mov_b32_e32 v81, v0
	v_mov_b32_e32 v82, v0
	v_mov_b32_e32 v83, v0
	v_mov_b32_e32 v84, v0
	v_mov_b32_e32 v85, v0
	v_mov_b32_e32 v86, v0
	v_mov_b32_e32 v87, v0
	v_mov_b32_e32 v96, v0
	v_mov_b32_e32 v97, v0
	v_mov_b32_e32 v98, v0
	v_mov_b32_e32 v99, v0
	v_mov_b32_e32 v100, v0
	v_mov_b32_e32 v101, v0
	v_mov_b32_e32 v102, v0
	v_mov_b32_e32 v103, v0
	v_mov_b32_e32 v112, v0
	v_mov_b32_e32 v113, v0
	v_mov_b32_e32 v114, v0
	v_mov_b32_e32 v115, v0
	v_mov_b32_e32 v116, v0
	v_mov_b32_e32 v117, v0
	v_mov_b32_e32 v118, v0
	v_mov_b32_e32 v119, v0
	v_mov_b32_e32 v72, v0
	v_mov_b32_e32 v73, v0
	v_mov_b32_e32 v74, v0
	v_mov_b32_e32 v75, v0
	v_mov_b32_e32 v76, v0
	v_mov_b32_e32 v77, v0
	v_mov_b32_e32 v78, v0
	v_mov_b32_e32 v79, v0
	v_mov_b32_e32 v88, v0
	v_mov_b32_e32 v89, v0
	v_mov_b32_e32 v90, v0
	v_mov_b32_e32 v91, v0
	v_mov_b32_e32 v92, v0
	v_mov_b32_e32 v93, v0
	v_mov_b32_e32 v94, v0
	v_mov_b32_e32 v95, v0
	v_mov_b32_e32 v104, v0
	v_mov_b32_e32 v105, v0
	v_mov_b32_e32 v106, v0
	v_mov_b32_e32 v107, v0
	v_mov_b32_e32 v108, v0
	v_mov_b32_e32 v109, v0
	v_mov_b32_e32 v110, v0
	v_mov_b32_e32 v111, v0
	v_mov_b32_e32 v120, v0
	v_mov_b32_e32 v121, v0
	v_mov_b32_e32 v122, v0
	v_mov_b32_e32 v123, v0
	v_mov_b32_e32 v124, v0
	v_mov_b32_e32 v125, v0
	v_mov_b32_e32 v126, v0
	v_mov_b32_e32 v127, v0
	v_readfirstlane_b32 s100, v198
	s_nop 3
	s_bitcmp1_b32 s100, 8
	s_cbranch_scc0 .Lgprio_1_skip
	s_setprio 1
.Lgprio_1_skip:
.LBB0_712:
	v_add_u32_e32 v154, 0x10000, v144
	v_add_u32_e32 v170, 0x14000, v144
	ds_read_b128 v[138:141], v154
	ds_read_b128 v[146:149], v154 offset:1024
	ds_read_b128 v[150:153], v154 offset:2048
	ds_read_b128 v[154:157], v154 offset:3072
	ds_read_b128 v[158:161], v170
	ds_read_b128 v[162:165], v170 offset:1024
	ds_read_b128 v[166:169], v170 offset:2048
	ds_read_b128 v[170:173], v170 offset:3072
	ds_read_b128 v[174:177], v145
	ds_read_b128 v[178:181], v145 offset:1024
	ds_read_b128 v[182:185], v145 offset:2048
	ds_read_b128 v[192:195], v145 offset:3072
	ds_read_b128 v[230:233], v145 offset:4096
	ds_read_b128 v[234:237], v145 offset:5120
	ds_read_b128 v[238:241], v145 offset:6144
	ds_read_b128 v[242:245], v145 offset:7168
	s_add_u32 s28, s26, 0xfffc0080
	s_addc_u32 s29, s27, -1
	s_add_i32 s33, 0, 0x10000
	s_cmp_eq_u32 s19, 12
	s_cselect_b32 s31, s1, s29
	s_cselect_b32 s30, s2, s28
	s_cselect_b32 s29, s3, s17
	s_cselect_b32 s28, s4, s9
	s_add_i32 s51, 0, 0x14000
	s_add_i32 m0, s25, 0xc000
	v_lshl_add_u64 v[186:187], s[26:27], 0, v[134:135]
	global_load_lds_dwordx4 v[186:187], off
	s_add_i32 m0, s25, 0xe000
	v_lshl_add_u64 v[186:187], s[26:27], 0, v[136:137]
	global_load_lds_dwordx4 v[186:187], off
	s_waitcnt vmcnt(8)
	s_waitcnt lgkmcnt(0)
	s_barrier
; #define PG8_STAGE(bufoff, gbase, voff) do { _Pragma("unroll") for (int _i = 0; _i < 2; ++_i) \
;         __builtin_amdgcn_global_load_lds((const unsigned*)((const char*)(gbase) + (voff)[_i]), (PG8_LAS unsigned*)(lds + (bufoff) + ldsw + _i * 8192), 16, 0, 0); } while (0)
; #define PG8_LDA(dst, b, h) do { _Pragma("unroll") for (int m = 0; m < 4; ++m) _Pragma("unroll") for (int k = 0; k < 2; ++k) dst[m][k] = *(const PG8_LAS bf16x8*)(lds + PG8_SA(b, h) + aoff + m * 2048 + k * 1024); } while (0)
; #define PG8_MMA(ai, bj, At, Bt) do { __builtin_amdgcn_s_setprio(1); _Pragma("unroll") for (int m = 0; m < 4; ++m) _Pragma("unroll") for (int n = 0; n < 2; ++n) _Pragma("unroll") for (int k = 0; k < 2; ++k) \
;         acc[ai][bj][m][n] = __builtin_amdgcn_mfma_f32_16x16x32_bf16(Bt[n][k], At[m][k], acc[ai][bj][m][n], 0, 0, 0); __builtin_amdgcn_s_setprio(0); } while (0)
; #define PG8_WAIT_V(n) asm volatile("s_waitcnt vmcnt(" #n ")" ::: "memory")
; #define PG8_WAIT_L(n) asm volatile("s_waitcnt lgkmcnt(" #n ")" ::: "memory")
; #define PG8_BAR __builtin_amdgcn_s_barrier()
; #define PG8_SCHED __builtin_amdgcn_sched_barrier(0)
; template <class Epi, class Sched, bool ALIGN_EPI = false, bool SP2 = false>
; __device__ __forceinline__ void gemm_phase(PG8_LAS unsigned char* lds, const Gemm g, const Sched& S, const Epi& E) {
;     ...
;             PG8_WAIT_V(8); PG8_WAIT_L(0); PG8_BAR; PG8_MMA(0, 0, At, B0); PG8_MMA(0, 1, At, B1); PG8_BAR; PG8_SCHED;
;             PG8_LDA(At, 0, 1); PG8_STAGE(PG8_SB(0, 0), b2, voffB); PG8_STAGE(PG8_SB(0, 1), b2 + hstepB, voffB); PG8_STAGE(PG8_SA(0, 0), a2, voffA);
;             PG8_WAIT_V(8); PG8_WAIT_L(0); PG8_BAR; PG8_MMA(1, 0, At, B0); PG8_MMA(1, 1, At, B1); PG8_BAR; PG8_SCHED;
	s_waitcnt lgkmcnt(0)
	v_mfma_f32_16x16x32_bf16 v[124:127], v[138:141], v[174:177], v[124:127]
	v_mfma_f32_16x16x32_bf16 v[120:123], v[150:153], v[174:177], v[120:123]
	v_mfma_f32_16x16x32_bf16 v[108:111], v[138:141], v[182:185], v[108:111]
	v_mfma_f32_16x16x32_bf16 v[104:107], v[150:153], v[182:185], v[104:107]
	v_mfma_f32_16x16x32_bf16 v[92:95], v[138:141], v[230:233], v[92:95]
	v_mfma_f32_16x16x32_bf16 v[88:91], v[150:153], v[230:233], v[88:91]
	v_mfma_f32_16x16x32_bf16 v[76:79], v[138:141], v[238:241], v[76:79]
	v_mfma_f32_16x16x32_bf16 v[72:75], v[150:153], v[238:241], v[72:75]
	v_mfma_f32_16x16x32_bf16 v[124:127], v[146:149], v[178:181], v[124:127]
	v_mfma_f32_16x16x32_bf16 v[120:123], v[154:157], v[178:181], v[120:123]
	v_mfma_f32_16x16x32_bf16 v[108:111], v[146:149], v[192:195], v[108:111]
	v_mfma_f32_16x16x32_bf16 v[104:107], v[154:157], v[192:195], v[104:107]
	v_mfma_f32_16x16x32_bf16 v[92:95], v[146:149], v[234:237], v[92:95]
	v_mfma_f32_16x16x32_bf16 v[88:91], v[154:157], v[234:237], v[88:91]
	v_mfma_f32_16x16x32_bf16 v[76:79], v[146:149], v[242:245], v[76:79]
	v_mfma_f32_16x16x32_bf16 v[72:75], v[154:157], v[242:245], v[72:75]
	v_mfma_f32_16x16x32_bf16 v[116:119], v[158:161], v[174:177], v[116:119]
	v_mfma_f32_16x16x32_bf16 v[112:115], v[166:169], v[174:177], v[112:115]
	v_mfma_f32_16x16x32_bf16 v[100:103], v[158:161], v[182:185], v[100:103]
	v_mfma_f32_16x16x32_bf16 v[96:99], v[166:169], v[182:185], v[96:99]
	v_mfma_f32_16x16x32_bf16 v[84:87], v[158:161], v[230:233], v[84:87]
	v_mfma_f32_16x16x32_bf16 v[80:83], v[166:169], v[230:233], v[80:83]
	v_mfma_f32_16x16x32_bf16 v[68:71], v[158:161], v[238:241], v[68:71]
	v_mfma_f32_16x16x32_bf16 v[64:67], v[166:169], v[238:241], v[64:67]
	v_mfma_f32_16x16x32_bf16 v[116:119], v[162:165], v[178:181], v[116:119]
	v_mfma_f32_16x16x32_bf16 v[112:115], v[170:173], v[178:181], v[112:115]
	v_mfma_f32_16x16x32_bf16 v[100:103], v[162:165], v[192:195], v[100:103]
	v_mfma_f32_16x16x32_bf16 v[96:99], v[170:173], v[192:195], v[96:99]
	v_mfma_f32_16x16x32_bf16 v[84:87], v[162:165], v[234:237], v[84:87]
	v_mfma_f32_16x16x32_bf16 v[80:83], v[170:173], v[234:237], v[80:83]
	v_mfma_f32_16x16x32_bf16 v[68:71], v[162:165], v[242:245], v[68:71]
	v_mfma_f32_16x16x32_bf16 v[64:67], v[170:173], v[242:245], v[64:67]
	s_barrier
	ds_read_b128 v[174:177], v145 offset:16384
	ds_read_b128 v[178:181], v145 offset:17408
	ds_read_b128 v[182:185], v145 offset:18432
	ds_read_b128 v[192:195], v145 offset:19456
	ds_read_b128 v[230:233], v145 offset:20480
	ds_read_b128 v[234:237], v145 offset:21504
	ds_read_b128 v[238:241], v145 offset:22528
	ds_read_b128 v[242:245], v145 offset:23552
	s_add_i32 s33, s33, s39
	s_mov_b32 m0, s33
	v_lshl_add_u64 v[186:187], s[28:29], 0, v[188:189]
	global_load_lds_dwordx4 v[186:187], off
	s_add_i32 m0, s33, 0x2000
	s_add_u32 s52, s28, 0x40000
	v_lshl_add_u64 v[196:197], s[28:29], 0, v[132:133]
	s_addc_u32 s53, s29, 0
	s_add_i32 s33, s51, s39
	global_load_lds_dwordx4 v[196:197], off
	v_lshl_add_u64 v[246:247], s[52:53], 0, v[188:189]
	s_mov_b32 m0, s33
	v_lshl_add_u64 v[248:249], s[30:31], 0, v[130:131]
	global_load_lds_dwordx4 v[246:247], off
	s_add_i32 m0, s33, 0x2000
	v_lshl_add_u64 v[246:247], s[52:53], 0, v[132:133]
	global_load_lds_dwordx4 v[246:247], off
	s_mov_b32 m0, s25
	v_lshl_add_u64 v[246:247], s[30:31], 0, v[128:129]
	global_load_lds_dwordx4 v[246:247], off
	s_mov_b32 m0, s40
	s_nop 0
	global_load_lds_dwordx4 v[248:249], off
	s_waitcnt vmcnt(8)
	s_waitcnt lgkmcnt(0)
	s_barrier
	s_waitcnt lgkmcnt(0)
	v_mfma_f32_16x16x32_bf16 v[60:63], v[138:141], v[174:177], v[60:63]
	v_mfma_f32_16x16x32_bf16 v[56:59], v[150:153], v[174:177], v[56:59]
	v_mfma_f32_16x16x32_bf16 v[44:47], v[138:141], v[182:185], v[44:47]
	v_mfma_f32_16x16x32_bf16 v[40:43], v[150:153], v[182:185], v[40:43]
	v_mfma_f32_16x16x32_bf16 v[28:31], v[138:141], v[230:233], v[28:31]
	v_mfma_f32_16x16x32_bf16 v[24:27], v[150:153], v[230:233], v[24:27]
	v_mfma_f32_16x16x32_bf16 v[12:15], v[138:141], v[238:241], v[12:15]
	v_mfma_f32_16x16x32_bf16 v[8:11], v[150:153], v[238:241], v[8:11]
	v_mfma_f32_16x16x32_bf16 v[60:63], v[146:149], v[178:181], v[60:63]
	v_mfma_f32_16x16x32_bf16 v[56:59], v[154:157], v[178:181], v[56:59]
	v_mfma_f32_16x16x32_bf16 v[44:47], v[146:149], v[192:195], v[44:47]
	v_mfma_f32_16x16x32_bf16 v[40:43], v[154:157], v[192:195], v[40:43]
	v_mfma_f32_16x16x32_bf16 v[28:31], v[146:149], v[234:237], v[28:31]
	v_mfma_f32_16x16x32_bf16 v[24:27], v[154:157], v[234:237], v[24:27]
	v_mfma_f32_16x16x32_bf16 v[12:15], v[146:149], v[242:245], v[12:15]
	v_mfma_f32_16x16x32_bf16 v[8:11], v[154:157], v[242:245], v[8:11]
	v_mfma_f32_16x16x32_bf16 v[52:55], v[158:161], v[174:177], v[52:55]
	v_mfma_f32_16x16x32_bf16 v[48:51], v[166:169], v[174:177], v[48:51]
	v_mfma_f32_16x16x32_bf16 v[36:39], v[158:161], v[182:185], v[36:39]
	v_mfma_f32_16x16x32_bf16 v[32:35], v[166:169], v[182:185], v[32:35]
	v_mfma_f32_16x16x32_bf16 v[20:23], v[158:161], v[230:233], v[20:23]
	v_mfma_f32_16x16x32_bf16 v[16:19], v[166:169], v[230:233], v[16:19]
	v_mfma_f32_16x16x32_bf16 v[4:7], v[158:161], v[238:241], v[4:7]
	v_mfma_f32_16x16x32_bf16 v[0:3], v[166:169], v[238:241], v[0:3]
	v_mfma_f32_16x16x32_bf16 v[52:55], v[162:165], v[178:181], v[52:55]
	v_mfma_f32_16x16x32_bf16 v[48:51], v[170:173], v[178:181], v[48:51]
	v_mfma_f32_16x16x32_bf16 v[36:39], v[162:165], v[192:195], v[36:39]
	v_mfma_f32_16x16x32_bf16 v[32:35], v[170:173], v[192:195], v[32:35]
	v_mfma_f32_16x16x32_bf16 v[20:23], v[162:165], v[234:237], v[20:23]
	v_mfma_f32_16x16x32_bf16 v[16:19], v[170:173], v[234:237], v[16:19]
	v_mfma_f32_16x16x32_bf16 v[4:7], v[162:165], v[242:245], v[4:7]
	v_mfma_f32_16x16x32_bf16 v[0:3], v[170:173], v[242:245], v[0:3]
	s_barrier
; #define PG8_STAGE(bufoff, gbase, voff) do { _Pragma("unroll") for (int _i = 0; _i < 2; ++_i) \
;         __builtin_amdgcn_global_load_lds((const unsigned*)((const char*)(gbase) + (voff)[_i]), (PG8_LAS unsigned*)(lds + (bufoff) + ldsw + _i * 8192), 16, 0, 0); } while (0)
; #define PG8_LDA(dst, b, h) do { _Pragma("unroll") for (int m = 0; m < 4; ++m) _Pragma("unroll") for (int k = 0; k < 2; ++k) dst[m][k] = *(const PG8_LAS bf16x8*)(lds + PG8_SA(b, h) + aoff + m * 2048 + k * 1024); } while (0)
; #define PG8_LDB(dst, b, h) do { _Pragma("unroll") for (int n = 0; n < 2; ++n) _Pragma("unroll") for (int k = 0; k < 2; ++k) dst[n][k] = *(const PG8_LAS bf16x8*)(lds + PG8_SB(b, h) + boff + n * 2048 + k * 1024); } while (0)
; #define PG8_MMA(ai, bj, At, Bt) do { __builtin_amdgcn_s_setprio(1); _Pragma("unroll") for (int m = 0; m < 4; ++m) _Pragma("unroll") for (int n = 0; n < 2; ++n) _Pragma("unroll") for (int k = 0; k < 2; ++k) \
;         acc[ai][bj][m][n] = __builtin_amdgcn_mfma_f32_16x16x32_bf16(Bt[n][k], At[m][k], acc[ai][bj][m][n], 0, 0, 0); __builtin_amdgcn_s_setprio(0); } while (0)
; #define PG8_WAIT_V(n) asm volatile("s_waitcnt vmcnt(" #n ")" ::: "memory")
; #define PG8_WAIT_L(n) asm volatile("s_waitcnt lgkmcnt(" #n ")" ::: "memory")
; #define PG8_BAR __builtin_amdgcn_s_barrier()
; #define PG8_SCHED __builtin_amdgcn_sched_barrier(0)
; template <class Epi, class Sched, bool ALIGN_EPI = false, bool SP2 = false>
; __device__ __forceinline__ void gemm_phase(PG8_LAS unsigned char* lds, const Gemm g, const Sched& S, const Epi& E) {
;     ...
;             PG8_LDB(B0, 1, 0); PG8_LDB(B1, 1, 1); PG8_SCHED; PG8_LDA(At, 1, 0); PG8_STAGE(PG8_SA(0, 1), a2 + hstepA, voffA);
;             PG8_WAIT_V(8); PG8_WAIT_L(0); PG8_BAR; PG8_MMA(0, 0, At, B0); PG8_MMA(0, 1, At, B1); PG8_BAR; PG8_SCHED;
	v_add_u32_e32 v154, 0x18000, v144
	v_add_u32_e32 v170, 0x1c000, v144
	ds_read_b128 v[138:141], v154
	ds_read_b128 v[146:149], v154 offset:1024
	ds_read_b128 v[150:153], v154 offset:2048
	ds_read_b128 v[154:157], v154 offset:3072
	ds_read_b128 v[158:161], v170
	ds_read_b128 v[162:165], v170 offset:1024
	ds_read_b128 v[166:169], v170 offset:2048
	ds_read_b128 v[170:173], v170 offset:3072
	ds_read_b128 v[174:177], v145 offset:32768
	ds_read_b128 v[178:181], v145 offset:33792
	ds_read_b128 v[182:185], v145 offset:34816
	ds_read_b128 v[192:195], v145 offset:35840
	ds_read_b128 v[230:233], v145 offset:36864
	ds_read_b128 v[234:237], v145 offset:37888
	ds_read_b128 v[238:241], v145 offset:38912
	ds_read_b128 v[242:245], v145 offset:39936
	s_add_i32 s33, 0, 0x18000
	s_add_i32 s51, 0, 0x1c000
	s_add_u32 s30, s30, 0x40000
	s_addc_u32 s31, s31, 0
	s_mov_b32 m0, s41
	v_lshl_add_u64 v[250:251], s[30:31], 0, v[128:129]
	global_load_lds_dwordx4 v[250:251], off
	s_mov_b32 m0, s42
	v_lshl_add_u64 v[250:251], s[30:31], 0, v[130:131]
	global_load_lds_dwordx4 v[250:251], off
	s_waitcnt vmcnt(8)
	s_waitcnt lgkmcnt(0)
	s_barrier
	s_waitcnt lgkmcnt(0)
	v_mfma_f32_16x16x32_bf16 v[124:127], v[138:141], v[174:177], v[124:127]
	v_mfma_f32_16x16x32_bf16 v[120:123], v[150:153], v[174:177], v[120:123]
	v_mfma_f32_16x16x32_bf16 v[108:111], v[138:141], v[182:185], v[108:111]
	v_mfma_f32_16x16x32_bf16 v[104:107], v[150:153], v[182:185], v[104:107]
	v_mfma_f32_16x16x32_bf16 v[92:95], v[138:141], v[230:233], v[92:95]
	v_mfma_f32_16x16x32_bf16 v[88:91], v[150:153], v[230:233], v[88:91]
	v_mfma_f32_16x16x32_bf16 v[76:79], v[138:141], v[238:241], v[76:79]
	v_mfma_f32_16x16x32_bf16 v[72:75], v[150:153], v[238:241], v[72:75]
	v_mfma_f32_16x16x32_bf16 v[124:127], v[146:149], v[178:181], v[124:127]
	v_mfma_f32_16x16x32_bf16 v[120:123], v[154:157], v[178:181], v[120:123]
	v_mfma_f32_16x16x32_bf16 v[108:111], v[146:149], v[192:195], v[108:111]
	v_mfma_f32_16x16x32_bf16 v[104:107], v[154:157], v[192:195], v[104:107]
	v_mfma_f32_16x16x32_bf16 v[92:95], v[146:149], v[234:237], v[92:95]
	v_mfma_f32_16x16x32_bf16 v[88:91], v[154:157], v[234:237], v[88:91]
	v_mfma_f32_16x16x32_bf16 v[76:79], v[146:149], v[242:245], v[76:79]
	v_mfma_f32_16x16x32_bf16 v[72:75], v[154:157], v[242:245], v[72:75]
	v_mfma_f32_16x16x32_bf16 v[116:119], v[158:161], v[174:177], v[116:119]
	v_mfma_f32_16x16x32_bf16 v[112:115], v[166:169], v[174:177], v[112:115]
	v_mfma_f32_16x16x32_bf16 v[100:103], v[158:161], v[182:185], v[100:103]
	v_mfma_f32_16x16x32_bf16 v[96:99], v[166:169], v[182:185], v[96:99]
	v_mfma_f32_16x16x32_bf16 v[84:87], v[158:161], v[230:233], v[84:87]
	v_mfma_f32_16x16x32_bf16 v[80:83], v[166:169], v[230:233], v[80:83]
	v_mfma_f32_16x16x32_bf16 v[68:71], v[158:161], v[238:241], v[68:71]
	v_mfma_f32_16x16x32_bf16 v[64:67], v[166:169], v[238:241], v[64:67]
	v_mfma_f32_16x16x32_bf16 v[116:119], v[162:165], v[178:181], v[116:119]
	v_mfma_f32_16x16x32_bf16 v[112:115], v[170:173], v[178:181], v[112:115]
	v_mfma_f32_16x16x32_bf16 v[100:103], v[162:165], v[192:195], v[100:103]
	v_mfma_f32_16x16x32_bf16 v[96:99], v[170:173], v[192:195], v[96:99]
	v_mfma_f32_16x16x32_bf16 v[84:87], v[162:165], v[234:237], v[84:87]
	v_mfma_f32_16x16x32_bf16 v[80:83], v[170:173], v[234:237], v[80:83]
	v_mfma_f32_16x16x32_bf16 v[68:71], v[162:165], v[242:245], v[68:71]
	v_mfma_f32_16x16x32_bf16 v[64:67], v[170:173], v[242:245], v[64:67]
	s_barrier
; #define PG8_STAGE(bufoff, gbase, voff) do { _Pragma("unroll") for (int _i = 0; _i < 2; ++_i) \
;         __builtin_amdgcn_global_load_lds((const unsigned*)((const char*)(gbase) + (voff)[_i]), (PG8_LAS unsigned*)(lds + (bufoff) + ldsw + _i * 8192), 16, 0, 0); } while (0)
; #define PG8_LDA(dst, b, h) do { _Pragma("unroll") for (int m = 0; m < 4; ++m) _Pragma("unroll") for (int k = 0; k < 2; ++k) dst[m][k] = *(const PG8_LAS bf16x8*)(lds + PG8_SA(b, h) + aoff + m * 2048 + k * 1024); } while (0)
; #define PG8_MMA(ai, bj, At, Bt) do { __builtin_amdgcn_s_setprio(1); _Pragma("unroll") for (int m = 0; m < 4; ++m) _Pragma("unroll") for (int n = 0; n < 2; ++n) _Pragma("unroll") for (int k = 0; k < 2; ++k) \
;         acc[ai][bj][m][n] = __builtin_amdgcn_mfma_f32_16x16x32_bf16(Bt[n][k], At[m][k], acc[ai][bj][m][n], 0, 0, 0); __builtin_amdgcn_s_setprio(0); } while (0)
; #define PG8_WAIT_V(n) asm volatile("s_waitcnt vmcnt(" #n ")" ::: "memory")
; #define PG8_WAIT_L(n) asm volatile("s_waitcnt lgkmcnt(" #n ")" ::: "memory")
; #define PG8_BAR __builtin_amdgcn_s_barrier()
; #define PG8_SCHED __builtin_amdgcn_sched_barrier(0)
; template <class Epi, class Sched, bool ALIGN_EPI = false, bool SP2 = false>
; __device__ __forceinline__ void gemm_phase(PG8_LAS unsigned char* lds, const Gemm g, const Sched& S, const Epi& E) {
;     ...
;             PG8_LDA(At, 1, 1); PG8_STAGE(PG8_SB(1, 0), b3, voffB); PG8_STAGE(PG8_SB(1, 1), b3 + hstepB, voffB); PG8_STAGE(PG8_SA(1, 0), a3, voffA);
;             PG8_WAIT_V(8); PG8_WAIT_L(0); PG8_BAR; PG8_MMA(1, 0, At, B0); PG8_MMA(1, 1, At, B1); PG8_BAR; PG8_SCHED;
	ds_read_b128 v[174:177], v145 offset:49152
	ds_read_b128 v[178:181], v145 offset:50176
	ds_read_b128 v[182:185], v145 offset:51200
	ds_read_b128 v[192:195], v145 offset:52224
	ds_read_b128 v[230:233], v145 offset:53248
	ds_read_b128 v[234:237], v145 offset:54272
	ds_read_b128 v[238:241], v145 offset:55296
	ds_read_b128 v[242:245], v145 offset:56320
	s_add_i32 s30, s33, s39
	s_mov_b32 m0, s30
	v_lshl_add_u64 v[186:187], v[186:187], 0, s[94:95]
	global_load_lds_dwordx4 v[186:187], off
	s_add_i32 m0, s30, 0x2000
	s_add_u32 s28, s28, 0x40080
	v_lshl_add_u64 v[186:187], v[196:197], 0, s[94:95]
	s_addc_u32 s29, s29, 0
	s_add_i32 s30, s51, s39
	global_load_lds_dwordx4 v[186:187], off
	s_mov_b32 m0, s30
	v_lshl_add_u64 v[186:187], s[28:29], 0, v[188:189]
	global_load_lds_dwordx4 v[186:187], off
	s_add_i32 m0, s30, 0x2000
	v_lshl_add_u64 v[186:187], s[28:29], 0, v[132:133]
	global_load_lds_dwordx4 v[186:187], off
	s_mov_b32 m0, s47
	v_lshl_add_u64 v[186:187], v[246:247], 0, s[94:95]
	global_load_lds_dwordx4 v[186:187], off
	s_mov_b32 m0, s48
	v_lshl_add_u64 v[186:187], v[248:249], 0, s[94:95]
	global_load_lds_dwordx4 v[186:187], off
	s_waitcnt vmcnt(8)
	s_waitcnt lgkmcnt(0)
	s_barrier
	s_waitcnt lgkmcnt(0)
	v_mfma_f32_16x16x32_bf16 v[60:63], v[138:141], v[174:177], v[60:63]
	v_mfma_f32_16x16x32_bf16 v[56:59], v[150:153], v[174:177], v[56:59]
	v_mfma_f32_16x16x32_bf16 v[44:47], v[138:141], v[182:185], v[44:47]
	v_mfma_f32_16x16x32_bf16 v[40:43], v[150:153], v[182:185], v[40:43]
	v_mfma_f32_16x16x32_bf16 v[28:31], v[138:141], v[230:233], v[28:31]
	v_mfma_f32_16x16x32_bf16 v[24:27], v[150:153], v[230:233], v[24:27]
	v_mfma_f32_16x16x32_bf16 v[12:15], v[138:141], v[238:241], v[12:15]
	v_mfma_f32_16x16x32_bf16 v[8:11], v[150:153], v[238:241], v[8:11]
	v_mfma_f32_16x16x32_bf16 v[60:63], v[146:149], v[178:181], v[60:63]
	v_mfma_f32_16x16x32_bf16 v[56:59], v[154:157], v[178:181], v[56:59]
	v_mfma_f32_16x16x32_bf16 v[44:47], v[146:149], v[192:195], v[44:47]
	v_mfma_f32_16x16x32_bf16 v[40:43], v[154:157], v[192:195], v[40:43]
	v_mfma_f32_16x16x32_bf16 v[28:31], v[146:149], v[234:237], v[28:31]
	v_mfma_f32_16x16x32_bf16 v[24:27], v[154:157], v[234:237], v[24:27]
	v_mfma_f32_16x16x32_bf16 v[12:15], v[146:149], v[242:245], v[12:15]
	v_mfma_f32_16x16x32_bf16 v[8:11], v[154:157], v[242:245], v[8:11]
	v_mfma_f32_16x16x32_bf16 v[52:55], v[158:161], v[174:177], v[52:55]
	v_mfma_f32_16x16x32_bf16 v[48:51], v[166:169], v[174:177], v[48:51]
	v_mfma_f32_16x16x32_bf16 v[36:39], v[158:161], v[182:185], v[36:39]
	v_mfma_f32_16x16x32_bf16 v[32:35], v[166:169], v[182:185], v[32:35]
	v_mfma_f32_16x16x32_bf16 v[20:23], v[158:161], v[230:233], v[20:23]
	v_mfma_f32_16x16x32_bf16 v[16:19], v[166:169], v[230:233], v[16:19]
	v_mfma_f32_16x16x32_bf16 v[4:7], v[158:161], v[238:241], v[4:7]
	v_mfma_f32_16x16x32_bf16 v[0:3], v[166:169], v[238:241], v[0:3]
	v_mfma_f32_16x16x32_bf16 v[52:55], v[162:165], v[178:181], v[52:55]
	v_mfma_f32_16x16x32_bf16 v[48:51], v[170:173], v[178:181], v[48:51]
	v_mfma_f32_16x16x32_bf16 v[36:39], v[162:165], v[192:195], v[36:39]
	v_mfma_f32_16x16x32_bf16 v[32:35], v[170:173], v[192:195], v[32:35]
	v_mfma_f32_16x16x32_bf16 v[20:23], v[162:165], v[234:237], v[20:23]
	v_mfma_f32_16x16x32_bf16 v[16:19], v[170:173], v[234:237], v[16:19]
	v_mfma_f32_16x16x32_bf16 v[4:7], v[162:165], v[242:245], v[4:7]
	v_mfma_f32_16x16x32_bf16 v[0:3], v[170:173], v[242:245], v[0:3]
	s_barrier
	s_add_i32 s19, s19, 2
	s_add_u32 s26, s26, 0x100
	s_addc_u32 s27, s27, 0
	s_add_u32 s9, s9, 0x100
	s_addc_u32 s17, s17, 0
	s_cmp_gt_u32 s19, 13
	s_cbranch_scc0 .LBB0_712
	s_setprio 0
	s_and_b64 vcc, exec, s[14:15]
	s_cbranch_vccz .LBB0_715
	s_barrier

; #define PG8_STAGE(bufoff, gbase, voff) do { _Pragma("unroll") for (int _i = 0; _i < 2; ++_i) \
;         __builtin_amdgcn_global_load_lds((const unsigned*)((const char*)(gbase) + (voff)[_i]), (PG8_LAS unsigned*)(lds + (bufoff) + ldsw + _i * 8192), 16, 0, 0); } while (0)
; #define PG8_LDA(dst, b, h) do { _Pragma("unroll") for (int m = 0; m < 4; ++m) _Pragma("unroll") for (int k = 0; k < 2; ++k) dst[m][k] = *(const PG8_LAS bf16x8*)(lds + PG8_SA(b, h) + aoff + m * 2048 + k * 1024); } while (0)
; #define PG8_LDB(dst, b, h) do { _Pragma("unroll") for (int n = 0; n < 2; ++n) _Pragma("unroll") for (int k = 0; k < 2; ++k) dst[n][k] = *(const PG8_LAS bf16x8*)(lds + PG8_SB(b, h) + boff + n * 2048 + k * 1024); } while (0)
; #define PG8_SCHED __builtin_amdgcn_sched_barrier(0)
; template <class Epi, class Sched, bool ALIGN_EPI = false, bool SP2 = false>
; __device__ __forceinline__ void gemm_phase(PG8_LAS unsigned char* lds, const Gemm g, const Sched& S, const Epi& E) {
;     ...
;         const char* nA = has_next ? (const char*)g.A + (size_t)nxt.pm * tstepA + (size_t)((nxt.pn / g.kdiv) * g.kmul) * 2 : cA; const char* nB = has_next ? (const char*)g.Bt + (size_t)nxt.pn * tstepB : cB;
; #pragma nounroll
;         for (int t = 0; t < nt; t += 2) {
;             const bool last = (t == nt - 2);
;             const char* a1 = cA + (size_t)(t + 1) * kstep;
;             const char* a2 = last ? nA : cA + (size_t)(t + 2) * kstep; const char* b2 = last ? nB : cB + (size_t)(t + 2) * kstep;
;             const char* a3 = a2 + kstep; const char* b3 = b2 + kstep;
;             if (last && has_next) S.a_ready(nxt);
;             if constexpr (SP2) {
;             PG8_LDB(B0, 0, 0); PG8_LDB(B1, 0, 1); PG8_SCHED; PG8_LDA(At, 0, 0); PG8_STAGE(PG8_SA(1, 1), a1 + hstepA, voffA);
;     ...
; #pragma unroll
;         for (int a = 0; a < 2; ++a)
; #pragma unroll
;             for (int b = 0; b < 2; ++b)
; #pragma unroll
;                 for (int m = 0; m < 4; ++m)
; #pragma unroll
;                     for (int n = 0; n < 2; ++n) acc[a][b][m][n] = (f32x4){0.f, 0.f, 0.f, 0.f};
;         cur = nxt; cA = nA; cB = nB; ++ui;
.LBB0_900:
	s_ashr_i32 s25, s24, 31
	s_lshl_b64 s[28:29], s[24:25], 17
	s_add_u32 s28, s33, s28
	s_addc_u32 s29, s48, s29
	s_and_b64 s[8:9], s[8:9], exec
	v_mov_b32_e32 v0, 0
	s_cselect_b32 s25, s29, s31
	s_cselect_b32 s63, s28, s30
	s_mov_b64 s[38:39], 0
	s_mov_b64 s[8:9], -1
	s_mov_b64 s[36:37], 0
	v_mov_b32_e32 v1, v0
	v_mov_b32_e32 v2, v0
	v_mov_b32_e32 v3, v0
	v_mov_b32_e32 v4, v0
	v_mov_b32_e32 v5, v0
	v_mov_b32_e32 v6, v0
	v_mov_b32_e32 v7, v0
	v_mov_b32_e32 v8, v0
	v_mov_b32_e32 v9, v0
	v_mov_b32_e32 v10, v0
	v_mov_b32_e32 v11, v0
	v_mov_b32_e32 v12, v0
	v_mov_b32_e32 v13, v0
	v_mov_b32_e32 v14, v0
	v_mov_b32_e32 v15, v0
	v_mov_b32_e32 v24, v0
	v_mov_b32_e32 v25, v0
	v_mov_b32_e32 v26, v0
	v_mov_b32_e32 v27, v0
	v_mov_b32_e32 v28, v0
	v_mov_b32_e32 v29, v0
	v_mov_b32_e32 v30, v0
	v_mov_b32_e32 v31, v0
	v_mov_b32_e32 v40, v0
	v_mov_b32_e32 v41, v0
	v_mov_b32_e32 v42, v0
	v_mov_b32_e32 v43, v0
	v_mov_b32_e32 v44, v0
	v_mov_b32_e32 v45, v0
	v_mov_b32_e32 v46, v0
	v_mov_b32_e32 v47, v0
	v_mov_b32_e32 v16, v0
	v_mov_b32_e32 v17, v0
	v_mov_b32_e32 v18, v0
	v_mov_b32_e32 v19, v0
	v_mov_b32_e32 v20, v0
	v_mov_b32_e32 v21, v0
	v_mov_b32_e32 v22, v0
	v_mov_b32_e32 v23, v0
	v_mov_b32_e32 v32, v0
	v_mov_b32_e32 v33, v0
	v_mov_b32_e32 v34, v0
	v_mov_b32_e32 v35, v0
	v_mov_b32_e32 v36, v0
	v_mov_b32_e32 v37, v0
	v_mov_b32_e32 v38, v0
	v_mov_b32_e32 v39, v0
	v_mov_b32_e32 v48, v0
	v_mov_b32_e32 v49, v0
	v_mov_b32_e32 v50, v0
	v_mov_b32_e32 v51, v0
	v_mov_b32_e32 v52, v0
	v_mov_b32_e32 v53, v0
	v_mov_b32_e32 v54, v0
	v_mov_b32_e32 v55, v0
	v_mov_b32_e32 v56, v0
	v_mov_b32_e32 v57, v0
	v_mov_b32_e32 v58, v0
	v_mov_b32_e32 v59, v0
	v_mov_b32_e32 v60, v0
	v_mov_b32_e32 v61, v0
	v_mov_b32_e32 v62, v0
	v_mov_b32_e32 v63, v0
	v_mov_b32_e32 v64, v0
	v_mov_b32_e32 v65, v0
	v_mov_b32_e32 v66, v0
	v_mov_b32_e32 v67, v0
	v_mov_b32_e32 v68, v0
	v_mov_b32_e32 v69, v0
	v_mov_b32_e32 v70, v0
	v_mov_b32_e32 v71, v0
	v_mov_b32_e32 v72, v0
	v_mov_b32_e32 v73, v0
	v_mov_b32_e32 v74, v0
	v_mov_b32_e32 v75, v0
	v_mov_b32_e32 v76, v0
	v_mov_b32_e32 v77, v0
	v_mov_b32_e32 v78, v0
	v_mov_b32_e32 v79, v0
	v_mov_b32_e32 v88, v0
	v_mov_b32_e32 v89, v0
	v_mov_b32_e32 v90, v0
	v_mov_b32_e32 v91, v0
	v_mov_b32_e32 v92, v0
	v_mov_b32_e32 v93, v0
	v_mov_b32_e32 v94, v0
	v_mov_b32_e32 v95, v0
	v_mov_b32_e32 v104, v0
	v_mov_b32_e32 v105, v0
	v_mov_b32_e32 v106, v0
	v_mov_b32_e32 v107, v0
	v_mov_b32_e32 v108, v0
	v_mov_b32_e32 v109, v0
	v_mov_b32_e32 v110, v0
	v_mov_b32_e32 v111, v0
	v_mov_b32_e32 v80, v0
	v_mov_b32_e32 v81, v0
	v_mov_b32_e32 v82, v0
	v_mov_b32_e32 v83, v0
	v_mov_b32_e32 v84, v0
	v_mov_b32_e32 v85, v0
	v_mov_b32_e32 v86, v0
	v_mov_b32_e32 v87, v0
	v_mov_b32_e32 v96, v0
	v_mov_b32_e32 v97, v0
	v_mov_b32_e32 v98, v0
	v_mov_b32_e32 v99, v0
	v_mov_b32_e32 v100, v0
	v_mov_b32_e32 v101, v0
	v_mov_b32_e32 v102, v0
	v_mov_b32_e32 v103, v0
	v_mov_b32_e32 v112, v0
	v_mov_b32_e32 v113, v0
	v_mov_b32_e32 v114, v0
	v_mov_b32_e32 v115, v0
	v_mov_b32_e32 v116, v0
	v_mov_b32_e32 v117, v0
	v_mov_b32_e32 v118, v0
	v_mov_b32_e32 v119, v0
	v_mov_b32_e32 v120, v0
	v_mov_b32_e32 v121, v0
	v_mov_b32_e32 v122, v0
	v_mov_b32_e32 v123, v0
	v_mov_b32_e32 v124, v0
	v_mov_b32_e32 v125, v0
	v_mov_b32_e32 v126, v0
	v_mov_b32_e32 v127, v0
	v_readfirstlane_b32 s100, v198
	s_nop 3
	s_bitcmp1_b32 s100, 8
	s_cbranch_scc0 .Lgprio_2_skip
	s_setprio 1
.Lgprio_2_skip:
.LBB0_901:
	v_add_u32_e32 v150, 0x10000, v136
	v_add_u32_e32 v166, 0x14000, v136
	ds_read_b128 v[138:141], v150
	ds_read_b128 v[142:145], v150 offset:1024
	ds_read_b128 v[146:149], v150 offset:2048
	ds_read_b128 v[150:153], v150 offset:3072
	ds_read_b128 v[154:157], v166
	ds_read_b128 v[158:161], v166 offset:1024
	ds_read_b128 v[162:165], v166 offset:2048
	ds_read_b128 v[166:169], v166 offset:3072
	ds_read_b128 v[170:173], v137
	ds_read_b128 v[174:177], v137 offset:1024
	ds_read_b128 v[178:181], v137 offset:2048
	ds_read_b128 v[182:185], v137 offset:3072
	ds_read_b128 v[192:195], v137 offset:4096
	ds_read_b128 v[230:233], v137 offset:5120
	ds_read_b128 v[234:237], v137 offset:6144
	ds_read_b128 v[238:241], v137 offset:7168
	s_add_u32 s44, s34, s38
	s_addc_u32 s45, s35, s39
	s_add_u32 s42, s44, 0x100
	s_addc_u32 s43, s45, 0
	s_and_b64 s[40:41], s[36:37], exec
	s_cselect_b32 s41, s27, s43
	s_cselect_b32 s40, s26, s42
	s_add_u32 s38, s30, s38
	s_addc_u32 s39, s31, s39
	s_add_u32 s38, s38, 0x100
	s_addc_u32 s39, s39, 0
	s_add_i32 s72, 0, 0x10000
	s_and_b64 s[36:37], s[36:37], exec
	s_cselect_b32 s43, s25, s39
	s_cselect_b32 s42, s63, s38
	s_add_i32 s37, 0, 0x14000
	s_add_u32 s46, s44, 0x50080
	s_addc_u32 s47, s45, 0
	s_add_i32 s71, s72, s49
	s_add_i32 m0, s51, 0xc000
	s_add_i32 s74, s51, 0xe000
	s_add_i32 s68, s71, 0x2000
	s_add_u32 s44, s42, 0x10000
	s_addc_u32 s45, s43, 0
	s_add_i32 s70, s37, s49
	s_add_i32 s69, s70, 0x2000
	s_add_i32 s67, 0, 0x18000
	s_add_i32 s66, 0, 0x1c000
	s_add_u32 s38, s40, 0x50000
	s_addc_u32 s39, s41, 0
	s_add_i32 s65, s67, s49
	s_add_i32 s64, s65, 0x2000
	s_add_u32 s36, s42, 0x10080
	s_addc_u32 s37, s43, 0
	s_add_i32 s73, s66, s49
	s_add_i32 s72, s73, 0x2000
	v_lshl_add_u64 v[186:187], s[46:47], 0, v[132:133]
	global_load_lds_dwordx4 v[186:187], off
	s_mov_b32 m0, s74
	v_lshl_add_u64 v[186:187], s[46:47], 0, v[130:131]
	global_load_lds_dwordx4 v[186:187], off
	s_waitcnt vmcnt(8)
	s_waitcnt lgkmcnt(0)
	s_barrier
; #define PG8_STAGE(bufoff, gbase, voff) do { _Pragma("unroll") for (int _i = 0; _i < 2; ++_i) \
;         __builtin_amdgcn_global_load_lds((const unsigned*)((const char*)(gbase) + (voff)[_i]), (PG8_LAS unsigned*)(lds + (bufoff) + ldsw + _i * 8192), 16, 0, 0); } while (0)
; #define PG8_LDA(dst, b, h) do { _Pragma("unroll") for (int m = 0; m < 4; ++m) _Pragma("unroll") for (int k = 0; k < 2; ++k) dst[m][k] = *(const PG8_LAS bf16x8*)(lds + PG8_SA(b, h) + aoff + m * 2048 + k * 1024); } while (0)
; #define PG8_MMA(ai, bj, At, Bt) do { __builtin_amdgcn_s_setprio(1); _Pragma("unroll") for (int m = 0; m < 4; ++m) _Pragma("unroll") for (int n = 0; n < 2; ++n) _Pragma("unroll") for (int k = 0; k < 2; ++k) \
;         acc[ai][bj][m][n] = __builtin_amdgcn_mfma_f32_16x16x32_bf16(Bt[n][k], At[m][k], acc[ai][bj][m][n], 0, 0, 0); __builtin_amdgcn_s_setprio(0); } while (0)
; #define PG8_WAIT_V(n) asm volatile("s_waitcnt vmcnt(" #n ")" ::: "memory")
; #define PG8_WAIT_L(n) asm volatile("s_waitcnt lgkmcnt(" #n ")" ::: "memory")
; #define PG8_BAR __builtin_amdgcn_s_barrier()
; #define PG8_SCHED __builtin_amdgcn_sched_barrier(0)
; template <class Epi, class Sched, bool ALIGN_EPI = false, bool SP2 = false>
; __device__ __forceinline__ void gemm_phase(PG8_LAS unsigned char* lds, const Gemm g, const Sched& S, const Epi& E) {
;     ...
;             PG8_WAIT_V(8); PG8_WAIT_L(0); PG8_BAR; PG8_MMA(0, 0, At, B0); PG8_MMA(0, 1, At, B1); PG8_BAR; PG8_SCHED;
;             PG8_LDA(At, 0, 1); PG8_STAGE(PG8_SB(0, 0), b2, voffB); PG8_STAGE(PG8_SB(0, 1), b2 + hstepB, voffB); PG8_STAGE(PG8_SA(0, 0), a2, voffA);
;             PG8_WAIT_V(8); PG8_WAIT_L(0); PG8_BAR; PG8_MMA(1, 0, At, B0); PG8_MMA(1, 1, At, B1); PG8_BAR; PG8_SCHED;
	s_waitcnt lgkmcnt(0)
	v_mfma_f32_16x16x32_bf16 v[124:127], v[138:141], v[170:173], v[124:127]
	v_mfma_f32_16x16x32_bf16 v[120:123], v[146:149], v[170:173], v[120:123]
	v_mfma_f32_16x16x32_bf16 v[116:119], v[138:141], v[178:181], v[116:119]
	v_mfma_f32_16x16x32_bf16 v[112:115], v[146:149], v[178:181], v[112:115]
	v_mfma_f32_16x16x32_bf16 v[100:103], v[138:141], v[192:195], v[100:103]
	v_mfma_f32_16x16x32_bf16 v[96:99], v[146:149], v[192:195], v[96:99]
	v_mfma_f32_16x16x32_bf16 v[84:87], v[138:141], v[234:237], v[84:87]
	v_mfma_f32_16x16x32_bf16 v[80:83], v[146:149], v[234:237], v[80:83]
	v_mfma_f32_16x16x32_bf16 v[124:127], v[142:145], v[174:177], v[124:127]
	v_mfma_f32_16x16x32_bf16 v[120:123], v[150:153], v[174:177], v[120:123]
	v_mfma_f32_16x16x32_bf16 v[116:119], v[142:145], v[182:185], v[116:119]
	v_mfma_f32_16x16x32_bf16 v[112:115], v[150:153], v[182:185], v[112:115]
	v_mfma_f32_16x16x32_bf16 v[100:103], v[142:145], v[230:233], v[100:103]
	v_mfma_f32_16x16x32_bf16 v[96:99], v[150:153], v[230:233], v[96:99]
	v_mfma_f32_16x16x32_bf16 v[84:87], v[142:145], v[238:241], v[84:87]
	v_mfma_f32_16x16x32_bf16 v[80:83], v[150:153], v[238:241], v[80:83]
	v_mfma_f32_16x16x32_bf16 v[108:111], v[154:157], v[170:173], v[108:111]
	v_mfma_f32_16x16x32_bf16 v[104:107], v[162:165], v[170:173], v[104:107]
	v_mfma_f32_16x16x32_bf16 v[92:95], v[154:157], v[178:181], v[92:95]
	v_mfma_f32_16x16x32_bf16 v[88:91], v[162:165], v[178:181], v[88:91]
	v_mfma_f32_16x16x32_bf16 v[76:79], v[154:157], v[192:195], v[76:79]
	v_mfma_f32_16x16x32_bf16 v[72:75], v[162:165], v[192:195], v[72:75]
	v_mfma_f32_16x16x32_bf16 v[68:71], v[154:157], v[234:237], v[68:71]
	v_mfma_f32_16x16x32_bf16 v[64:67], v[162:165], v[234:237], v[64:67]
	v_mfma_f32_16x16x32_bf16 v[108:111], v[158:161], v[174:177], v[108:111]
	v_mfma_f32_16x16x32_bf16 v[104:107], v[166:169], v[174:177], v[104:107]
	v_mfma_f32_16x16x32_bf16 v[92:95], v[158:161], v[182:185], v[92:95]
	v_mfma_f32_16x16x32_bf16 v[88:91], v[166:169], v[182:185], v[88:91]
	v_mfma_f32_16x16x32_bf16 v[76:79], v[158:161], v[230:233], v[76:79]
	v_mfma_f32_16x16x32_bf16 v[72:75], v[166:169], v[230:233], v[72:75]
	v_mfma_f32_16x16x32_bf16 v[68:71], v[158:161], v[238:241], v[68:71]
	v_mfma_f32_16x16x32_bf16 v[64:67], v[166:169], v[238:241], v[64:67]
	s_barrier
	ds_read_b128 v[170:173], v137 offset:16384
	ds_read_b128 v[174:177], v137 offset:17408
	ds_read_b128 v[178:181], v137 offset:18432
	ds_read_b128 v[182:185], v137 offset:19456
	ds_read_b128 v[192:195], v137 offset:20480
	ds_read_b128 v[230:233], v137 offset:21504
	ds_read_b128 v[234:237], v137 offset:22528
	ds_read_b128 v[238:241], v137 offset:23552
	s_mov_b32 m0, s71
	v_lshl_add_u64 v[186:187], s[42:43], 0, v[188:189]
	global_load_lds_dwordx4 v[186:187], off
	v_lshl_add_u64 v[196:197], s[42:43], 0, v[128:129]
	s_mov_b32 m0, s68
	v_lshl_add_u64 v[242:243], s[44:45], 0, v[188:189]
	global_load_lds_dwordx4 v[196:197], off
	s_mov_b32 m0, s70
	v_lshl_add_u64 v[244:245], s[40:41], 0, v[130:131]
	global_load_lds_dwordx4 v[242:243], off
	s_mov_b32 m0, s69
	v_lshl_add_u64 v[242:243], s[44:45], 0, v[128:129]
	global_load_lds_dwordx4 v[242:243], off
	s_mov_b32 m0, s51
	v_lshl_add_u64 v[242:243], s[40:41], 0, v[132:133]
	global_load_lds_dwordx4 v[242:243], off
	s_mov_b32 m0, s52
	s_nop 0
	global_load_lds_dwordx4 v[244:245], off
	s_waitcnt vmcnt(8)
	s_waitcnt lgkmcnt(0)
	s_barrier
	s_waitcnt lgkmcnt(0)
	v_mfma_f32_16x16x32_bf16 v[60:63], v[138:141], v[170:173], v[60:63]
	v_mfma_f32_16x16x32_bf16 v[56:59], v[146:149], v[170:173], v[56:59]
	v_mfma_f32_16x16x32_bf16 v[52:55], v[138:141], v[178:181], v[52:55]
	v_mfma_f32_16x16x32_bf16 v[48:51], v[146:149], v[178:181], v[48:51]
	v_mfma_f32_16x16x32_bf16 v[36:39], v[138:141], v[192:195], v[36:39]
	v_mfma_f32_16x16x32_bf16 v[32:35], v[146:149], v[192:195], v[32:35]
	v_mfma_f32_16x16x32_bf16 v[20:23], v[138:141], v[234:237], v[20:23]
	v_mfma_f32_16x16x32_bf16 v[16:19], v[146:149], v[234:237], v[16:19]
	v_mfma_f32_16x16x32_bf16 v[60:63], v[142:145], v[174:177], v[60:63]
	v_mfma_f32_16x16x32_bf16 v[56:59], v[150:153], v[174:177], v[56:59]
	v_mfma_f32_16x16x32_bf16 v[52:55], v[142:145], v[182:185], v[52:55]
	v_mfma_f32_16x16x32_bf16 v[48:51], v[150:153], v[182:185], v[48:51]
	v_mfma_f32_16x16x32_bf16 v[36:39], v[142:145], v[230:233], v[36:39]
	v_mfma_f32_16x16x32_bf16 v[32:35], v[150:153], v[230:233], v[32:35]
	v_mfma_f32_16x16x32_bf16 v[20:23], v[142:145], v[238:241], v[20:23]
	v_mfma_f32_16x16x32_bf16 v[16:19], v[150:153], v[238:241], v[16:19]
	v_mfma_f32_16x16x32_bf16 v[44:47], v[154:157], v[170:173], v[44:47]
	v_mfma_f32_16x16x32_bf16 v[40:43], v[162:165], v[170:173], v[40:43]
	v_mfma_f32_16x16x32_bf16 v[28:31], v[154:157], v[178:181], v[28:31]
	v_mfma_f32_16x16x32_bf16 v[24:27], v[162:165], v[178:181], v[24:27]
	v_mfma_f32_16x16x32_bf16 v[12:15], v[154:157], v[192:195], v[12:15]
	v_mfma_f32_16x16x32_bf16 v[8:11], v[162:165], v[192:195], v[8:11]
	v_mfma_f32_16x16x32_bf16 v[4:7], v[154:157], v[234:237], v[4:7]
	v_mfma_f32_16x16x32_bf16 v[0:3], v[162:165], v[234:237], v[0:3]
	v_mfma_f32_16x16x32_bf16 v[44:47], v[158:161], v[174:177], v[44:47]
	v_mfma_f32_16x16x32_bf16 v[40:43], v[166:169], v[174:177], v[40:43]
	v_mfma_f32_16x16x32_bf16 v[28:31], v[158:161], v[182:185], v[28:31]
	v_mfma_f32_16x16x32_bf16 v[24:27], v[166:169], v[182:185], v[24:27]
	v_mfma_f32_16x16x32_bf16 v[12:15], v[158:161], v[230:233], v[12:15]
	v_mfma_f32_16x16x32_bf16 v[8:11], v[166:169], v[230:233], v[8:11]
	v_mfma_f32_16x16x32_bf16 v[4:7], v[158:161], v[238:241], v[4:7]
	v_mfma_f32_16x16x32_bf16 v[0:3], v[166:169], v[238:241], v[0:3]
	s_barrier
; #define PG8_STAGE(bufoff, gbase, voff) do { _Pragma("unroll") for (int _i = 0; _i < 2; ++_i) \
;         __builtin_amdgcn_global_load_lds((const unsigned*)((const char*)(gbase) + (voff)[_i]), (PG8_LAS unsigned*)(lds + (bufoff) + ldsw + _i * 8192), 16, 0, 0); } while (0)
; #define PG8_LDA(dst, b, h) do { _Pragma("unroll") for (int m = 0; m < 4; ++m) _Pragma("unroll") for (int k = 0; k < 2; ++k) dst[m][k] = *(const PG8_LAS bf16x8*)(lds + PG8_SA(b, h) + aoff + m * 2048 + k * 1024); } while (0)
; #define PG8_LDB(dst, b, h) do { _Pragma("unroll") for (int n = 0; n < 2; ++n) _Pragma("unroll") for (int k = 0; k < 2; ++k) dst[n][k] = *(const PG8_LAS bf16x8*)(lds + PG8_SB(b, h) + boff + n * 2048 + k * 1024); } while (0)
; #define PG8_MMA(ai, bj, At, Bt) do { __builtin_amdgcn_s_setprio(1); _Pragma("unroll") for (int m = 0; m < 4; ++m) _Pragma("unroll") for (int n = 0; n < 2; ++n) _Pragma("unroll") for (int k = 0; k < 2; ++k) \
;         acc[ai][bj][m][n] = __builtin_amdgcn_mfma_f32_16x16x32_bf16(Bt[n][k], At[m][k], acc[ai][bj][m][n], 0, 0, 0); __builtin_amdgcn_s_setprio(0); } while (0)
; #define PG8_WAIT_V(n) asm volatile("s_waitcnt vmcnt(" #n ")" ::: "memory")
; #define PG8_WAIT_L(n) asm volatile("s_waitcnt lgkmcnt(" #n ")" ::: "memory")
; #define PG8_BAR __builtin_amdgcn_s_barrier()
; #define PG8_SCHED __builtin_amdgcn_sched_barrier(0)
; template <class Epi, class Sched, bool ALIGN_EPI = false, bool SP2 = false>
; __device__ __forceinline__ void gemm_phase(PG8_LAS unsigned char* lds, const Gemm g, const Sched& S, const Epi& E) {
;     ...
;             PG8_LDB(B0, 1, 0); PG8_LDB(B1, 1, 1); PG8_SCHED; PG8_LDA(At, 1, 0); PG8_STAGE(PG8_SA(0, 1), a2 + hstepA, voffA);
;             PG8_WAIT_V(8); PG8_WAIT_L(0); PG8_BAR; PG8_MMA(0, 0, At, B0); PG8_MMA(0, 1, At, B1); PG8_BAR; PG8_SCHED;
;             PG8_LDA(At, 1, 1); PG8_STAGE(PG8_SB(1, 0), b3, voffB); PG8_STAGE(PG8_SB(1, 1), b3 + hstepB, voffB); PG8_STAGE(PG8_SA(1, 0), a3, voffA);
;             PG8_WAIT_V(8); PG8_WAIT_L(0); PG8_BAR; PG8_MMA(1, 0, At, B0); PG8_MMA(1, 1, At, B1); PG8_BAR; PG8_SCHED;
	v_add_u32_e32 v150, 0x18000, v136
	v_add_u32_e32 v166, 0x1c000, v136
	ds_read_b128 v[138:141], v150
	ds_read_b128 v[142:145], v150 offset:1024
	ds_read_b128 v[146:149], v150 offset:2048
	ds_read_b128 v[150:153], v150 offset:3072
	ds_read_b128 v[154:157], v166
	ds_read_b128 v[158:161], v166 offset:1024
	ds_read_b128 v[162:165], v166 offset:2048
	ds_read_b128 v[166:169], v166 offset:3072
	ds_read_b128 v[170:173], v137 offset:32768
	ds_read_b128 v[174:177], v137 offset:33792
	ds_read_b128 v[178:181], v137 offset:34816
	ds_read_b128 v[182:185], v137 offset:35840
	ds_read_b128 v[192:195], v137 offset:36864
	ds_read_b128 v[230:233], v137 offset:37888
	ds_read_b128 v[234:237], v137 offset:38912
	ds_read_b128 v[238:241], v137 offset:39936
	s_mov_b32 m0, s53
	v_lshl_add_u64 v[246:247], s[38:39], 0, v[132:133]
	global_load_lds_dwordx4 v[246:247], off
	s_mov_b32 m0, s54
	v_lshl_add_u64 v[246:247], s[38:39], 0, v[130:131]
	global_load_lds_dwordx4 v[246:247], off
	s_waitcnt vmcnt(8)
	s_waitcnt lgkmcnt(0)
	s_barrier
	s_waitcnt lgkmcnt(0)
	v_mfma_f32_16x16x32_bf16 v[124:127], v[138:141], v[170:173], v[124:127]
	v_mfma_f32_16x16x32_bf16 v[120:123], v[146:149], v[170:173], v[120:123]
	v_mfma_f32_16x16x32_bf16 v[116:119], v[138:141], v[178:181], v[116:119]
	v_mfma_f32_16x16x32_bf16 v[112:115], v[146:149], v[178:181], v[112:115]
	v_mfma_f32_16x16x32_bf16 v[100:103], v[138:141], v[192:195], v[100:103]
	v_mfma_f32_16x16x32_bf16 v[96:99], v[146:149], v[192:195], v[96:99]
	v_mfma_f32_16x16x32_bf16 v[84:87], v[138:141], v[234:237], v[84:87]
	v_mfma_f32_16x16x32_bf16 v[80:83], v[146:149], v[234:237], v[80:83]
	v_mfma_f32_16x16x32_bf16 v[124:127], v[142:145], v[174:177], v[124:127]
	v_mfma_f32_16x16x32_bf16 v[120:123], v[150:153], v[174:177], v[120:123]
	v_mfma_f32_16x16x32_bf16 v[116:119], v[142:145], v[182:185], v[116:119]
	v_mfma_f32_16x16x32_bf16 v[112:115], v[150:153], v[182:185], v[112:115]
	v_mfma_f32_16x16x32_bf16 v[100:103], v[142:145], v[230:233], v[100:103]
	v_mfma_f32_16x16x32_bf16 v[96:99], v[150:153], v[230:233], v[96:99]
	v_mfma_f32_16x16x32_bf16 v[84:87], v[142:145], v[238:241], v[84:87]
	v_mfma_f32_16x16x32_bf16 v[80:83], v[150:153], v[238:241], v[80:83]
	v_mfma_f32_16x16x32_bf16 v[108:111], v[154:157], v[170:173], v[108:111]
	v_mfma_f32_16x16x32_bf16 v[104:107], v[162:165], v[170:173], v[104:107]
	v_mfma_f32_16x16x32_bf16 v[92:95], v[154:157], v[178:181], v[92:95]
	v_mfma_f32_16x16x32_bf16 v[88:91], v[162:165], v[178:181], v[88:91]
	v_mfma_f32_16x16x32_bf16 v[76:79], v[154:157], v[192:195], v[76:79]
	v_mfma_f32_16x16x32_bf16 v[72:75], v[162:165], v[192:195], v[72:75]
	v_mfma_f32_16x16x32_bf16 v[68:71], v[154:157], v[234:237], v[68:71]
	v_mfma_f32_16x16x32_bf16 v[64:67], v[162:165], v[234:237], v[64:67]
	v_mfma_f32_16x16x32_bf16 v[108:111], v[158:161], v[174:177], v[108:111]
	v_mfma_f32_16x16x32_bf16 v[104:107], v[166:169], v[174:177], v[104:107]
	v_mfma_f32_16x16x32_bf16 v[92:95], v[158:161], v[182:185], v[92:95]
	v_mfma_f32_16x16x32_bf16 v[88:91], v[166:169], v[182:185], v[88:91]
	v_mfma_f32_16x16x32_bf16 v[76:79], v[158:161], v[230:233], v[76:79]
	v_mfma_f32_16x16x32_bf16 v[72:75], v[166:169], v[230:233], v[72:75]
	v_mfma_f32_16x16x32_bf16 v[68:71], v[158:161], v[238:241], v[68:71]
	v_mfma_f32_16x16x32_bf16 v[64:67], v[166:169], v[238:241], v[64:67]
	s_barrier
	ds_read_b128 v[170:173], v137 offset:49152
	ds_read_b128 v[174:177], v137 offset:50176
	ds_read_b128 v[178:181], v137 offset:51200
	ds_read_b128 v[182:185], v137 offset:52224
	ds_read_b128 v[192:195], v137 offset:53248
	ds_read_b128 v[230:233], v137 offset:54272
	ds_read_b128 v[234:237], v137 offset:55296
	ds_read_b128 v[238:241], v137 offset:56320
	s_mov_b32 m0, s65
	v_lshl_add_u64 v[186:187], v[186:187], 0, s[94:95]
	global_load_lds_dwordx4 v[186:187], off
	s_mov_b32 m0, s64
	v_lshl_add_u64 v[186:187], v[196:197], 0, s[94:95]
	global_load_lds_dwordx4 v[186:187], off
	s_mov_b32 m0, s73
	v_lshl_add_u64 v[186:187], s[36:37], 0, v[188:189]
	global_load_lds_dwordx4 v[186:187], off
	s_mov_b32 m0, s72
	v_lshl_add_u64 v[186:187], s[36:37], 0, v[128:129]
	global_load_lds_dwordx4 v[186:187], off
	s_mov_b32 m0, s56
	v_lshl_add_u64 v[186:187], v[242:243], 0, s[94:95]
	global_load_lds_dwordx4 v[186:187], off
	s_mov_b32 m0, s57
	v_lshl_add_u64 v[186:187], v[244:245], 0, s[94:95]
	global_load_lds_dwordx4 v[186:187], off
	s_waitcnt vmcnt(8)
	s_waitcnt lgkmcnt(0)
	s_barrier
	s_waitcnt lgkmcnt(0)
	v_mfma_f32_16x16x32_bf16 v[60:63], v[138:141], v[170:173], v[60:63]
	v_mfma_f32_16x16x32_bf16 v[56:59], v[146:149], v[170:173], v[56:59]
	v_mfma_f32_16x16x32_bf16 v[52:55], v[138:141], v[178:181], v[52:55]
	v_mfma_f32_16x16x32_bf16 v[48:51], v[146:149], v[178:181], v[48:51]
	v_mfma_f32_16x16x32_bf16 v[36:39], v[138:141], v[192:195], v[36:39]
	v_mfma_f32_16x16x32_bf16 v[32:35], v[146:149], v[192:195], v[32:35]
	v_mfma_f32_16x16x32_bf16 v[20:23], v[138:141], v[234:237], v[20:23]
	v_mfma_f32_16x16x32_bf16 v[16:19], v[146:149], v[234:237], v[16:19]
	v_mfma_f32_16x16x32_bf16 v[60:63], v[142:145], v[174:177], v[60:63]
	v_mfma_f32_16x16x32_bf16 v[56:59], v[150:153], v[174:177], v[56:59]
	v_mfma_f32_16x16x32_bf16 v[52:55], v[142:145], v[182:185], v[52:55]
	v_mfma_f32_16x16x32_bf16 v[48:51], v[150:153], v[182:185], v[48:51]
	v_mfma_f32_16x16x32_bf16 v[36:39], v[142:145], v[230:233], v[36:39]
	v_mfma_f32_16x16x32_bf16 v[32:35], v[150:153], v[230:233], v[32:35]
	v_mfma_f32_16x16x32_bf16 v[20:23], v[142:145], v[238:241], v[20:23]
	v_mfma_f32_16x16x32_bf16 v[16:19], v[150:153], v[238:241], v[16:19]
	v_mfma_f32_16x16x32_bf16 v[44:47], v[154:157], v[170:173], v[44:47]
	v_mfma_f32_16x16x32_bf16 v[40:43], v[162:165], v[170:173], v[40:43]
	v_mfma_f32_16x16x32_bf16 v[28:31], v[154:157], v[178:181], v[28:31]
	v_mfma_f32_16x16x32_bf16 v[24:27], v[162:165], v[178:181], v[24:27]
	v_mfma_f32_16x16x32_bf16 v[12:15], v[154:157], v[192:195], v[12:15]
	v_mfma_f32_16x16x32_bf16 v[8:11], v[162:165], v[192:195], v[8:11]
	v_mfma_f32_16x16x32_bf16 v[4:7], v[154:157], v[234:237], v[4:7]
	v_mfma_f32_16x16x32_bf16 v[0:3], v[162:165], v[234:237], v[0:3]
	v_mfma_f32_16x16x32_bf16 v[44:47], v[158:161], v[174:177], v[44:47]
	v_mfma_f32_16x16x32_bf16 v[40:43], v[166:169], v[174:177], v[40:43]
	v_mfma_f32_16x16x32_bf16 v[28:31], v[158:161], v[182:185], v[28:31]
	v_mfma_f32_16x16x32_bf16 v[24:27], v[166:169], v[182:185], v[24:27]
	v_mfma_f32_16x16x32_bf16 v[12:15], v[158:161], v[230:233], v[12:15]
	v_mfma_f32_16x16x32_bf16 v[8:11], v[166:169], v[230:233], v[8:11]
	v_mfma_f32_16x16x32_bf16 v[4:7], v[158:161], v[238:241], v[4:7]
	v_mfma_f32_16x16x32_bf16 v[0:3], v[166:169], v[238:241], v[0:3]
	s_barrier
	s_andn2_b64 vcc, exec, s[8:9]
	s_mov_b64 s[36:37], -1
	s_mov_b64 s[8:9], 0
	s_mov_b64 s[38:39], 0x100
	s_cbranch_vccz .LBB0_901
	s_setprio 0
	s_and_b64 vcc, exec, s[20:21]
	s_cbranch_vccz .LBB0_904
	s_barrier

; #define PG8_STAGE(bufoff, gbase, voff) do { _Pragma("unroll") for (int _i = 0; _i < 2; ++_i) \
;         __builtin_amdgcn_global_load_lds((const unsigned*)((const char*)(gbase) + (voff)[_i]), (PG8_LAS unsigned*)(lds + (bufoff) + ldsw + _i * 8192), 16, 0, 0); } while (0)
; #define PG8_LDA(dst, b, h) do { _Pragma("unroll") for (int m = 0; m < 4; ++m) _Pragma("unroll") for (int k = 0; k < 2; ++k) dst[m][k] = *(const PG8_LAS bf16x8*)(lds + PG8_SA(b, h) + aoff + m * 2048 + k * 1024); } while (0)
; #define PG8_LDB(dst, b, h) do { _Pragma("unroll") for (int n = 0; n < 2; ++n) _Pragma("unroll") for (int k = 0; k < 2; ++k) dst[n][k] = *(const PG8_LAS bf16x8*)(lds + PG8_SB(b, h) + boff + n * 2048 + k * 1024); } while (0)
; #define PG8_SCHED __builtin_amdgcn_sched_barrier(0)
; template <class Epi, class Sched, bool ALIGN_EPI = false, bool SP2 = false>
; __device__ __forceinline__ void gemm_phase(PG8_LAS unsigned char* lds, const Gemm g, const Sched& S, const Epi& E) {
;     ...
;         const char* nA = has_next ? (const char*)g.A + (size_t)nxt.pm * tstepA + (size_t)((nxt.pn / g.kdiv) * g.kmul) * 2 : cA; const char* nB = has_next ? (const char*)g.Bt + (size_t)nxt.pn * tstepB : cB;
; #pragma nounroll
;         for (int t = 0; t < nt; t += 2) {
;             const bool last = (t == nt - 2);
;             const char* a1 = cA + (size_t)(t + 1) * kstep;
;             const char* a2 = last ? nA : cA + (size_t)(t + 2) * kstep; const char* b2 = last ? nB : cB + (size_t)(t + 2) * kstep;
;             const char* a3 = a2 + kstep; const char* b3 = b2 + kstep;
;             if (last && has_next) S.a_ready(nxt);
;             if constexpr (SP2) {
;             PG8_LDB(B0, 0, 0); PG8_LDB(B1, 0, 1); PG8_SCHED; PG8_LDA(At, 0, 0); PG8_STAGE(PG8_SA(1, 1), a1 + hstepA, voffA);
;     ...
; #pragma unroll
;         for (int a = 0; a < 2; ++a)
; #pragma unroll
;             for (int b = 0; b < 2; ++b)
; #pragma unroll
;                 for (int m = 0; m < 4; ++m)
; #pragma unroll
;                     for (int n = 0; n < 2; ++n) acc[a][b][m][n] = (f32x4){0.f, 0.f, 0.f, 0.f};
;         cur = nxt; cA = nA; cB = nB; ++ui;
.LBB0_1641:
	s_add_u32 s26, s26, 0x80
	s_addc_u32 s27, s27, 0
	s_add_u32 s72, s28, 0x100
	v_mov_b32_e32 v0, 0
	s_addc_u32 s73, s29, 0
	s_mov_b32 s28, 0
	v_mov_b32_e32 v1, v0
	v_mov_b32_e32 v2, v0
	v_mov_b32_e32 v3, v0
	v_mov_b32_e32 v16, v0
	v_mov_b32_e32 v17, v0
	v_mov_b32_e32 v18, v0
	v_mov_b32_e32 v19, v0
	v_mov_b32_e32 v4, v0
	v_mov_b32_e32 v5, v0
	v_mov_b32_e32 v6, v0
	v_mov_b32_e32 v7, v0
	v_mov_b32_e32 v24, v0
	v_mov_b32_e32 v25, v0
	v_mov_b32_e32 v26, v0
	v_mov_b32_e32 v27, v0
	v_mov_b32_e32 v8, v0
	v_mov_b32_e32 v9, v0
	v_mov_b32_e32 v10, v0
	v_mov_b32_e32 v11, v0
	v_mov_b32_e32 v32, v0
	v_mov_b32_e32 v33, v0
	v_mov_b32_e32 v34, v0
	v_mov_b32_e32 v35, v0
	v_mov_b32_e32 v12, v0
	v_mov_b32_e32 v13, v0
	v_mov_b32_e32 v14, v0
	v_mov_b32_e32 v15, v0
	v_mov_b32_e32 v40, v0
	v_mov_b32_e32 v41, v0
	v_mov_b32_e32 v42, v0
	v_mov_b32_e32 v43, v0
	v_mov_b32_e32 v52, v0
	v_mov_b32_e32 v53, v0
	v_mov_b32_e32 v54, v0
	v_mov_b32_e32 v55, v0
	v_mov_b32_e32 v84, v0
	v_mov_b32_e32 v85, v0
	v_mov_b32_e32 v86, v0
	v_mov_b32_e32 v87, v0
	v_mov_b32_e32 v60, v0
	v_mov_b32_e32 v61, v0
	v_mov_b32_e32 v62, v0
	v_mov_b32_e32 v63, v0
	v_mov_b32_e32 v100, v0
	v_mov_b32_e32 v101, v0
	v_mov_b32_e32 v102, v0
	v_mov_b32_e32 v103, v0
	v_mov_b32_e32 v68, v0
	v_mov_b32_e32 v69, v0
	v_mov_b32_e32 v70, v0
	v_mov_b32_e32 v71, v0
	v_mov_b32_e32 v104, v0
	v_mov_b32_e32 v105, v0
	v_mov_b32_e32 v106, v0
	v_mov_b32_e32 v107, v0
	v_mov_b32_e32 v76, v0
	v_mov_b32_e32 v77, v0
	v_mov_b32_e32 v78, v0
	v_mov_b32_e32 v79, v0
	v_mov_b32_e32 v108, v0
	v_mov_b32_e32 v109, v0
	v_mov_b32_e32 v110, v0
	v_mov_b32_e32 v111, v0
	v_mov_b32_e32 v20, v0
	v_mov_b32_e32 v21, v0
	v_mov_b32_e32 v22, v0
	v_mov_b32_e32 v23, v0
	v_mov_b32_e32 v48, v0
	v_mov_b32_e32 v49, v0
	v_mov_b32_e32 v50, v0
	v_mov_b32_e32 v51, v0
	v_mov_b32_e32 v28, v0
	v_mov_b32_e32 v29, v0
	v_mov_b32_e32 v30, v0
	v_mov_b32_e32 v31, v0
	v_mov_b32_e32 v56, v0
	v_mov_b32_e32 v57, v0
	v_mov_b32_e32 v58, v0
	v_mov_b32_e32 v59, v0
	v_mov_b32_e32 v36, v0
	v_mov_b32_e32 v37, v0
	v_mov_b32_e32 v38, v0
	v_mov_b32_e32 v39, v0
	v_mov_b32_e32 v64, v0
	v_mov_b32_e32 v65, v0
	v_mov_b32_e32 v66, v0
	v_mov_b32_e32 v67, v0
	v_mov_b32_e32 v44, v0
	v_mov_b32_e32 v45, v0
	v_mov_b32_e32 v46, v0
	v_mov_b32_e32 v47, v0
	v_mov_b32_e32 v72, v0
	v_mov_b32_e32 v73, v0
	v_mov_b32_e32 v74, v0
	v_mov_b32_e32 v75, v0
	v_mov_b32_e32 v80, v0
	v_mov_b32_e32 v81, v0
	v_mov_b32_e32 v82, v0
	v_mov_b32_e32 v83, v0
	v_mov_b32_e32 v112, v0
	v_mov_b32_e32 v113, v0
	v_mov_b32_e32 v114, v0
	v_mov_b32_e32 v115, v0
	v_mov_b32_e32 v88, v0
	v_mov_b32_e32 v89, v0
	v_mov_b32_e32 v90, v0
	v_mov_b32_e32 v91, v0
	v_mov_b32_e32 v116, v0
	v_mov_b32_e32 v117, v0
	v_mov_b32_e32 v118, v0
	v_mov_b32_e32 v119, v0
	v_mov_b32_e32 v92, v0
	v_mov_b32_e32 v93, v0
	v_mov_b32_e32 v94, v0
	v_mov_b32_e32 v95, v0
	v_mov_b32_e32 v120, v0
	v_mov_b32_e32 v121, v0
	v_mov_b32_e32 v122, v0
	v_mov_b32_e32 v123, v0
	v_mov_b32_e32 v96, v0
	v_mov_b32_e32 v97, v0
	v_mov_b32_e32 v98, v0
	v_mov_b32_e32 v99, v0
	v_mov_b32_e32 v124, v0
	v_mov_b32_e32 v125, v0
	v_mov_b32_e32 v126, v0
	v_mov_b32_e32 v127, v0
	v_readfirstlane_b32 s100, v198
	s_nop 3
	s_bitcmp1_b32 s100, 8
	s_cbranch_scc0 .Lgprio_3_skip
	s_setprio 1
.Lgprio_3_skip:
.LBB0_1642:
	v_add_u32_e32 v150, 0x10000, v148
	v_add_u32_e32 v166, 0x14000, v148
	ds_read_b128 v[128:131], v150
	ds_read_b128 v[138:141], v150 offset:1024
	ds_read_b128 v[142:145], v150 offset:2048
	ds_read_b128 v[150:153], v150 offset:3072
	ds_read_b128 v[154:157], v166
	ds_read_b128 v[158:161], v166 offset:1024
	ds_read_b128 v[162:165], v166 offset:2048
	ds_read_b128 v[166:169], v166 offset:3072
	ds_read_b128 v[170:173], v149
	ds_read_b128 v[174:177], v149 offset:1024
	ds_read_b128 v[178:181], v149 offset:2048
	ds_read_b128 v[182:185], v149 offset:3072
	ds_read_b128 v[192:195], v149 offset:4096
	ds_read_b128 v[230:233], v149 offset:5120
	ds_read_b128 v[234:237], v149 offset:6144
	ds_read_b128 v[238:241], v149 offset:7168
	s_add_i32 s74, s28, 2
	s_add_u32 s75, s26, 0x80
	s_addc_u32 s29, s27, 0
	s_add_i32 s78, 0, 0x10000
	s_cmp_eq_u32 s54, s28
	s_cselect_b32 s29, s9, s29
	s_cselect_b32 s28, s8, s75
	s_cselect_b32 s77, s25, s73
	s_cselect_b32 s76, s24, s72
	s_add_i32 s75, 0, 0x14000
	s_add_i32 m0, s36, 0xc000
	v_lshl_add_u64 v[186:187], s[26:27], 0, v[134:135]
	global_load_lds_dwordx4 v[186:187], off
	s_add_i32 m0, s36, 0xe000
	v_lshl_add_u64 v[186:187], s[26:27], 0, v[136:137]
	global_load_lds_dwordx4 v[186:187], off
	s_waitcnt vmcnt(8)
	s_waitcnt lgkmcnt(0)
	s_barrier
; #define PG8_STAGE(bufoff, gbase, voff) do { _Pragma("unroll") for (int _i = 0; _i < 2; ++_i) \
;         __builtin_amdgcn_global_load_lds((const unsigned*)((const char*)(gbase) + (voff)[_i]), (PG8_LAS unsigned*)(lds + (bufoff) + ldsw + _i * 8192), 16, 0, 0); } while (0)
; #define PG8_LDA(dst, b, h) do { _Pragma("unroll") for (int m = 0; m < 4; ++m) _Pragma("unroll") for (int k = 0; k < 2; ++k) dst[m][k] = *(const PG8_LAS bf16x8*)(lds + PG8_SA(b, h) + aoff + m * 2048 + k * 1024); } while (0)
; #define PG8_MMA(ai, bj, At, Bt) do { __builtin_amdgcn_s_setprio(1); _Pragma("unroll") for (int m = 0; m < 4; ++m) _Pragma("unroll") for (int n = 0; n < 2; ++n) _Pragma("unroll") for (int k = 0; k < 2; ++k) \
;         acc[ai][bj][m][n] = __builtin_amdgcn_mfma_f32_16x16x32_bf16(Bt[n][k], At[m][k], acc[ai][bj][m][n], 0, 0, 0); __builtin_amdgcn_s_setprio(0); } while (0)
; #define PG8_WAIT_V(n) asm volatile("s_waitcnt vmcnt(" #n ")" ::: "memory")
; #define PG8_WAIT_L(n) asm volatile("s_waitcnt lgkmcnt(" #n ")" ::: "memory")
; #define PG8_BAR __builtin_amdgcn_s_barrier()
; #define PG8_SCHED __builtin_amdgcn_sched_barrier(0)
; template <class Epi, class Sched, bool ALIGN_EPI = false, bool SP2 = false>
; __device__ __forceinline__ void gemm_phase(PG8_LAS unsigned char* lds, const Gemm g, const Sched& S, const Epi& E) {
;     ...
;             PG8_WAIT_V(8); PG8_WAIT_L(0); PG8_BAR; PG8_MMA(0, 0, At, B0); PG8_MMA(0, 1, At, B1); PG8_BAR; PG8_SCHED;
;             PG8_LDA(At, 0, 1); PG8_STAGE(PG8_SB(0, 0), b2, voffB); PG8_STAGE(PG8_SB(0, 1), b2 + hstepB, voffB); PG8_STAGE(PG8_SA(0, 0), a2, voffA);
;             PG8_WAIT_V(8); PG8_WAIT_L(0); PG8_BAR; PG8_MMA(1, 0, At, B0); PG8_MMA(1, 1, At, B1); PG8_BAR; PG8_SCHED;
	s_waitcnt lgkmcnt(0)
	v_mfma_f32_16x16x32_bf16 v[124:127], v[128:131], v[170:173], v[124:127]
	v_mfma_f32_16x16x32_bf16 v[96:99], v[142:145], v[170:173], v[96:99]
	v_mfma_f32_16x16x32_bf16 v[120:123], v[128:131], v[178:181], v[120:123]
	v_mfma_f32_16x16x32_bf16 v[92:95], v[142:145], v[178:181], v[92:95]
	v_mfma_f32_16x16x32_bf16 v[116:119], v[128:131], v[192:195], v[116:119]
	v_mfma_f32_16x16x32_bf16 v[88:91], v[142:145], v[192:195], v[88:91]
	v_mfma_f32_16x16x32_bf16 v[112:115], v[128:131], v[234:237], v[112:115]
	v_mfma_f32_16x16x32_bf16 v[80:83], v[142:145], v[234:237], v[80:83]
	v_mfma_f32_16x16x32_bf16 v[124:127], v[138:141], v[174:177], v[124:127]
	v_mfma_f32_16x16x32_bf16 v[96:99], v[150:153], v[174:177], v[96:99]
	v_mfma_f32_16x16x32_bf16 v[120:123], v[138:141], v[182:185], v[120:123]
	v_mfma_f32_16x16x32_bf16 v[92:95], v[150:153], v[182:185], v[92:95]
	v_mfma_f32_16x16x32_bf16 v[116:119], v[138:141], v[230:233], v[116:119]
	v_mfma_f32_16x16x32_bf16 v[88:91], v[150:153], v[230:233], v[88:91]
	v_mfma_f32_16x16x32_bf16 v[112:115], v[138:141], v[238:241], v[112:115]
	v_mfma_f32_16x16x32_bf16 v[80:83], v[150:153], v[238:241], v[80:83]
	v_mfma_f32_16x16x32_bf16 v[72:75], v[154:157], v[170:173], v[72:75]
	v_mfma_f32_16x16x32_bf16 v[44:47], v[162:165], v[170:173], v[44:47]
	v_mfma_f32_16x16x32_bf16 v[64:67], v[154:157], v[178:181], v[64:67]
	v_mfma_f32_16x16x32_bf16 v[36:39], v[162:165], v[178:181], v[36:39]
	v_mfma_f32_16x16x32_bf16 v[56:59], v[154:157], v[192:195], v[56:59]
	v_mfma_f32_16x16x32_bf16 v[28:31], v[162:165], v[192:195], v[28:31]
	v_mfma_f32_16x16x32_bf16 v[48:51], v[154:157], v[234:237], v[48:51]
	v_mfma_f32_16x16x32_bf16 v[20:23], v[162:165], v[234:237], v[20:23]
	v_mfma_f32_16x16x32_bf16 v[72:75], v[158:161], v[174:177], v[72:75]
	v_mfma_f32_16x16x32_bf16 v[44:47], v[166:169], v[174:177], v[44:47]
	v_mfma_f32_16x16x32_bf16 v[64:67], v[158:161], v[182:185], v[64:67]
	v_mfma_f32_16x16x32_bf16 v[36:39], v[166:169], v[182:185], v[36:39]
	v_mfma_f32_16x16x32_bf16 v[56:59], v[158:161], v[230:233], v[56:59]
	v_mfma_f32_16x16x32_bf16 v[28:31], v[166:169], v[230:233], v[28:31]
	v_mfma_f32_16x16x32_bf16 v[48:51], v[158:161], v[238:241], v[48:51]
	v_mfma_f32_16x16x32_bf16 v[20:23], v[166:169], v[238:241], v[20:23]
	s_barrier
	ds_read_b128 v[170:173], v149 offset:16384
	ds_read_b128 v[174:177], v149 offset:17408
	ds_read_b128 v[178:181], v149 offset:18432
	ds_read_b128 v[182:185], v149 offset:19456
	ds_read_b128 v[192:195], v149 offset:20480
	ds_read_b128 v[230:233], v149 offset:21504
	ds_read_b128 v[234:237], v149 offset:22528
	ds_read_b128 v[238:241], v149 offset:23552
	s_add_i32 s78, s78, s30
	s_mov_b32 m0, s78
	v_lshl_add_u64 v[186:187], s[76:77], 0, v[188:189]
	global_load_lds_dwordx4 v[186:187], off
	s_add_i32 m0, s78, 0x2000
	v_lshl_add_u64 v[196:197], s[76:77], 0, v[132:133]
	s_add_u32 s76, s76, s44
	s_addc_u32 s77, s77, 0
	s_add_i32 s75, s75, s30
	global_load_lds_dwordx4 v[196:197], off
	v_lshl_add_u64 v[242:243], s[76:77], 0, v[188:189]
	s_mov_b32 m0, s75
	v_lshl_add_u64 v[244:245], s[76:77], 0, v[132:133]
	global_load_lds_dwordx4 v[242:243], off
	s_add_i32 m0, s75, 0x2000
	v_lshl_add_u64 v[246:247], s[28:29], 0, v[188:189]
	global_load_lds_dwordx4 v[244:245], off
	s_mov_b32 m0, s36
	v_lshl_add_u64 v[248:249], s[28:29], 0, v[132:133]
	global_load_lds_dwordx4 v[246:247], off
	s_mov_b32 m0, s37
	s_nop 0
	global_load_lds_dwordx4 v[248:249], off
	s_waitcnt vmcnt(8)
	s_waitcnt lgkmcnt(0)
	s_barrier
	s_waitcnt lgkmcnt(0)
	v_mfma_f32_16x16x32_bf16 v[108:111], v[128:131], v[170:173], v[108:111]
	v_mfma_f32_16x16x32_bf16 v[76:79], v[142:145], v[170:173], v[76:79]
	v_mfma_f32_16x16x32_bf16 v[104:107], v[128:131], v[178:181], v[104:107]
	v_mfma_f32_16x16x32_bf16 v[68:71], v[142:145], v[178:181], v[68:71]
	v_mfma_f32_16x16x32_bf16 v[100:103], v[128:131], v[192:195], v[100:103]
	v_mfma_f32_16x16x32_bf16 v[60:63], v[142:145], v[192:195], v[60:63]
	v_mfma_f32_16x16x32_bf16 v[84:87], v[128:131], v[234:237], v[84:87]
	v_mfma_f32_16x16x32_bf16 v[52:55], v[142:145], v[234:237], v[52:55]
	v_mfma_f32_16x16x32_bf16 v[108:111], v[138:141], v[174:177], v[108:111]
	v_mfma_f32_16x16x32_bf16 v[76:79], v[150:153], v[174:177], v[76:79]
	v_mfma_f32_16x16x32_bf16 v[104:107], v[138:141], v[182:185], v[104:107]
	v_mfma_f32_16x16x32_bf16 v[68:71], v[150:153], v[182:185], v[68:71]
	v_mfma_f32_16x16x32_bf16 v[100:103], v[138:141], v[230:233], v[100:103]
	v_mfma_f32_16x16x32_bf16 v[60:63], v[150:153], v[230:233], v[60:63]
	v_mfma_f32_16x16x32_bf16 v[84:87], v[138:141], v[238:241], v[84:87]
	v_mfma_f32_16x16x32_bf16 v[52:55], v[150:153], v[238:241], v[52:55]
	v_mfma_f32_16x16x32_bf16 v[40:43], v[154:157], v[170:173], v[40:43]
	v_mfma_f32_16x16x32_bf16 v[12:15], v[162:165], v[170:173], v[12:15]
	v_mfma_f32_16x16x32_bf16 v[32:35], v[154:157], v[178:181], v[32:35]
	v_mfma_f32_16x16x32_bf16 v[8:11], v[162:165], v[178:181], v[8:11]
	v_mfma_f32_16x16x32_bf16 v[24:27], v[154:157], v[192:195], v[24:27]
	v_mfma_f32_16x16x32_bf16 v[4:7], v[162:165], v[192:195], v[4:7]
	v_mfma_f32_16x16x32_bf16 v[16:19], v[154:157], v[234:237], v[16:19]
	v_mfma_f32_16x16x32_bf16 v[0:3], v[162:165], v[234:237], v[0:3]
	v_mfma_f32_16x16x32_bf16 v[40:43], v[158:161], v[174:177], v[40:43]
	v_mfma_f32_16x16x32_bf16 v[12:15], v[166:169], v[174:177], v[12:15]
	v_mfma_f32_16x16x32_bf16 v[32:35], v[158:161], v[182:185], v[32:35]
	v_mfma_f32_16x16x32_bf16 v[8:11], v[166:169], v[182:185], v[8:11]
	v_mfma_f32_16x16x32_bf16 v[24:27], v[158:161], v[230:233], v[24:27]
	v_mfma_f32_16x16x32_bf16 v[4:7], v[166:169], v[230:233], v[4:7]
	v_mfma_f32_16x16x32_bf16 v[16:19], v[158:161], v[238:241], v[16:19]
	v_mfma_f32_16x16x32_bf16 v[0:3], v[166:169], v[238:241], v[0:3]
	s_barrier
; #define PG8_STAGE(bufoff, gbase, voff) do { _Pragma("unroll") for (int _i = 0; _i < 2; ++_i) \
;         __builtin_amdgcn_global_load_lds((const unsigned*)((const char*)(gbase) + (voff)[_i]), (PG8_LAS unsigned*)(lds + (bufoff) + ldsw + _i * 8192), 16, 0, 0); } while (0)
; #define PG8_LDA(dst, b, h) do { _Pragma("unroll") for (int m = 0; m < 4; ++m) _Pragma("unroll") for (int k = 0; k < 2; ++k) dst[m][k] = *(const PG8_LAS bf16x8*)(lds + PG8_SA(b, h) + aoff + m * 2048 + k * 1024); } while (0)
; #define PG8_LDB(dst, b, h) do { _Pragma("unroll") for (int n = 0; n < 2; ++n) _Pragma("unroll") for (int k = 0; k < 2; ++k) dst[n][k] = *(const PG8_LAS bf16x8*)(lds + PG8_SB(b, h) + boff + n * 2048 + k * 1024); } while (0)
; #define PG8_MMA(ai, bj, At, Bt) do { __builtin_amdgcn_s_setprio(1); _Pragma("unroll") for (int m = 0; m < 4; ++m) _Pragma("unroll") for (int n = 0; n < 2; ++n) _Pragma("unroll") for (int k = 0; k < 2; ++k) \
;         acc[ai][bj][m][n] = __builtin_amdgcn_mfma_f32_16x16x32_bf16(Bt[n][k], At[m][k], acc[ai][bj][m][n], 0, 0, 0); __builtin_amdgcn_s_setprio(0); } while (0)
; #define PG8_WAIT_V(n) asm volatile("s_waitcnt vmcnt(" #n ")" ::: "memory")
; #define PG8_WAIT_L(n) asm volatile("s_waitcnt lgkmcnt(" #n ")" ::: "memory")
; #define PG8_BAR __builtin_amdgcn_s_barrier()
; #define PG8_SCHED __builtin_amdgcn_sched_barrier(0)
; template <class Epi, class Sched, bool ALIGN_EPI = false, bool SP2 = false>
; __device__ __forceinline__ void gemm_phase(PG8_LAS unsigned char* lds, const Gemm g, const Sched& S, const Epi& E) {
;     ...
;             PG8_LDB(B0, 1, 0); PG8_LDB(B1, 1, 1); PG8_SCHED; PG8_LDA(At, 1, 0); PG8_STAGE(PG8_SA(0, 1), a2 + hstepA, voffA);
;             PG8_WAIT_V(8); PG8_WAIT_L(0); PG8_BAR; PG8_MMA(0, 0, At, B0); PG8_MMA(0, 1, At, B1); PG8_BAR; PG8_SCHED;
;             PG8_LDA(At, 1, 1); PG8_STAGE(PG8_SB(1, 0), b3, voffB); PG8_STAGE(PG8_SB(1, 1), b3 + hstepB, voffB); PG8_STAGE(PG8_SA(1, 0), a3, voffA);
;             PG8_WAIT_V(8); PG8_WAIT_L(0); PG8_BAR; PG8_MMA(1, 0, At, B0); PG8_MMA(1, 1, At, B1); PG8_BAR; PG8_SCHED;
	v_add_u32_e32 v150, 0x18000, v148
	v_add_u32_e32 v166, 0x1c000, v148
	ds_read_b128 v[128:131], v150
	ds_read_b128 v[138:141], v150 offset:1024
	ds_read_b128 v[142:145], v150 offset:2048
	ds_read_b128 v[150:153], v150 offset:3072
	ds_read_b128 v[154:157], v166
	ds_read_b128 v[158:161], v166 offset:1024
	ds_read_b128 v[162:165], v166 offset:2048
	ds_read_b128 v[166:169], v166 offset:3072
	ds_read_b128 v[170:173], v149 offset:32768
	ds_read_b128 v[174:177], v149 offset:33792
	ds_read_b128 v[178:181], v149 offset:34816
	ds_read_b128 v[182:185], v149 offset:35840
	ds_read_b128 v[192:195], v149 offset:36864
	ds_read_b128 v[230:233], v149 offset:37888
	ds_read_b128 v[234:237], v149 offset:38912
	ds_read_b128 v[238:241], v149 offset:39936
	s_add_i32 s75, 0, 0x18000
	s_add_i32 s76, 0, 0x1c000
	s_add_u32 s28, s28, s44
	s_addc_u32 s29, s29, 0
	s_mov_b32 m0, s46
	v_lshl_add_u64 v[250:251], s[28:29], 0, v[188:189]
	global_load_lds_dwordx4 v[250:251], off
	s_mov_b32 m0, s47
	v_lshl_add_u64 v[250:251], s[28:29], 0, v[132:133]
	global_load_lds_dwordx4 v[250:251], off
	s_waitcnt vmcnt(8)
	s_waitcnt lgkmcnt(0)
	s_barrier
	s_waitcnt lgkmcnt(0)
	v_mfma_f32_16x16x32_bf16 v[124:127], v[128:131], v[170:173], v[124:127]
	v_mfma_f32_16x16x32_bf16 v[96:99], v[142:145], v[170:173], v[96:99]
	v_mfma_f32_16x16x32_bf16 v[120:123], v[128:131], v[178:181], v[120:123]
	v_mfma_f32_16x16x32_bf16 v[92:95], v[142:145], v[178:181], v[92:95]
	v_mfma_f32_16x16x32_bf16 v[116:119], v[128:131], v[192:195], v[116:119]
	v_mfma_f32_16x16x32_bf16 v[88:91], v[142:145], v[192:195], v[88:91]
	v_mfma_f32_16x16x32_bf16 v[112:115], v[128:131], v[234:237], v[112:115]
	v_mfma_f32_16x16x32_bf16 v[80:83], v[142:145], v[234:237], v[80:83]
	v_mfma_f32_16x16x32_bf16 v[124:127], v[138:141], v[174:177], v[124:127]
	v_mfma_f32_16x16x32_bf16 v[96:99], v[150:153], v[174:177], v[96:99]
	v_mfma_f32_16x16x32_bf16 v[120:123], v[138:141], v[182:185], v[120:123]
	v_mfma_f32_16x16x32_bf16 v[92:95], v[150:153], v[182:185], v[92:95]
	v_mfma_f32_16x16x32_bf16 v[116:119], v[138:141], v[230:233], v[116:119]
	v_mfma_f32_16x16x32_bf16 v[88:91], v[150:153], v[230:233], v[88:91]
	v_mfma_f32_16x16x32_bf16 v[112:115], v[138:141], v[238:241], v[112:115]
	v_mfma_f32_16x16x32_bf16 v[80:83], v[150:153], v[238:241], v[80:83]
	v_mfma_f32_16x16x32_bf16 v[72:75], v[154:157], v[170:173], v[72:75]
	v_mfma_f32_16x16x32_bf16 v[44:47], v[162:165], v[170:173], v[44:47]
	v_mfma_f32_16x16x32_bf16 v[64:67], v[154:157], v[178:181], v[64:67]
	v_mfma_f32_16x16x32_bf16 v[36:39], v[162:165], v[178:181], v[36:39]
	v_mfma_f32_16x16x32_bf16 v[56:59], v[154:157], v[192:195], v[56:59]
	v_mfma_f32_16x16x32_bf16 v[28:31], v[162:165], v[192:195], v[28:31]
	v_mfma_f32_16x16x32_bf16 v[48:51], v[154:157], v[234:237], v[48:51]
	v_mfma_f32_16x16x32_bf16 v[20:23], v[162:165], v[234:237], v[20:23]
	v_mfma_f32_16x16x32_bf16 v[72:75], v[158:161], v[174:177], v[72:75]
	v_mfma_f32_16x16x32_bf16 v[44:47], v[166:169], v[174:177], v[44:47]
	v_mfma_f32_16x16x32_bf16 v[64:67], v[158:161], v[182:185], v[64:67]
	v_mfma_f32_16x16x32_bf16 v[36:39], v[166:169], v[182:185], v[36:39]
	v_mfma_f32_16x16x32_bf16 v[56:59], v[158:161], v[230:233], v[56:59]
	v_mfma_f32_16x16x32_bf16 v[28:31], v[166:169], v[230:233], v[28:31]
	v_mfma_f32_16x16x32_bf16 v[48:51], v[158:161], v[238:241], v[48:51]
	v_mfma_f32_16x16x32_bf16 v[20:23], v[166:169], v[238:241], v[20:23]
	s_barrier
	ds_read_b128 v[170:173], v149 offset:49152
	ds_read_b128 v[174:177], v149 offset:50176
	ds_read_b128 v[178:181], v149 offset:51200
	ds_read_b128 v[182:185], v149 offset:52224
	ds_read_b128 v[192:195], v149 offset:53248
	ds_read_b128 v[230:233], v149 offset:54272
	ds_read_b128 v[234:237], v149 offset:55296
	ds_read_b128 v[238:241], v149 offset:56320
	s_add_i32 s28, s75, s30
	s_mov_b32 m0, s28
	v_lshl_add_u64 v[186:187], v[186:187], 0, s[94:95]
	global_load_lds_dwordx4 v[186:187], off
	v_lshl_add_u64 v[186:187], v[196:197], 0, s[94:95]
	s_add_i32 m0, s28, 0x2000
	s_add_i32 s28, s76, s30
	global_load_lds_dwordx4 v[186:187], off
	s_mov_b32 m0, s28
	v_lshl_add_u64 v[186:187], v[242:243], 0, s[94:95]
	global_load_lds_dwordx4 v[186:187], off
	s_add_i32 m0, s28, 0x2000
	v_lshl_add_u64 v[186:187], v[244:245], 0, s[94:95]
	global_load_lds_dwordx4 v[186:187], off
	s_mov_b32 m0, s62
	v_lshl_add_u64 v[186:187], v[246:247], 0, s[94:95]
	global_load_lds_dwordx4 v[186:187], off
	s_mov_b32 m0, s63
	v_lshl_add_u64 v[186:187], v[248:249], 0, s[94:95]
	global_load_lds_dwordx4 v[186:187], off
	s_waitcnt vmcnt(8)
	s_waitcnt lgkmcnt(0)
	s_barrier
	s_waitcnt lgkmcnt(0)
	v_mfma_f32_16x16x32_bf16 v[108:111], v[128:131], v[170:173], v[108:111]
	v_mfma_f32_16x16x32_bf16 v[76:79], v[142:145], v[170:173], v[76:79]
	v_mfma_f32_16x16x32_bf16 v[104:107], v[128:131], v[178:181], v[104:107]
	v_mfma_f32_16x16x32_bf16 v[68:71], v[142:145], v[178:181], v[68:71]
	v_mfma_f32_16x16x32_bf16 v[100:103], v[128:131], v[192:195], v[100:103]
	v_mfma_f32_16x16x32_bf16 v[60:63], v[142:145], v[192:195], v[60:63]
	v_mfma_f32_16x16x32_bf16 v[84:87], v[128:131], v[234:237], v[84:87]
	v_mfma_f32_16x16x32_bf16 v[52:55], v[142:145], v[234:237], v[52:55]
	v_mfma_f32_16x16x32_bf16 v[108:111], v[138:141], v[174:177], v[108:111]
	v_mfma_f32_16x16x32_bf16 v[76:79], v[150:153], v[174:177], v[76:79]
	v_mfma_f32_16x16x32_bf16 v[104:107], v[138:141], v[182:185], v[104:107]
	v_mfma_f32_16x16x32_bf16 v[68:71], v[150:153], v[182:185], v[68:71]
	v_mfma_f32_16x16x32_bf16 v[100:103], v[138:141], v[230:233], v[100:103]
	v_mfma_f32_16x16x32_bf16 v[60:63], v[150:153], v[230:233], v[60:63]
	v_mfma_f32_16x16x32_bf16 v[84:87], v[138:141], v[238:241], v[84:87]
	v_mfma_f32_16x16x32_bf16 v[52:55], v[150:153], v[238:241], v[52:55]
	v_mfma_f32_16x16x32_bf16 v[40:43], v[154:157], v[170:173], v[40:43]
	v_mfma_f32_16x16x32_bf16 v[12:15], v[162:165], v[170:173], v[12:15]
	v_mfma_f32_16x16x32_bf16 v[32:35], v[154:157], v[178:181], v[32:35]
	v_mfma_f32_16x16x32_bf16 v[8:11], v[162:165], v[178:181], v[8:11]
	v_mfma_f32_16x16x32_bf16 v[24:27], v[154:157], v[192:195], v[24:27]
	v_mfma_f32_16x16x32_bf16 v[4:7], v[162:165], v[192:195], v[4:7]
	v_mfma_f32_16x16x32_bf16 v[16:19], v[154:157], v[234:237], v[16:19]
	v_mfma_f32_16x16x32_bf16 v[0:3], v[162:165], v[234:237], v[0:3]
	v_mfma_f32_16x16x32_bf16 v[40:43], v[158:161], v[174:177], v[40:43]
	v_mfma_f32_16x16x32_bf16 v[12:15], v[166:169], v[174:177], v[12:15]
	v_mfma_f32_16x16x32_bf16 v[32:35], v[158:161], v[182:185], v[32:35]
	v_mfma_f32_16x16x32_bf16 v[8:11], v[166:169], v[182:185], v[8:11]
	v_mfma_f32_16x16x32_bf16 v[24:27], v[158:161], v[230:233], v[24:27]
	v_mfma_f32_16x16x32_bf16 v[4:7], v[166:169], v[230:233], v[4:7]
	v_mfma_f32_16x16x32_bf16 v[16:19], v[158:161], v[238:241], v[16:19]
	v_mfma_f32_16x16x32_bf16 v[0:3], v[166:169], v[238:241], v[0:3]
	s_barrier
	s_add_u32 s26, s26, 0x100
	s_addc_u32 s27, s27, 0
	s_add_u32 s72, s72, 0x100
	s_addc_u32 s73, s73, 0
	s_cmp_ge_u32 s74, s52
	s_mov_b32 s28, s74
	s_cbranch_scc0 .LBB0_1642
	s_setprio 0
	s_and_b64 vcc, exec, s[14:15]
	s_cbranch_vccz .LBB0_1645
	s_barrier

; #define PG8_STAGE(bufoff, gbase, voff) do { _Pragma("unroll") for (int _i = 0; _i < 2; ++_i) \
;         __builtin_amdgcn_global_load_lds((const unsigned*)((const char*)(gbase) + (voff)[_i]), (PG8_LAS unsigned*)(lds + (bufoff) + ldsw + _i * 8192), 16, 0, 0); } while (0)
; #define PG8_LDA(dst, b, h) do { _Pragma("unroll") for (int m = 0; m < 4; ++m) _Pragma("unroll") for (int k = 0; k < 2; ++k) dst[m][k] = *(const PG8_LAS bf16x8*)(lds + PG8_SA(b, h) + aoff + m * 2048 + k * 1024); } while (0)
; #define PG8_LDB(dst, b, h) do { _Pragma("unroll") for (int n = 0; n < 2; ++n) _Pragma("unroll") for (int k = 0; k < 2; ++k) dst[n][k] = *(const PG8_LAS bf16x8*)(lds + PG8_SB(b, h) + boff + n * 2048 + k * 1024); } while (0)
; #define PG8_SCHED __builtin_amdgcn_sched_barrier(0)
; template <class Epi, class Sched, bool ALIGN_EPI = false, bool SP2 = false>
; __device__ __forceinline__ void gemm_phase(PG8_LAS unsigned char* lds, const Gemm g, const Sched& S, const Epi& E) {
;     ...
;         const char* nA = has_next ? (const char*)g.A + (size_t)nxt.pm * tstepA + (size_t)((nxt.pn / g.kdiv) * g.kmul) * 2 : cA; const char* nB = has_next ? (const char*)g.Bt + (size_t)nxt.pn * tstepB : cB;
; #pragma nounroll
;         for (int t = 0; t < nt; t += 2) {
;             const bool last = (t == nt - 2);
;             const char* a1 = cA + (size_t)(t + 1) * kstep;
;             const char* a2 = last ? nA : cA + (size_t)(t + 2) * kstep; const char* b2 = last ? nB : cB + (size_t)(t + 2) * kstep;
;             const char* a3 = a2 + kstep; const char* b3 = b2 + kstep;
;             if (last && has_next) S.a_ready(nxt);
;             if constexpr (SP2) {
;             PG8_LDB(B0, 0, 0); PG8_LDB(B1, 0, 1); PG8_SCHED; PG8_LDA(At, 0, 0); PG8_STAGE(PG8_SA(1, 1), a1 + hstepA, voffA);
;     ...
; #pragma unroll
;         for (int a = 0; a < 2; ++a)
; #pragma unroll
;             for (int b = 0; b < 2; ++b)
; #pragma unroll
;                 for (int m = 0; m < 4; ++m)
; #pragma unroll
;                     for (int n = 0; n < 2; ++n) acc[a][b][m][n] = (f32x4){0.f, 0.f, 0.f, 0.f};
;         cur = nxt; cA = nA; cB = nB; ++ui;
.LBB0_1799:
	s_ashr_i32 s37, s36, 31
	s_lshl_b64 s[8:9], s[36:37], 19
	s_add_u32 s40, s33, s8
	s_addc_u32 s41, s50, s9
	s_and_b64 s[8:9], s[6:7], exec
	s_cselect_b32 s13, s41, s47
	s_cselect_b32 s15, s40, s46
	s_ashr_i32 s35, s34, 31
	s_lshl_b64 s[8:9], s[34:35], 19
	s_add_u32 s42, s51, s8
	s_addc_u32 s43, s52, s9
	s_and_b64 s[8:9], s[6:7], exec
	s_cselect_b32 s35, s43, s45
	s_cselect_b32 s37, s42, s44
	s_add_u32 s8, s46, 0x40080
	s_addc_u32 s9, s47, 0
	s_add_u32 s46, s44, 0x100
	v_mov_b32_e32 v0, 0
	s_addc_u32 s47, s45, 0
	s_mov_b32 s70, -2
	v_mov_b32_e32 v1, v0
	v_mov_b32_e32 v2, v0
	v_mov_b32_e32 v3, v0
	v_mov_b32_e32 v64, v0
	v_mov_b32_e32 v65, v0
	v_mov_b32_e32 v66, v0
	v_mov_b32_e32 v67, v0
	v_mov_b32_e32 v20, v0
	v_mov_b32_e32 v21, v0
	v_mov_b32_e32 v22, v0
	v_mov_b32_e32 v23, v0
	v_mov_b32_e32 v84, v0
	v_mov_b32_e32 v85, v0
	v_mov_b32_e32 v86, v0
	v_mov_b32_e32 v87, v0
	v_mov_b32_e32 v4, v0
	v_mov_b32_e32 v5, v0
	v_mov_b32_e32 v6, v0
	v_mov_b32_e32 v7, v0
	v_mov_b32_e32 v28, v0
	v_mov_b32_e32 v29, v0
	v_mov_b32_e32 v30, v0
	v_mov_b32_e32 v31, v0
	v_mov_b32_e32 v32, v0
	v_mov_b32_e32 v33, v0
	v_mov_b32_e32 v34, v0
	v_mov_b32_e32 v35, v0
	v_mov_b32_e32 v96, v0
	v_mov_b32_e32 v97, v0
	v_mov_b32_e32 v98, v0
	v_mov_b32_e32 v99, v0
	v_mov_b32_e32 v52, v0
	v_mov_b32_e32 v53, v0
	v_mov_b32_e32 v54, v0
	v_mov_b32_e32 v55, v0
	v_mov_b32_e32 v116, v0
	v_mov_b32_e32 v117, v0
	v_mov_b32_e32 v118, v0
	v_mov_b32_e32 v119, v0
	v_mov_b32_e32 v36, v0
	v_mov_b32_e32 v37, v0
	v_mov_b32_e32 v38, v0
	v_mov_b32_e32 v39, v0
	v_mov_b32_e32 v60, v0
	v_mov_b32_e32 v61, v0
	v_mov_b32_e32 v62, v0
	v_mov_b32_e32 v63, v0
	v_mov_b32_e32 v124, v0
	v_mov_b32_e32 v125, v0
	v_mov_b32_e32 v126, v0
	v_mov_b32_e32 v127, v0
	v_mov_b32_e32 v100, v0
	v_mov_b32_e32 v101, v0
	v_mov_b32_e32 v102, v0
	v_mov_b32_e32 v103, v0
	v_mov_b32_e32 v92, v0
	v_mov_b32_e32 v93, v0
	v_mov_b32_e32 v94, v0
	v_mov_b32_e32 v95, v0
	v_mov_b32_e32 v68, v0
	v_mov_b32_e32 v69, v0
	v_mov_b32_e32 v70, v0
	v_mov_b32_e32 v71, v0
	v_mov_b32_e32 v8, v0
	v_mov_b32_e32 v9, v0
	v_mov_b32_e32 v10, v0
	v_mov_b32_e32 v11, v0
	v_mov_b32_e32 v72, v0
	v_mov_b32_e32 v73, v0
	v_mov_b32_e32 v74, v0
	v_mov_b32_e32 v75, v0
	v_mov_b32_e32 v16, v0
	v_mov_b32_e32 v17, v0
	v_mov_b32_e32 v18, v0
	v_mov_b32_e32 v19, v0
	v_mov_b32_e32 v80, v0
	v_mov_b32_e32 v81, v0
	v_mov_b32_e32 v82, v0
	v_mov_b32_e32 v83, v0
	v_mov_b32_e32 v12, v0
	v_mov_b32_e32 v13, v0
	v_mov_b32_e32 v14, v0
	v_mov_b32_e32 v15, v0
	v_mov_b32_e32 v76, v0
	v_mov_b32_e32 v77, v0
	v_mov_b32_e32 v78, v0
	v_mov_b32_e32 v79, v0
	v_mov_b32_e32 v24, v0
	v_mov_b32_e32 v25, v0
	v_mov_b32_e32 v26, v0
	v_mov_b32_e32 v27, v0
	v_mov_b32_e32 v88, v0
	v_mov_b32_e32 v89, v0
	v_mov_b32_e32 v90, v0
	v_mov_b32_e32 v91, v0
	v_mov_b32_e32 v40, v0
	v_mov_b32_e32 v41, v0
	v_mov_b32_e32 v42, v0
	v_mov_b32_e32 v43, v0
	v_mov_b32_e32 v104, v0
	v_mov_b32_e32 v105, v0
	v_mov_b32_e32 v106, v0
	v_mov_b32_e32 v107, v0
	v_mov_b32_e32 v48, v0
	v_mov_b32_e32 v49, v0
	v_mov_b32_e32 v50, v0
	v_mov_b32_e32 v51, v0
	v_mov_b32_e32 v112, v0
	v_mov_b32_e32 v113, v0
	v_mov_b32_e32 v114, v0
	v_mov_b32_e32 v115, v0
	v_mov_b32_e32 v44, v0
	v_mov_b32_e32 v45, v0
	v_mov_b32_e32 v46, v0
	v_mov_b32_e32 v47, v0
	v_mov_b32_e32 v108, v0
	v_mov_b32_e32 v109, v0
	v_mov_b32_e32 v110, v0
	v_mov_b32_e32 v111, v0
	v_mov_b32_e32 v56, v0
	v_mov_b32_e32 v57, v0
	v_mov_b32_e32 v58, v0
	v_mov_b32_e32 v59, v0
	v_mov_b32_e32 v120, v0
	v_mov_b32_e32 v121, v0
	v_mov_b32_e32 v122, v0
	v_mov_b32_e32 v123, v0
	v_readfirstlane_b32 s100, v198
	s_nop 3
	s_bitcmp1_b32 s100, 8
	s_cbranch_scc0 .Lgprio_4_skip
	s_setprio 1
.Lgprio_4_skip:
.LBB0_1800:
	v_add_u32_e32 v140, 0x10000, v229
	v_add_u32_e32 v156, 0x14000, v229
	ds_read_b128 v[128:131], v140
	ds_read_b128 v[132:135], v140 offset:1024
	ds_read_b128 v[136:139], v140 offset:2048
	ds_read_b128 v[140:143], v140 offset:3072
	ds_read_b128 v[144:147], v156
	ds_read_b128 v[148:151], v156 offset:1024
	ds_read_b128 v[152:155], v156 offset:2048
	ds_read_b128 v[156:159], v156 offset:3072
	ds_read_b128 v[160:163], v230
	ds_read_b128 v[164:167], v230 offset:1024
	ds_read_b128 v[178:181], v230 offset:2048
	ds_read_b128 v[182:185], v230 offset:3072
	ds_read_b128 v[192:195], v230 offset:4096
	ds_read_b128 v[232:235], v230 offset:5120
	ds_read_b128 v[236:239], v230 offset:6144
	ds_read_b128 v[240:243], v230 offset:7168
	s_add_u32 s10, s8, 0xfffc0080
	s_addc_u32 s11, s9, -1
	s_add_i32 s71, 0, 0x10000
	s_cmp_eq_u32 s70, 12
	s_cselect_b32 s45, s13, s11
	s_cselect_b32 s44, s15, s10
	s_cselect_b32 s11, s35, s47
	s_cselect_b32 s10, s37, s46
	s_add_i32 s74, 0, 0x14000
	s_add_i32 m0, s54, 0xc000
	v_lshl_add_u64 v[186:187], s[8:9], 0, v[174:175]
	global_load_lds_dwordx4 v[186:187], off
	s_add_i32 m0, s54, 0xe000
	v_lshl_add_u64 v[186:187], s[8:9], 0, v[176:177]
	global_load_lds_dwordx4 v[186:187], off
	s_waitcnt vmcnt(8)
	s_waitcnt lgkmcnt(0)
	s_barrier
; #define PG8_STAGE(bufoff, gbase, voff) do { _Pragma("unroll") for (int _i = 0; _i < 2; ++_i) \
;         __builtin_amdgcn_global_load_lds((const unsigned*)((const char*)(gbase) + (voff)[_i]), (PG8_LAS unsigned*)(lds + (bufoff) + ldsw + _i * 8192), 16, 0, 0); } while (0)
; #define PG8_LDA(dst, b, h) do { _Pragma("unroll") for (int m = 0; m < 4; ++m) _Pragma("unroll") for (int k = 0; k < 2; ++k) dst[m][k] = *(const PG8_LAS bf16x8*)(lds + PG8_SA(b, h) + aoff + m * 2048 + k * 1024); } while (0)
; #define PG8_MMA(ai, bj, At, Bt) do { __builtin_amdgcn_s_setprio(1); _Pragma("unroll") for (int m = 0; m < 4; ++m) _Pragma("unroll") for (int n = 0; n < 2; ++n) _Pragma("unroll") for (int k = 0; k < 2; ++k) \
;         acc[ai][bj][m][n] = __builtin_amdgcn_mfma_f32_16x16x32_bf16(Bt[n][k], At[m][k], acc[ai][bj][m][n], 0, 0, 0); __builtin_amdgcn_s_setprio(0); } while (0)
; #define PG8_WAIT_V(n) asm volatile("s_waitcnt vmcnt(" #n ")" ::: "memory")
; #define PG8_WAIT_L(n) asm volatile("s_waitcnt lgkmcnt(" #n ")" ::: "memory")
; #define PG8_BAR __builtin_amdgcn_s_barrier()
; #define PG8_SCHED __builtin_amdgcn_sched_barrier(0)
; template <class Epi, class Sched, bool ALIGN_EPI = false, bool SP2 = false>
; __device__ __forceinline__ void gemm_phase(PG8_LAS unsigned char* lds, const Gemm g, const Sched& S, const Epi& E) {
;     ...
;             PG8_WAIT_V(8); PG8_WAIT_L(0); PG8_BAR; PG8_MMA(0, 0, At, B0); PG8_MMA(0, 1, At, B1); PG8_BAR; PG8_SCHED;
;             PG8_LDA(At, 0, 1); PG8_STAGE(PG8_SB(0, 0), b2, voffB); PG8_STAGE(PG8_SB(0, 1), b2 + hstepB, voffB); PG8_STAGE(PG8_SA(0, 0), a2, voffA);
;             PG8_WAIT_V(8); PG8_WAIT_L(0); PG8_BAR; PG8_MMA(1, 0, At, B0); PG8_MMA(1, 1, At, B1); PG8_BAR; PG8_SCHED;
	s_waitcnt lgkmcnt(0)
	v_mfma_f32_16x16x32_bf16 v[124:127], v[128:131], v[160:163], v[124:127]
	v_mfma_f32_16x16x32_bf16 v[60:63], v[136:139], v[160:163], v[60:63]
	v_mfma_f32_16x16x32_bf16 v[120:123], v[128:131], v[178:181], v[120:123]
	v_mfma_f32_16x16x32_bf16 v[56:59], v[136:139], v[178:181], v[56:59]
	v_mfma_f32_16x16x32_bf16 v[108:111], v[128:131], v[192:195], v[108:111]
	v_mfma_f32_16x16x32_bf16 v[44:47], v[136:139], v[192:195], v[44:47]
	v_mfma_f32_16x16x32_bf16 v[100:103], v[128:131], v[236:239], v[100:103]
	v_mfma_f32_16x16x32_bf16 v[36:39], v[136:139], v[236:239], v[36:39]
	v_mfma_f32_16x16x32_bf16 v[124:127], v[132:135], v[164:167], v[124:127]
	v_mfma_f32_16x16x32_bf16 v[60:63], v[140:143], v[164:167], v[60:63]
	v_mfma_f32_16x16x32_bf16 v[120:123], v[132:135], v[182:185], v[120:123]
	v_mfma_f32_16x16x32_bf16 v[56:59], v[140:143], v[182:185], v[56:59]
	v_mfma_f32_16x16x32_bf16 v[108:111], v[132:135], v[232:235], v[108:111]
	v_mfma_f32_16x16x32_bf16 v[44:47], v[140:143], v[232:235], v[44:47]
	v_mfma_f32_16x16x32_bf16 v[100:103], v[132:135], v[240:243], v[100:103]
	v_mfma_f32_16x16x32_bf16 v[36:39], v[140:143], v[240:243], v[36:39]
	v_mfma_f32_16x16x32_bf16 v[116:119], v[144:147], v[160:163], v[116:119]
	v_mfma_f32_16x16x32_bf16 v[52:55], v[152:155], v[160:163], v[52:55]
	v_mfma_f32_16x16x32_bf16 v[112:115], v[144:147], v[178:181], v[112:115]
	v_mfma_f32_16x16x32_bf16 v[48:51], v[152:155], v[178:181], v[48:51]
	v_mfma_f32_16x16x32_bf16 v[104:107], v[144:147], v[192:195], v[104:107]
	v_mfma_f32_16x16x32_bf16 v[40:43], v[152:155], v[192:195], v[40:43]
	v_mfma_f32_16x16x32_bf16 v[96:99], v[144:147], v[236:239], v[96:99]
	v_mfma_f32_16x16x32_bf16 v[32:35], v[152:155], v[236:239], v[32:35]
	v_mfma_f32_16x16x32_bf16 v[116:119], v[148:151], v[164:167], v[116:119]
	v_mfma_f32_16x16x32_bf16 v[52:55], v[156:159], v[164:167], v[52:55]
	v_mfma_f32_16x16x32_bf16 v[112:115], v[148:151], v[182:185], v[112:115]
	v_mfma_f32_16x16x32_bf16 v[48:51], v[156:159], v[182:185], v[48:51]
	v_mfma_f32_16x16x32_bf16 v[104:107], v[148:151], v[232:235], v[104:107]
	v_mfma_f32_16x16x32_bf16 v[40:43], v[156:159], v[232:235], v[40:43]
	v_mfma_f32_16x16x32_bf16 v[96:99], v[148:151], v[240:243], v[96:99]
	v_mfma_f32_16x16x32_bf16 v[32:35], v[156:159], v[240:243], v[32:35]
	s_barrier
	ds_read_b128 v[160:163], v230 offset:16384
	ds_read_b128 v[164:167], v230 offset:17408
	ds_read_b128 v[178:181], v230 offset:18432
	ds_read_b128 v[182:185], v230 offset:19456
	ds_read_b128 v[192:195], v230 offset:20480
	ds_read_b128 v[232:235], v230 offset:21504
	ds_read_b128 v[236:239], v230 offset:22528
	ds_read_b128 v[240:243], v230 offset:23552
	s_add_i32 s71, s71, s53
	s_mov_b32 m0, s71
	v_lshl_add_u64 v[186:187], s[10:11], 0, v[188:189]
	global_load_lds_dwordx4 v[186:187], off
	s_add_i32 m0, s71, 0x2000
	s_add_u32 s72, s10, 0x40000
	v_lshl_add_u64 v[244:245], s[10:11], 0, v[172:173]
	s_addc_u32 s73, s11, 0
	s_add_i32 s71, s74, s53
	global_load_lds_dwordx4 v[244:245], off
	v_lshl_add_u64 v[246:247], s[72:73], 0, v[188:189]
	s_mov_b32 m0, s71
	v_lshl_add_u64 v[248:249], s[44:45], 0, v[170:171]
	global_load_lds_dwordx4 v[246:247], off
	s_add_i32 m0, s71, 0x2000
	v_lshl_add_u64 v[246:247], s[72:73], 0, v[172:173]
	global_load_lds_dwordx4 v[246:247], off
	s_mov_b32 m0, s54
	v_lshl_add_u64 v[246:247], s[44:45], 0, v[168:169]
	global_load_lds_dwordx4 v[246:247], off
	s_mov_b32 m0, s55
	s_nop 0
	global_load_lds_dwordx4 v[248:249], off
	s_waitcnt vmcnt(8)
	s_waitcnt lgkmcnt(0)
	s_barrier
	s_waitcnt lgkmcnt(0)
	v_mfma_f32_16x16x32_bf16 v[92:95], v[128:131], v[160:163], v[92:95]
	v_mfma_f32_16x16x32_bf16 v[28:31], v[136:139], v[160:163], v[28:31]
	v_mfma_f32_16x16x32_bf16 v[88:91], v[128:131], v[178:181], v[88:91]
	v_mfma_f32_16x16x32_bf16 v[24:27], v[136:139], v[178:181], v[24:27]
	v_mfma_f32_16x16x32_bf16 v[76:79], v[128:131], v[192:195], v[76:79]
	v_mfma_f32_16x16x32_bf16 v[12:15], v[136:139], v[192:195], v[12:15]
	v_mfma_f32_16x16x32_bf16 v[68:71], v[128:131], v[236:239], v[68:71]
	v_mfma_f32_16x16x32_bf16 v[4:7], v[136:139], v[236:239], v[4:7]
	v_mfma_f32_16x16x32_bf16 v[92:95], v[132:135], v[164:167], v[92:95]
	v_mfma_f32_16x16x32_bf16 v[28:31], v[140:143], v[164:167], v[28:31]
	v_mfma_f32_16x16x32_bf16 v[88:91], v[132:135], v[182:185], v[88:91]
	v_mfma_f32_16x16x32_bf16 v[24:27], v[140:143], v[182:185], v[24:27]
	v_mfma_f32_16x16x32_bf16 v[76:79], v[132:135], v[232:235], v[76:79]
	v_mfma_f32_16x16x32_bf16 v[12:15], v[140:143], v[232:235], v[12:15]
	v_mfma_f32_16x16x32_bf16 v[68:71], v[132:135], v[240:243], v[68:71]
	v_mfma_f32_16x16x32_bf16 v[4:7], v[140:143], v[240:243], v[4:7]
	v_mfma_f32_16x16x32_bf16 v[84:87], v[144:147], v[160:163], v[84:87]
	v_mfma_f32_16x16x32_bf16 v[20:23], v[152:155], v[160:163], v[20:23]
	v_mfma_f32_16x16x32_bf16 v[80:83], v[144:147], v[178:181], v[80:83]
	v_mfma_f32_16x16x32_bf16 v[16:19], v[152:155], v[178:181], v[16:19]
	v_mfma_f32_16x16x32_bf16 v[72:75], v[144:147], v[192:195], v[72:75]
	v_mfma_f32_16x16x32_bf16 v[8:11], v[152:155], v[192:195], v[8:11]
	v_mfma_f32_16x16x32_bf16 v[64:67], v[144:147], v[236:239], v[64:67]
	v_mfma_f32_16x16x32_bf16 v[0:3], v[152:155], v[236:239], v[0:3]
	v_mfma_f32_16x16x32_bf16 v[84:87], v[148:151], v[164:167], v[84:87]
	v_mfma_f32_16x16x32_bf16 v[20:23], v[156:159], v[164:167], v[20:23]
	v_mfma_f32_16x16x32_bf16 v[80:83], v[148:151], v[182:185], v[80:83]
	v_mfma_f32_16x16x32_bf16 v[16:19], v[156:159], v[182:185], v[16:19]
	v_mfma_f32_16x16x32_bf16 v[72:75], v[148:151], v[232:235], v[72:75]
	v_mfma_f32_16x16x32_bf16 v[8:11], v[156:159], v[232:235], v[8:11]
	v_mfma_f32_16x16x32_bf16 v[64:67], v[148:151], v[240:243], v[64:67]
	v_mfma_f32_16x16x32_bf16 v[0:3], v[156:159], v[240:243], v[0:3]
	s_barrier
; #define PG8_STAGE(bufoff, gbase, voff) do { _Pragma("unroll") for (int _i = 0; _i < 2; ++_i) \
;         __builtin_amdgcn_global_load_lds((const unsigned*)((const char*)(gbase) + (voff)[_i]), (PG8_LAS unsigned*)(lds + (bufoff) + ldsw + _i * 8192), 16, 0, 0); } while (0)
; #define PG8_LDA(dst, b, h) do { _Pragma("unroll") for (int m = 0; m < 4; ++m) _Pragma("unroll") for (int k = 0; k < 2; ++k) dst[m][k] = *(const PG8_LAS bf16x8*)(lds + PG8_SA(b, h) + aoff + m * 2048 + k * 1024); } while (0)
; #define PG8_LDB(dst, b, h) do { _Pragma("unroll") for (int n = 0; n < 2; ++n) _Pragma("unroll") for (int k = 0; k < 2; ++k) dst[n][k] = *(const PG8_LAS bf16x8*)(lds + PG8_SB(b, h) + boff + n * 2048 + k * 1024); } while (0)
; #define PG8_MMA(ai, bj, At, Bt) do { __builtin_amdgcn_s_setprio(1); _Pragma("unroll") for (int m = 0; m < 4; ++m) _Pragma("unroll") for (int n = 0; n < 2; ++n) _Pragma("unroll") for (int k = 0; k < 2; ++k) \
;         acc[ai][bj][m][n] = __builtin_amdgcn_mfma_f32_16x16x32_bf16(Bt[n][k], At[m][k], acc[ai][bj][m][n], 0, 0, 0); __builtin_amdgcn_s_setprio(0); } while (0)
; #define PG8_WAIT_V(n) asm volatile("s_waitcnt vmcnt(" #n ")" ::: "memory")
; #define PG8_WAIT_L(n) asm volatile("s_waitcnt lgkmcnt(" #n ")" ::: "memory")
; #define PG8_BAR __builtin_amdgcn_s_barrier()
; #define PG8_SCHED __builtin_amdgcn_sched_barrier(0)
; template <class Epi, class Sched, bool ALIGN_EPI = false, bool SP2 = false>
; __device__ __forceinline__ void gemm_phase(PG8_LAS unsigned char* lds, const Gemm g, const Sched& S, const Epi& E) {
;     ...
;             PG8_LDB(B0, 1, 0); PG8_LDB(B1, 1, 1); PG8_SCHED; PG8_LDA(At, 1, 0); PG8_STAGE(PG8_SA(0, 1), a2 + hstepA, voffA);
;             PG8_WAIT_V(8); PG8_WAIT_L(0); PG8_BAR; PG8_MMA(0, 0, At, B0); PG8_MMA(0, 1, At, B1); PG8_BAR; PG8_SCHED;
	v_add_u32_e32 v140, 0x18000, v229
	v_add_u32_e32 v156, 0x1c000, v229
	ds_read_b128 v[128:131], v140
	ds_read_b128 v[132:135], v140 offset:1024
	ds_read_b128 v[136:139], v140 offset:2048
	ds_read_b128 v[140:143], v140 offset:3072
	ds_read_b128 v[144:147], v156
	ds_read_b128 v[148:151], v156 offset:1024
	ds_read_b128 v[152:155], v156 offset:2048
	ds_read_b128 v[156:159], v156 offset:3072
	ds_read_b128 v[160:163], v230 offset:32768
	ds_read_b128 v[164:167], v230 offset:33792
	ds_read_b128 v[178:181], v230 offset:34816
	ds_read_b128 v[182:185], v230 offset:35840
	ds_read_b128 v[192:195], v230 offset:36864
	ds_read_b128 v[232:235], v230 offset:37888
	ds_read_b128 v[236:239], v230 offset:38912
	ds_read_b128 v[240:243], v230 offset:39936
	s_add_i32 s71, 0, 0x18000
	s_add_i32 s72, 0, 0x1c000
	s_add_u32 s44, s44, 0x40000
	s_addc_u32 s45, s45, 0
	s_mov_b32 m0, s56
	v_lshl_add_u64 v[250:251], s[44:45], 0, v[168:169]
	global_load_lds_dwordx4 v[250:251], off
	s_mov_b32 m0, s57
	v_lshl_add_u64 v[250:251], s[44:45], 0, v[170:171]
	global_load_lds_dwordx4 v[250:251], off
	s_waitcnt vmcnt(8)
	s_waitcnt lgkmcnt(0)
	s_barrier
	s_waitcnt lgkmcnt(0)
	v_mfma_f32_16x16x32_bf16 v[124:127], v[128:131], v[160:163], v[124:127]
	v_mfma_f32_16x16x32_bf16 v[60:63], v[136:139], v[160:163], v[60:63]
	v_mfma_f32_16x16x32_bf16 v[120:123], v[128:131], v[178:181], v[120:123]
	v_mfma_f32_16x16x32_bf16 v[56:59], v[136:139], v[178:181], v[56:59]
	v_mfma_f32_16x16x32_bf16 v[108:111], v[128:131], v[192:195], v[108:111]
	v_mfma_f32_16x16x32_bf16 v[44:47], v[136:139], v[192:195], v[44:47]
	v_mfma_f32_16x16x32_bf16 v[100:103], v[128:131], v[236:239], v[100:103]
	v_mfma_f32_16x16x32_bf16 v[36:39], v[136:139], v[236:239], v[36:39]
	v_mfma_f32_16x16x32_bf16 v[124:127], v[132:135], v[164:167], v[124:127]
	v_mfma_f32_16x16x32_bf16 v[60:63], v[140:143], v[164:167], v[60:63]
	v_mfma_f32_16x16x32_bf16 v[120:123], v[132:135], v[182:185], v[120:123]
	v_mfma_f32_16x16x32_bf16 v[56:59], v[140:143], v[182:185], v[56:59]
	v_mfma_f32_16x16x32_bf16 v[108:111], v[132:135], v[232:235], v[108:111]
	v_mfma_f32_16x16x32_bf16 v[44:47], v[140:143], v[232:235], v[44:47]
	v_mfma_f32_16x16x32_bf16 v[100:103], v[132:135], v[240:243], v[100:103]
	v_mfma_f32_16x16x32_bf16 v[36:39], v[140:143], v[240:243], v[36:39]
	v_mfma_f32_16x16x32_bf16 v[116:119], v[144:147], v[160:163], v[116:119]
	v_mfma_f32_16x16x32_bf16 v[52:55], v[152:155], v[160:163], v[52:55]
	v_mfma_f32_16x16x32_bf16 v[112:115], v[144:147], v[178:181], v[112:115]
	v_mfma_f32_16x16x32_bf16 v[48:51], v[152:155], v[178:181], v[48:51]
	v_mfma_f32_16x16x32_bf16 v[104:107], v[144:147], v[192:195], v[104:107]
	v_mfma_f32_16x16x32_bf16 v[40:43], v[152:155], v[192:195], v[40:43]
	v_mfma_f32_16x16x32_bf16 v[96:99], v[144:147], v[236:239], v[96:99]
	v_mfma_f32_16x16x32_bf16 v[32:35], v[152:155], v[236:239], v[32:35]
	v_mfma_f32_16x16x32_bf16 v[116:119], v[148:151], v[164:167], v[116:119]
	v_mfma_f32_16x16x32_bf16 v[52:55], v[156:159], v[164:167], v[52:55]
	v_mfma_f32_16x16x32_bf16 v[112:115], v[148:151], v[182:185], v[112:115]
	v_mfma_f32_16x16x32_bf16 v[48:51], v[156:159], v[182:185], v[48:51]
	v_mfma_f32_16x16x32_bf16 v[104:107], v[148:151], v[232:235], v[104:107]
	v_mfma_f32_16x16x32_bf16 v[40:43], v[156:159], v[232:235], v[40:43]
	v_mfma_f32_16x16x32_bf16 v[96:99], v[148:151], v[240:243], v[96:99]
	v_mfma_f32_16x16x32_bf16 v[32:35], v[156:159], v[240:243], v[32:35]
	s_barrier
; #define PG8_STAGE(bufoff, gbase, voff) do { _Pragma("unroll") for (int _i = 0; _i < 2; ++_i) \
;         __builtin_amdgcn_global_load_lds((const unsigned*)((const char*)(gbase) + (voff)[_i]), (PG8_LAS unsigned*)(lds + (bufoff) + ldsw + _i * 8192), 16, 0, 0); } while (0)
; #define PG8_LDA(dst, b, h) do { _Pragma("unroll") for (int m = 0; m < 4; ++m) _Pragma("unroll") for (int k = 0; k < 2; ++k) dst[m][k] = *(const PG8_LAS bf16x8*)(lds + PG8_SA(b, h) + aoff + m * 2048 + k * 1024); } while (0)
; #define PG8_WAIT_V(n) asm volatile("s_waitcnt vmcnt(" #n ")" ::: "memory")
; template <class Epi, class Sched, bool ALIGN_EPI = false, bool SP2 = false>
; __device__ __forceinline__ void gemm_phase(PG8_LAS unsigned char* lds, const Gemm g, const Sched& S, const Epi& E) {
;     ...
;             PG8_LDA(At, 1, 1); PG8_STAGE(PG8_SB(1, 0), b3, voffB); PG8_STAGE(PG8_SB(1, 1), b3 + hstepB, voffB); PG8_STAGE(PG8_SA(1, 0), a3, voffA);
;             PG8_WAIT_V(8); PG8_WAIT_L(0); PG8_BAR; PG8_MMA(1, 0, At, B0); PG8_MMA(1, 1, At, B1); PG8_BAR; PG8_SCHED;
;             } else {
;             PG8_LDB(B0, 0, 0); PG8_SCHED; PG8_LDA(At, 0, 0); PG8_STAGE(PG8_SA(1, 1), a1 + hstepA, voffA);
;             PG8_WAIT_L(8); PG8_BAR; PG8_WAIT_L(0); PG8_MMA(0, 0, At, B0); PG8_BAR; PG8_SCHED;
;             PG8_LDB(B1, 0, 1); PG8_STAGE(PG8_SB(0, 0), b2, voffB);
;             PG8_BAR; PG8_WAIT_L(0); PG8_MMA(0, 1, At, B1); PG8_BAR;
;             PG8_LDA(At, 0, 1); PG8_STAGE(PG8_SA(0, 0), a2, voffA);
;             PG8_BAR; PG8_WAIT_L(0); PG8_MMA(1, 0, At, B0); PG8_BAR; PG8_SCHED;
;             PG8_STAGE(PG8_SB(0, 1), b2 + hstepB, voffB);
;             PG8_WAIT_V(6); PG8_BAR; PG8_MMA(1, 1, At, B1); PG8_BAR;
;             PG8_LDB(B0, 1, 0); PG8_SCHED; PG8_LDA(At, 1, 0); PG8_STAGE(PG8_SA(0, 1), a2 + hstepA, voffA);
;             PG8_WAIT_L(8); PG8_BAR; PG8_WAIT_L(0); PG8_MMA(0, 0, At, B0); PG8_BAR; PG8_SCHED;
;             PG8_LDB(B1, 1, 1); PG8_STAGE(PG8_SB(1, 0), b3, voffB);
;             PG8_BAR; PG8_WAIT_L(0); PG8_MMA(0, 1, At, B1); PG8_BAR;
;             PG8_LDA(At, 1, 1); PG8_STAGE(PG8_SA(1, 0), a3, voffA);
;             PG8_BAR; PG8_WAIT_L(0); PG8_MMA(1, 0, At, B0); PG8_BAR; PG8_SCHED;
;             PG8_STAGE(PG8_SB(1, 1), b3 + hstepB, voffB);
;             PG8_WAIT_V(6); PG8_BAR; PG8_MMA(1, 1, At, B1); PG8_BAR;
;             }
;         }
;         if constexpr (ALIGN_EPI) { if (wr == 0) PG8_BAR; }
	ds_read_b128 v[160:163], v230 offset:49152
	ds_read_b128 v[164:167], v230 offset:50176
	ds_read_b128 v[178:181], v230 offset:51200
	ds_read_b128 v[182:185], v230 offset:52224
	ds_read_b128 v[192:195], v230 offset:53248
	ds_read_b128 v[232:235], v230 offset:54272
	ds_read_b128 v[236:239], v230 offset:55296
	ds_read_b128 v[240:243], v230 offset:56320
	s_add_i32 s44, s71, s53
	s_mov_b32 m0, s44
	v_lshl_add_u64 v[186:187], v[186:187], 0, s[94:95]
	global_load_lds_dwordx4 v[186:187], off
	s_add_i32 m0, s44, 0x2000
	s_add_u32 s10, s10, 0x40080
	v_lshl_add_u64 v[186:187], v[244:245], 0, s[94:95]
	s_addc_u32 s11, s11, 0
	s_add_i32 s44, s72, s53
	global_load_lds_dwordx4 v[186:187], off
	s_mov_b32 m0, s44
	v_lshl_add_u64 v[186:187], s[10:11], 0, v[188:189]
	global_load_lds_dwordx4 v[186:187], off
	s_add_i32 m0, s44, 0x2000
	v_lshl_add_u64 v[186:187], s[10:11], 0, v[172:173]
	global_load_lds_dwordx4 v[186:187], off
	s_mov_b32 m0, s60
	v_lshl_add_u64 v[186:187], v[246:247], 0, s[94:95]
	global_load_lds_dwordx4 v[186:187], off
	s_mov_b32 m0, s61
	v_lshl_add_u64 v[186:187], v[248:249], 0, s[94:95]
	global_load_lds_dwordx4 v[186:187], off
	s_waitcnt vmcnt(8)
	s_waitcnt lgkmcnt(0)
	s_barrier
	s_waitcnt lgkmcnt(0)
	v_mfma_f32_16x16x32_bf16 v[92:95], v[128:131], v[160:163], v[92:95]
	v_mfma_f32_16x16x32_bf16 v[28:31], v[136:139], v[160:163], v[28:31]
	v_mfma_f32_16x16x32_bf16 v[88:91], v[128:131], v[178:181], v[88:91]
	v_mfma_f32_16x16x32_bf16 v[24:27], v[136:139], v[178:181], v[24:27]
	v_mfma_f32_16x16x32_bf16 v[76:79], v[128:131], v[192:195], v[76:79]
	v_mfma_f32_16x16x32_bf16 v[12:15], v[136:139], v[192:195], v[12:15]
	v_mfma_f32_16x16x32_bf16 v[68:71], v[128:131], v[236:239], v[68:71]
	v_mfma_f32_16x16x32_bf16 v[4:7], v[136:139], v[236:239], v[4:7]
	v_mfma_f32_16x16x32_bf16 v[92:95], v[132:135], v[164:167], v[92:95]
	v_mfma_f32_16x16x32_bf16 v[28:31], v[140:143], v[164:167], v[28:31]
	v_mfma_f32_16x16x32_bf16 v[88:91], v[132:135], v[182:185], v[88:91]
	v_mfma_f32_16x16x32_bf16 v[24:27], v[140:143], v[182:185], v[24:27]
	v_mfma_f32_16x16x32_bf16 v[76:79], v[132:135], v[232:235], v[76:79]
	v_mfma_f32_16x16x32_bf16 v[12:15], v[140:143], v[232:235], v[12:15]
	v_mfma_f32_16x16x32_bf16 v[68:71], v[132:135], v[240:243], v[68:71]
	v_mfma_f32_16x16x32_bf16 v[4:7], v[140:143], v[240:243], v[4:7]
	v_mfma_f32_16x16x32_bf16 v[84:87], v[144:147], v[160:163], v[84:87]
	v_mfma_f32_16x16x32_bf16 v[20:23], v[152:155], v[160:163], v[20:23]
	v_mfma_f32_16x16x32_bf16 v[80:83], v[144:147], v[178:181], v[80:83]
	v_mfma_f32_16x16x32_bf16 v[16:19], v[152:155], v[178:181], v[16:19]
	v_mfma_f32_16x16x32_bf16 v[72:75], v[144:147], v[192:195], v[72:75]
	v_mfma_f32_16x16x32_bf16 v[8:11], v[152:155], v[192:195], v[8:11]
	v_mfma_f32_16x16x32_bf16 v[64:67], v[144:147], v[236:239], v[64:67]
	v_mfma_f32_16x16x32_bf16 v[0:3], v[152:155], v[236:239], v[0:3]
	v_mfma_f32_16x16x32_bf16 v[84:87], v[148:151], v[164:167], v[84:87]
	v_mfma_f32_16x16x32_bf16 v[20:23], v[156:159], v[164:167], v[20:23]
	v_mfma_f32_16x16x32_bf16 v[80:83], v[148:151], v[182:185], v[80:83]
	v_mfma_f32_16x16x32_bf16 v[16:19], v[156:159], v[182:185], v[16:19]
	v_mfma_f32_16x16x32_bf16 v[72:75], v[148:151], v[232:235], v[72:75]
	v_mfma_f32_16x16x32_bf16 v[8:11], v[156:159], v[232:235], v[8:11]
	v_mfma_f32_16x16x32_bf16 v[64:67], v[148:151], v[240:243], v[64:67]
	v_mfma_f32_16x16x32_bf16 v[0:3], v[156:159], v[240:243], v[0:3]
	s_barrier
	s_add_i32 s70, s70, 2
	s_add_u32 s8, s8, 0x100
	s_addc_u32 s9, s9, 0
	s_add_u32 s46, s46, 0x100
	s_addc_u32 s47, s47, 0
	s_cmp_gt_u32 s70, 13
	s_cbranch_scc0 .LBB0_1800
	s_setprio 0
	s_and_b64 vcc, exec, s[26:27]
	s_cbranch_vccz .LBB0_1803
	s_barrier

; #define PG8_STAGE(bufoff, gbase, voff) do { _Pragma("unroll") for (int _i = 0; _i < 2; ++_i) \
;         __builtin_amdgcn_global_load_lds((const unsigned*)((const char*)(gbase) + (voff)[_i]), (PG8_LAS unsigned*)(lds + (bufoff) + ldsw + _i * 8192), 16, 0, 0); } while (0)
; #define PG8_LDA(dst, b, h) do { _Pragma("unroll") for (int m = 0; m < 4; ++m) _Pragma("unroll") for (int k = 0; k < 2; ++k) dst[m][k] = *(const PG8_LAS bf16x8*)(lds + PG8_SA(b, h) + aoff + m * 2048 + k * 1024); } while (0)
; #define PG8_LDB(dst, b, h) do { _Pragma("unroll") for (int n = 0; n < 2; ++n) _Pragma("unroll") for (int k = 0; k < 2; ++k) dst[n][k] = *(const PG8_LAS bf16x8*)(lds + PG8_SB(b, h) + boff + n * 2048 + k * 1024); } while (0)
; #define PG8_WAIT_V(n) asm volatile("s_waitcnt vmcnt(" #n ")" ::: "memory")
; #define PG8_WAIT_L(n) asm volatile("s_waitcnt lgkmcnt(" #n ")" ::: "memory")
; #define PG8_BAR __builtin_amdgcn_s_barrier()
; template <class Epi, class Sched, bool ALIGN_EPI = false, bool SP2 = false>
; __device__ __forceinline__ void gemm_phase(PG8_LAS unsigned char* lds, const Gemm g, const Sched& S, const Epi& E) {
;     ...
;         const bool has_next = S.next(ui + 1, nxt);
;         const char* nA = has_next ? (const char*)g.A + (size_t)nxt.pm * tstepA + (size_t)((nxt.pn / g.kdiv) * g.kmul) * 2 : cA; const char* nB = has_next ? (const char*)g.Bt + (size_t)nxt.pn * tstepB : cB;
; #pragma nounroll
;         for (int t = 0; t < nt; t += 2) {
;             const bool last = (t == nt - 2);
;             const char* a1 = cA + (size_t)(t + 1) * kstep;
;             const char* a2 = last ? nA : cA + (size_t)(t + 2) * kstep; const char* b2 = last ? nB : cB + (size_t)(t + 2) * kstep;
;             const char* a3 = a2 + kstep; const char* b3 = b2 + kstep;
;             if (last && has_next) S.a_ready(nxt);
;             if constexpr (SP2) {
;             PG8_LDB(B0, 0, 0); PG8_LDB(B1, 0, 1); PG8_SCHED; PG8_LDA(At, 0, 0); PG8_STAGE(PG8_SA(1, 1), a1 + hstepA, voffA);
;             PG8_WAIT_V(8); PG8_WAIT_L(0); PG8_BAR; PG8_MMA(0, 0, At, B0); PG8_MMA(0, 1, At, B1); PG8_BAR; PG8_SCHED;
;     ...
; #pragma unroll
;         for (int a = 0; a < 2; ++a)
; #pragma unroll
;             for (int b = 0; b < 2; ++b)
; #pragma unroll
;                 for (int m = 0; m < 4; ++m)
; #pragma unroll
;                     for (int n = 0; n < 2; ++n) acc[a][b][m][n] = (f32x4){0.f, 0.f, 0.f, 0.f};
.LBB0_1992:
	s_add_u32 s65, s24, 0x100
	v_mov_b32_e32 v0, 0
	s_addc_u32 s66, s25, 0
	s_mov_b32 s67, -2
	v_mov_b32_e32 v1, v0
	v_mov_b32_e32 v2, v0
	v_mov_b32_e32 v3, v0
	v_mov_b32_e32 v28, v0
	v_mov_b32_e32 v29, v0
	v_mov_b32_e32 v30, v0
	v_mov_b32_e32 v31, v0
	v_mov_b32_e32 v4, v0
	v_mov_b32_e32 v5, v0
	v_mov_b32_e32 v6, v0
	v_mov_b32_e32 v7, v0
	v_mov_b32_e32 v32, v0
	v_mov_b32_e32 v33, v0
	v_mov_b32_e32 v34, v0
	v_mov_b32_e32 v35, v0
	v_mov_b32_e32 v8, v0
	v_mov_b32_e32 v9, v0
	v_mov_b32_e32 v10, v0
	v_mov_b32_e32 v11, v0
	v_mov_b32_e32 v40, v0
	v_mov_b32_e32 v41, v0
	v_mov_b32_e32 v42, v0
	v_mov_b32_e32 v43, v0
	v_mov_b32_e32 v12, v0
	v_mov_b32_e32 v13, v0
	v_mov_b32_e32 v14, v0
	v_mov_b32_e32 v15, v0
	v_mov_b32_e32 v44, v0
	v_mov_b32_e32 v45, v0
	v_mov_b32_e32 v46, v0
	v_mov_b32_e32 v47, v0
	v_mov_b32_e32 v60, v0
	v_mov_b32_e32 v61, v0
	v_mov_b32_e32 v62, v0
	v_mov_b32_e32 v63, v0
	v_mov_b32_e32 v88, v0
	v_mov_b32_e32 v89, v0
	v_mov_b32_e32 v90, v0
	v_mov_b32_e32 v91, v0
	v_mov_b32_e32 v68, v0
	v_mov_b32_e32 v69, v0
	v_mov_b32_e32 v70, v0
	v_mov_b32_e32 v71, v0
	v_mov_b32_e32 v100, v0
	v_mov_b32_e32 v101, v0
	v_mov_b32_e32 v102, v0
	v_mov_b32_e32 v103, v0
	v_mov_b32_e32 v72, v0
	v_mov_b32_e32 v73, v0
	v_mov_b32_e32 v74, v0
	v_mov_b32_e32 v75, v0
	v_mov_b32_e32 v104, v0
	v_mov_b32_e32 v105, v0
	v_mov_b32_e32 v106, v0
	v_mov_b32_e32 v107, v0
	v_mov_b32_e32 v76, v0
	v_mov_b32_e32 v77, v0
	v_mov_b32_e32 v78, v0
	v_mov_b32_e32 v79, v0
	v_mov_b32_e32 v108, v0
	v_mov_b32_e32 v109, v0
	v_mov_b32_e32 v110, v0
	v_mov_b32_e32 v111, v0
	v_mov_b32_e32 v16, v0
	v_mov_b32_e32 v17, v0
	v_mov_b32_e32 v18, v0
	v_mov_b32_e32 v19, v0
	v_mov_b32_e32 v48, v0
	v_mov_b32_e32 v49, v0
	v_mov_b32_e32 v50, v0
	v_mov_b32_e32 v51, v0
	v_mov_b32_e32 v20, v0
	v_mov_b32_e32 v21, v0
	v_mov_b32_e32 v22, v0
	v_mov_b32_e32 v23, v0
	v_mov_b32_e32 v52, v0
	v_mov_b32_e32 v53, v0
	v_mov_b32_e32 v54, v0
	v_mov_b32_e32 v55, v0
	v_mov_b32_e32 v24, v0
	v_mov_b32_e32 v25, v0
	v_mov_b32_e32 v26, v0
	v_mov_b32_e32 v27, v0
	v_mov_b32_e32 v56, v0
	v_mov_b32_e32 v57, v0
	v_mov_b32_e32 v58, v0
	v_mov_b32_e32 v59, v0
	v_mov_b32_e32 v36, v0
	v_mov_b32_e32 v37, v0
	v_mov_b32_e32 v38, v0
	v_mov_b32_e32 v39, v0
	v_mov_b32_e32 v64, v0
	v_mov_b32_e32 v65, v0
	v_mov_b32_e32 v66, v0
	v_mov_b32_e32 v67, v0
	v_mov_b32_e32 v80, v0
	v_mov_b32_e32 v81, v0
	v_mov_b32_e32 v82, v0
	v_mov_b32_e32 v83, v0
	v_mov_b32_e32 v112, v0
	v_mov_b32_e32 v113, v0
	v_mov_b32_e32 v114, v0
	v_mov_b32_e32 v115, v0
	v_mov_b32_e32 v84, v0
	v_mov_b32_e32 v85, v0
	v_mov_b32_e32 v86, v0
	v_mov_b32_e32 v87, v0
	v_mov_b32_e32 v116, v0
	v_mov_b32_e32 v117, v0
	v_mov_b32_e32 v118, v0
	v_mov_b32_e32 v119, v0
	v_mov_b32_e32 v92, v0
	v_mov_b32_e32 v93, v0
	v_mov_b32_e32 v94, v0
	v_mov_b32_e32 v95, v0
	v_mov_b32_e32 v120, v0
	v_mov_b32_e32 v121, v0
	v_mov_b32_e32 v122, v0
	v_mov_b32_e32 v123, v0
	v_mov_b32_e32 v96, v0
	v_mov_b32_e32 v97, v0
	v_mov_b32_e32 v98, v0
	v_mov_b32_e32 v99, v0
	v_mov_b32_e32 v124, v0
	v_mov_b32_e32 v125, v0
	v_mov_b32_e32 v126, v0
	v_mov_b32_e32 v127, v0
	v_readfirstlane_b32 s100, v198
	s_nop 3
	s_bitcmp1_b32 s100, 8
	s_cbranch_scc0 .Lgprio_5_skip
	s_setprio 1
.Lgprio_5_skip:
.LBB0_1993:
	v_add_u32_e32 v150, 0x10000, v140
	v_add_u32_e32 v166, 0x14000, v140
	ds_read_b128 v[134:137], v150
	ds_read_b128 v[142:145], v150 offset:1024
	ds_read_b128 v[146:149], v150 offset:2048
	ds_read_b128 v[150:153], v150 offset:3072
	ds_read_b128 v[154:157], v166
	ds_read_b128 v[158:161], v166 offset:1024
	ds_read_b128 v[162:165], v166 offset:2048
	ds_read_b128 v[166:169], v166 offset:3072
	ds_read_b128 v[170:173], v141
	ds_read_b128 v[174:177], v141 offset:1024
	ds_read_b128 v[178:181], v141 offset:2048
	ds_read_b128 v[182:185], v141 offset:3072
	ds_read_b128 v[192:195], v141 offset:4096
	ds_read_b128 v[230:233], v141 offset:5120
	ds_read_b128 v[234:237], v141 offset:6144
	ds_read_b128 v[238:241], v141 offset:7168
	s_add_u32 s24, s22, 0x100
	s_addc_u32 s25, s23, 0
	s_add_i32 s68, 0, 0x10000
	s_cmp_eq_u32 s67, 40
	s_cselect_b32 s29, s9, s25
	s_cselect_b32 s28, s8, s24
	s_cselect_b32 s27, s21, s66
	s_cselect_b32 s26, s20, s65
	s_add_i32 s69, 0, 0x14000
	s_add_i32 m0, s36, 0xc000
	v_lshl_add_u64 v[186:187], s[22:23], 0, v[130:131]
	global_load_lds_dwordx4 v[186:187], off
	s_add_i32 m0, s36, 0xe000
	v_lshl_add_u64 v[186:187], s[22:23], 0, v[132:133]
	global_load_lds_dwordx4 v[186:187], off
	s_waitcnt vmcnt(8)
	s_waitcnt lgkmcnt(0)
	s_barrier
	s_waitcnt lgkmcnt(0)
	v_mfma_f32_16x16x32_bf16 v[124:127], v[134:137], v[170:173], v[124:127]
	v_mfma_f32_16x16x32_bf16 v[96:99], v[146:149], v[170:173], v[96:99]
	v_mfma_f32_16x16x32_bf16 v[120:123], v[134:137], v[178:181], v[120:123]
	v_mfma_f32_16x16x32_bf16 v[92:95], v[146:149], v[178:181], v[92:95]
	v_mfma_f32_16x16x32_bf16 v[116:119], v[134:137], v[192:195], v[116:119]
	v_mfma_f32_16x16x32_bf16 v[84:87], v[146:149], v[192:195], v[84:87]
	v_mfma_f32_16x16x32_bf16 v[112:115], v[134:137], v[234:237], v[112:115]
	v_mfma_f32_16x16x32_bf16 v[80:83], v[146:149], v[234:237], v[80:83]
	v_mfma_f32_16x16x32_bf16 v[124:127], v[142:145], v[174:177], v[124:127]
	v_mfma_f32_16x16x32_bf16 v[96:99], v[150:153], v[174:177], v[96:99]
	v_mfma_f32_16x16x32_bf16 v[120:123], v[142:145], v[182:185], v[120:123]
	v_mfma_f32_16x16x32_bf16 v[92:95], v[150:153], v[182:185], v[92:95]
	v_mfma_f32_16x16x32_bf16 v[116:119], v[142:145], v[230:233], v[116:119]
	v_mfma_f32_16x16x32_bf16 v[84:87], v[150:153], v[230:233], v[84:87]
	v_mfma_f32_16x16x32_bf16 v[112:115], v[142:145], v[238:241], v[112:115]
	v_mfma_f32_16x16x32_bf16 v[80:83], v[150:153], v[238:241], v[80:83]
	v_mfma_f32_16x16x32_bf16 v[64:67], v[154:157], v[170:173], v[64:67]
	v_mfma_f32_16x16x32_bf16 v[36:39], v[162:165], v[170:173], v[36:39]
	v_mfma_f32_16x16x32_bf16 v[56:59], v[154:157], v[178:181], v[56:59]
	v_mfma_f32_16x16x32_bf16 v[24:27], v[162:165], v[178:181], v[24:27]
	v_mfma_f32_16x16x32_bf16 v[52:55], v[154:157], v[192:195], v[52:55]
	v_mfma_f32_16x16x32_bf16 v[20:23], v[162:165], v[192:195], v[20:23]
	v_mfma_f32_16x16x32_bf16 v[48:51], v[154:157], v[234:237], v[48:51]
	v_mfma_f32_16x16x32_bf16 v[16:19], v[162:165], v[234:237], v[16:19]
	v_mfma_f32_16x16x32_bf16 v[64:67], v[158:161], v[174:177], v[64:67]
	v_mfma_f32_16x16x32_bf16 v[36:39], v[166:169], v[174:177], v[36:39]
	v_mfma_f32_16x16x32_bf16 v[56:59], v[158:161], v[182:185], v[56:59]
	v_mfma_f32_16x16x32_bf16 v[24:27], v[166:169], v[182:185], v[24:27]
	v_mfma_f32_16x16x32_bf16 v[52:55], v[158:161], v[230:233], v[52:55]
	v_mfma_f32_16x16x32_bf16 v[20:23], v[166:169], v[230:233], v[20:23]
	v_mfma_f32_16x16x32_bf16 v[48:51], v[158:161], v[238:241], v[48:51]
	v_mfma_f32_16x16x32_bf16 v[16:19], v[166:169], v[238:241], v[16:19]
	s_barrier
; #define PG8_STAGE(bufoff, gbase, voff) do { _Pragma("unroll") for (int _i = 0; _i < 2; ++_i) \
;         __builtin_amdgcn_global_load_lds((const unsigned*)((const char*)(gbase) + (voff)[_i]), (PG8_LAS unsigned*)(lds + (bufoff) + ldsw + _i * 8192), 16, 0, 0); } while (0)
; #define PG8_LDA(dst, b, h) do { _Pragma("unroll") for (int m = 0; m < 4; ++m) _Pragma("unroll") for (int k = 0; k < 2; ++k) dst[m][k] = *(const PG8_LAS bf16x8*)(lds + PG8_SA(b, h) + aoff + m * 2048 + k * 1024); } while (0)
; #define PG8_LDB(dst, b, h) do { _Pragma("unroll") for (int n = 0; n < 2; ++n) _Pragma("unroll") for (int k = 0; k < 2; ++k) dst[n][k] = *(const PG8_LAS bf16x8*)(lds + PG8_SB(b, h) + boff + n * 2048 + k * 1024); } while (0)
; #define PG8_MMA(ai, bj, At, Bt) do { __builtin_amdgcn_s_setprio(1); _Pragma("unroll") for (int m = 0; m < 4; ++m) _Pragma("unroll") for (int n = 0; n < 2; ++n) _Pragma("unroll") for (int k = 0; k < 2; ++k) \
;         acc[ai][bj][m][n] = __builtin_amdgcn_mfma_f32_16x16x32_bf16(Bt[n][k], At[m][k], acc[ai][bj][m][n], 0, 0, 0); __builtin_amdgcn_s_setprio(0); } while (0)
; #define PG8_WAIT_V(n) asm volatile("s_waitcnt vmcnt(" #n ")" ::: "memory")
; #define PG8_WAIT_L(n) asm volatile("s_waitcnt lgkmcnt(" #n ")" ::: "memory")
; #define PG8_BAR __builtin_amdgcn_s_barrier()
; #define PG8_SCHED __builtin_amdgcn_sched_barrier(0)
; template <class Epi, class Sched, bool ALIGN_EPI = false, bool SP2 = false>
; __device__ __forceinline__ void gemm_phase(PG8_LAS unsigned char* lds, const Gemm g, const Sched& S, const Epi& E) {
;     ...
;             PG8_WAIT_V(8); PG8_WAIT_L(0); PG8_BAR; PG8_MMA(0, 0, At, B0); PG8_MMA(0, 1, At, B1); PG8_BAR; PG8_SCHED;
;             PG8_LDA(At, 0, 1); PG8_STAGE(PG8_SB(0, 0), b2, voffB); PG8_STAGE(PG8_SB(0, 1), b2 + hstepB, voffB); PG8_STAGE(PG8_SA(0, 0), a2, voffA);
;             PG8_WAIT_V(8); PG8_WAIT_L(0); PG8_BAR; PG8_MMA(1, 0, At, B0); PG8_MMA(1, 1, At, B1); PG8_BAR; PG8_SCHED;
;             PG8_LDB(B0, 1, 0); PG8_LDB(B1, 1, 1); PG8_SCHED; PG8_LDA(At, 1, 0); PG8_STAGE(PG8_SA(0, 1), a2 + hstepA, voffA);
;             PG8_WAIT_V(8); PG8_WAIT_L(0); PG8_BAR; PG8_MMA(0, 0, At, B0); PG8_MMA(0, 1, At, B1); PG8_BAR; PG8_SCHED;
	ds_read_b128 v[170:173], v141 offset:16384
	ds_read_b128 v[174:177], v141 offset:17408
	ds_read_b128 v[178:181], v141 offset:18432
	ds_read_b128 v[182:185], v141 offset:19456
	ds_read_b128 v[192:195], v141 offset:20480
	ds_read_b128 v[230:233], v141 offset:21504
	ds_read_b128 v[234:237], v141 offset:22528
	ds_read_b128 v[238:241], v141 offset:23552
	s_add_i32 s22, s68, s35
	s_mov_b32 m0, s22
	v_lshl_add_u64 v[186:187], s[26:27], 0, v[188:189]
	global_load_lds_dwordx4 v[186:187], off
	s_add_i32 m0, s22, 0x2000
	s_add_u32 s22, s26, 0xb0000
	v_lshl_add_u64 v[196:197], s[26:27], 0, v[128:129]
	s_addc_u32 s23, s27, 0
	s_add_i32 s68, s69, s35
	global_load_lds_dwordx4 v[196:197], off
	v_lshl_add_u64 v[242:243], s[22:23], 0, v[188:189]
	s_mov_b32 m0, s68
	v_lshl_add_u64 v[244:245], s[28:29], 0, v[128:129]
	global_load_lds_dwordx4 v[242:243], off
	s_add_i32 m0, s68, 0x2000
	v_lshl_add_u64 v[242:243], s[22:23], 0, v[128:129]
	global_load_lds_dwordx4 v[242:243], off
	s_mov_b32 m0, s36
	v_lshl_add_u64 v[242:243], s[28:29], 0, v[188:189]
	global_load_lds_dwordx4 v[242:243], off
	s_mov_b32 m0, s37
	s_nop 0
	global_load_lds_dwordx4 v[244:245], off
	s_waitcnt vmcnt(8)
	s_waitcnt lgkmcnt(0)
	s_barrier
	s_waitcnt lgkmcnt(0)
	v_mfma_f32_16x16x32_bf16 v[108:111], v[134:137], v[170:173], v[108:111]
	v_mfma_f32_16x16x32_bf16 v[76:79], v[146:149], v[170:173], v[76:79]
	v_mfma_f32_16x16x32_bf16 v[104:107], v[134:137], v[178:181], v[104:107]
	v_mfma_f32_16x16x32_bf16 v[72:75], v[146:149], v[178:181], v[72:75]
	v_mfma_f32_16x16x32_bf16 v[100:103], v[134:137], v[192:195], v[100:103]
	v_mfma_f32_16x16x32_bf16 v[68:71], v[146:149], v[192:195], v[68:71]
	v_mfma_f32_16x16x32_bf16 v[88:91], v[134:137], v[234:237], v[88:91]
	v_mfma_f32_16x16x32_bf16 v[60:63], v[146:149], v[234:237], v[60:63]
	v_mfma_f32_16x16x32_bf16 v[108:111], v[142:145], v[174:177], v[108:111]
	v_mfma_f32_16x16x32_bf16 v[76:79], v[150:153], v[174:177], v[76:79]
	v_mfma_f32_16x16x32_bf16 v[104:107], v[142:145], v[182:185], v[104:107]
	v_mfma_f32_16x16x32_bf16 v[72:75], v[150:153], v[182:185], v[72:75]
	v_mfma_f32_16x16x32_bf16 v[100:103], v[142:145], v[230:233], v[100:103]
	v_mfma_f32_16x16x32_bf16 v[68:71], v[150:153], v[230:233], v[68:71]
	v_mfma_f32_16x16x32_bf16 v[88:91], v[142:145], v[238:241], v[88:91]
	v_mfma_f32_16x16x32_bf16 v[60:63], v[150:153], v[238:241], v[60:63]
	v_mfma_f32_16x16x32_bf16 v[44:47], v[154:157], v[170:173], v[44:47]
	v_mfma_f32_16x16x32_bf16 v[12:15], v[162:165], v[170:173], v[12:15]
	v_mfma_f32_16x16x32_bf16 v[40:43], v[154:157], v[178:181], v[40:43]
	v_mfma_f32_16x16x32_bf16 v[8:11], v[162:165], v[178:181], v[8:11]
	v_mfma_f32_16x16x32_bf16 v[32:35], v[154:157], v[192:195], v[32:35]
	v_mfma_f32_16x16x32_bf16 v[4:7], v[162:165], v[192:195], v[4:7]
	v_mfma_f32_16x16x32_bf16 v[28:31], v[154:157], v[234:237], v[28:31]
	v_mfma_f32_16x16x32_bf16 v[0:3], v[162:165], v[234:237], v[0:3]
	v_mfma_f32_16x16x32_bf16 v[44:47], v[158:161], v[174:177], v[44:47]
	v_mfma_f32_16x16x32_bf16 v[12:15], v[166:169], v[174:177], v[12:15]
	v_mfma_f32_16x16x32_bf16 v[40:43], v[158:161], v[182:185], v[40:43]
	v_mfma_f32_16x16x32_bf16 v[8:11], v[166:169], v[182:185], v[8:11]
	v_mfma_f32_16x16x32_bf16 v[32:35], v[158:161], v[230:233], v[32:35]
	v_mfma_f32_16x16x32_bf16 v[4:7], v[166:169], v[230:233], v[4:7]
	v_mfma_f32_16x16x32_bf16 v[28:31], v[158:161], v[238:241], v[28:31]
	v_mfma_f32_16x16x32_bf16 v[0:3], v[166:169], v[238:241], v[0:3]
	s_barrier
	v_add_u32_e32 v150, 0x18000, v140
	v_add_u32_e32 v166, 0x1c000, v140
	ds_read_b128 v[134:137], v150
	ds_read_b128 v[142:145], v150 offset:1024
	ds_read_b128 v[146:149], v150 offset:2048
	ds_read_b128 v[150:153], v150 offset:3072
	ds_read_b128 v[154:157], v166
	ds_read_b128 v[158:161], v166 offset:1024
	ds_read_b128 v[162:165], v166 offset:2048
	ds_read_b128 v[166:169], v166 offset:3072
	ds_read_b128 v[170:173], v141 offset:32768
	ds_read_b128 v[174:177], v141 offset:33792
	ds_read_b128 v[178:181], v141 offset:34816
	ds_read_b128 v[182:185], v141 offset:35840
	ds_read_b128 v[192:195], v141 offset:36864
	ds_read_b128 v[230:233], v141 offset:37888
	ds_read_b128 v[234:237], v141 offset:38912
	ds_read_b128 v[238:241], v141 offset:39936
	s_add_i32 s68, 0, 0x18000
	s_add_i32 s69, 0, 0x1c000
	s_add_u32 s22, s28, 0xb0000
	s_addc_u32 s23, s29, 0
	s_mov_b32 m0, s44
	v_lshl_add_u64 v[246:247], s[22:23], 0, v[188:189]
	global_load_lds_dwordx4 v[246:247], off
	s_mov_b32 m0, s45
	v_lshl_add_u64 v[246:247], s[22:23], 0, v[128:129]
	global_load_lds_dwordx4 v[246:247], off
	s_waitcnt vmcnt(8)
	s_waitcnt lgkmcnt(0)
	s_barrier
; #define PG8_STAGE(bufoff, gbase, voff) do { _Pragma("unroll") for (int _i = 0; _i < 2; ++_i) \
;         __builtin_amdgcn_global_load_lds((const unsigned*)((const char*)(gbase) + (voff)[_i]), (PG8_LAS unsigned*)(lds + (bufoff) + ldsw + _i * 8192), 16, 0, 0); } while (0)
; #define PG8_WAIT_V(n) asm volatile("s_waitcnt vmcnt(" #n ")" ::: "memory")
; #define PG8_WAIT_L(n) asm volatile("s_waitcnt lgkmcnt(" #n ")" ::: "memory")
; template <class Epi, class Sched, bool ALIGN_EPI = false, bool SP2 = false>
; __device__ __forceinline__ void gemm_phase(PG8_LAS unsigned char* lds, const Gemm g, const Sched& S, const Epi& E) {
;     ...
;             PG8_WAIT_V(8); PG8_WAIT_L(0); PG8_BAR; PG8_MMA(0, 0, At, B0); PG8_MMA(0, 1, At, B1); PG8_BAR; PG8_SCHED;
;             PG8_LDA(At, 1, 1); PG8_STAGE(PG8_SB(1, 0), b3, voffB); PG8_STAGE(PG8_SB(1, 1), b3 + hstepB, voffB); PG8_STAGE(PG8_SA(1, 0), a3, voffA);
;             PG8_WAIT_V(8); PG8_WAIT_L(0); PG8_BAR; PG8_MMA(1, 0, At, B0); PG8_MMA(1, 1, At, B1); PG8_BAR; PG8_SCHED;
;             } else {
;             PG8_LDB(B0, 0, 0); PG8_SCHED; PG8_LDA(At, 0, 0); PG8_STAGE(PG8_SA(1, 1), a1 + hstepA, voffA);
;             PG8_WAIT_L(8); PG8_BAR; PG8_WAIT_L(0); PG8_MMA(0, 0, At, B0); PG8_BAR; PG8_SCHED;
;             PG8_LDB(B1, 0, 1); PG8_STAGE(PG8_SB(0, 0), b2, voffB);
;             PG8_BAR; PG8_WAIT_L(0); PG8_MMA(0, 1, At, B1); PG8_BAR;
;             PG8_LDA(At, 0, 1); PG8_STAGE(PG8_SA(0, 0), a2, voffA);
;             PG8_BAR; PG8_WAIT_L(0); PG8_MMA(1, 0, At, B0); PG8_BAR; PG8_SCHED;
;             PG8_STAGE(PG8_SB(0, 1), b2 + hstepB, voffB);
;             PG8_WAIT_V(6); PG8_BAR; PG8_MMA(1, 1, At, B1); PG8_BAR;
;             PG8_LDB(B0, 1, 0); PG8_SCHED; PG8_LDA(At, 1, 0); PG8_STAGE(PG8_SA(0, 1), a2 + hstepA, voffA);
;             PG8_WAIT_L(8); PG8_BAR; PG8_WAIT_L(0); PG8_MMA(0, 0, At, B0); PG8_BAR; PG8_SCHED;
;             PG8_LDB(B1, 1, 1); PG8_STAGE(PG8_SB(1, 0), b3, voffB);
;             PG8_BAR; PG8_WAIT_L(0); PG8_MMA(0, 1, At, B1); PG8_BAR;
;             PG8_LDA(At, 1, 1); PG8_STAGE(PG8_SA(1, 0), a3, voffA);
;             PG8_BAR; PG8_WAIT_L(0); PG8_MMA(1, 0, At, B0); PG8_BAR; PG8_SCHED;
;             PG8_STAGE(PG8_SB(1, 1), b3 + hstepB, voffB);
;             PG8_WAIT_V(6); PG8_BAR; PG8_MMA(1, 1, At, B1); PG8_BAR;
;             }
;         }
;         if constexpr (ALIGN_EPI) { if (wr == 0) PG8_BAR; }
	s_waitcnt lgkmcnt(0)
	v_mfma_f32_16x16x32_bf16 v[124:127], v[134:137], v[170:173], v[124:127]
	v_mfma_f32_16x16x32_bf16 v[96:99], v[146:149], v[170:173], v[96:99]
	v_mfma_f32_16x16x32_bf16 v[120:123], v[134:137], v[178:181], v[120:123]
	v_mfma_f32_16x16x32_bf16 v[92:95], v[146:149], v[178:181], v[92:95]
	v_mfma_f32_16x16x32_bf16 v[116:119], v[134:137], v[192:195], v[116:119]
	v_mfma_f32_16x16x32_bf16 v[84:87], v[146:149], v[192:195], v[84:87]
	v_mfma_f32_16x16x32_bf16 v[112:115], v[134:137], v[234:237], v[112:115]
	v_mfma_f32_16x16x32_bf16 v[80:83], v[146:149], v[234:237], v[80:83]
	v_mfma_f32_16x16x32_bf16 v[124:127], v[142:145], v[174:177], v[124:127]
	v_mfma_f32_16x16x32_bf16 v[96:99], v[150:153], v[174:177], v[96:99]
	v_mfma_f32_16x16x32_bf16 v[120:123], v[142:145], v[182:185], v[120:123]
	v_mfma_f32_16x16x32_bf16 v[92:95], v[150:153], v[182:185], v[92:95]
	v_mfma_f32_16x16x32_bf16 v[116:119], v[142:145], v[230:233], v[116:119]
	v_mfma_f32_16x16x32_bf16 v[84:87], v[150:153], v[230:233], v[84:87]
	v_mfma_f32_16x16x32_bf16 v[112:115], v[142:145], v[238:241], v[112:115]
	v_mfma_f32_16x16x32_bf16 v[80:83], v[150:153], v[238:241], v[80:83]
	v_mfma_f32_16x16x32_bf16 v[64:67], v[154:157], v[170:173], v[64:67]
	v_mfma_f32_16x16x32_bf16 v[36:39], v[162:165], v[170:173], v[36:39]
	v_mfma_f32_16x16x32_bf16 v[56:59], v[154:157], v[178:181], v[56:59]
	v_mfma_f32_16x16x32_bf16 v[24:27], v[162:165], v[178:181], v[24:27]
	v_mfma_f32_16x16x32_bf16 v[52:55], v[154:157], v[192:195], v[52:55]
	v_mfma_f32_16x16x32_bf16 v[20:23], v[162:165], v[192:195], v[20:23]
	v_mfma_f32_16x16x32_bf16 v[48:51], v[154:157], v[234:237], v[48:51]
	v_mfma_f32_16x16x32_bf16 v[16:19], v[162:165], v[234:237], v[16:19]
	v_mfma_f32_16x16x32_bf16 v[64:67], v[158:161], v[174:177], v[64:67]
	v_mfma_f32_16x16x32_bf16 v[36:39], v[166:169], v[174:177], v[36:39]
	v_mfma_f32_16x16x32_bf16 v[56:59], v[158:161], v[182:185], v[56:59]
	v_mfma_f32_16x16x32_bf16 v[24:27], v[166:169], v[182:185], v[24:27]
	v_mfma_f32_16x16x32_bf16 v[52:55], v[158:161], v[230:233], v[52:55]
	v_mfma_f32_16x16x32_bf16 v[20:23], v[166:169], v[230:233], v[20:23]
	v_mfma_f32_16x16x32_bf16 v[48:51], v[158:161], v[238:241], v[48:51]
	v_mfma_f32_16x16x32_bf16 v[16:19], v[166:169], v[238:241], v[16:19]
	s_barrier
	ds_read_b128 v[170:173], v141 offset:49152
	ds_read_b128 v[174:177], v141 offset:50176
	ds_read_b128 v[178:181], v141 offset:51200
	ds_read_b128 v[182:185], v141 offset:52224
	ds_read_b128 v[192:195], v141 offset:53248
	ds_read_b128 v[230:233], v141 offset:54272
	ds_read_b128 v[234:237], v141 offset:55296
	ds_read_b128 v[238:241], v141 offset:56320
	s_add_i32 s22, s68, s35
	s_mov_b32 m0, s22
	v_lshl_add_u64 v[186:187], v[186:187], 0, s[94:95]
	global_load_lds_dwordx4 v[186:187], off
	s_add_i32 m0, s22, 0x2000
	s_add_u32 s22, s26, 0xb0080
	v_lshl_add_u64 v[186:187], v[196:197], 0, s[94:95]
	s_addc_u32 s23, s27, 0
	s_add_i32 s26, s69, s35
	global_load_lds_dwordx4 v[186:187], off
	s_mov_b32 m0, s26
	v_lshl_add_u64 v[186:187], s[22:23], 0, v[188:189]
	global_load_lds_dwordx4 v[186:187], off
	s_add_i32 m0, s26, 0x2000
	v_lshl_add_u64 v[186:187], s[22:23], 0, v[128:129]
	global_load_lds_dwordx4 v[186:187], off
	s_mov_b32 m0, s57
	v_lshl_add_u64 v[186:187], v[242:243], 0, s[94:95]
	global_load_lds_dwordx4 v[186:187], off
	s_mov_b32 m0, s58
	v_lshl_add_u64 v[186:187], v[244:245], 0, s[94:95]
	global_load_lds_dwordx4 v[186:187], off
	s_waitcnt vmcnt(8)
	s_waitcnt lgkmcnt(0)
	s_barrier
	s_waitcnt lgkmcnt(0)
	v_mfma_f32_16x16x32_bf16 v[108:111], v[134:137], v[170:173], v[108:111]
	v_mfma_f32_16x16x32_bf16 v[76:79], v[146:149], v[170:173], v[76:79]
	v_mfma_f32_16x16x32_bf16 v[104:107], v[134:137], v[178:181], v[104:107]
	v_mfma_f32_16x16x32_bf16 v[72:75], v[146:149], v[178:181], v[72:75]
	v_mfma_f32_16x16x32_bf16 v[100:103], v[134:137], v[192:195], v[100:103]
	v_mfma_f32_16x16x32_bf16 v[68:71], v[146:149], v[192:195], v[68:71]
	v_mfma_f32_16x16x32_bf16 v[88:91], v[134:137], v[234:237], v[88:91]
	v_mfma_f32_16x16x32_bf16 v[60:63], v[146:149], v[234:237], v[60:63]
	v_mfma_f32_16x16x32_bf16 v[108:111], v[142:145], v[174:177], v[108:111]
	v_mfma_f32_16x16x32_bf16 v[76:79], v[150:153], v[174:177], v[76:79]
	v_mfma_f32_16x16x32_bf16 v[104:107], v[142:145], v[182:185], v[104:107]
	v_mfma_f32_16x16x32_bf16 v[72:75], v[150:153], v[182:185], v[72:75]
	v_mfma_f32_16x16x32_bf16 v[100:103], v[142:145], v[230:233], v[100:103]
	v_mfma_f32_16x16x32_bf16 v[68:71], v[150:153], v[230:233], v[68:71]
	v_mfma_f32_16x16x32_bf16 v[88:91], v[142:145], v[238:241], v[88:91]
	v_mfma_f32_16x16x32_bf16 v[60:63], v[150:153], v[238:241], v[60:63]
	v_mfma_f32_16x16x32_bf16 v[44:47], v[154:157], v[170:173], v[44:47]
	v_mfma_f32_16x16x32_bf16 v[12:15], v[162:165], v[170:173], v[12:15]
	v_mfma_f32_16x16x32_bf16 v[40:43], v[154:157], v[178:181], v[40:43]
	v_mfma_f32_16x16x32_bf16 v[8:11], v[162:165], v[178:181], v[8:11]
	v_mfma_f32_16x16x32_bf16 v[32:35], v[154:157], v[192:195], v[32:35]
	v_mfma_f32_16x16x32_bf16 v[4:7], v[162:165], v[192:195], v[4:7]
	v_mfma_f32_16x16x32_bf16 v[28:31], v[154:157], v[234:237], v[28:31]
	v_mfma_f32_16x16x32_bf16 v[0:3], v[162:165], v[234:237], v[0:3]
	v_mfma_f32_16x16x32_bf16 v[44:47], v[158:161], v[174:177], v[44:47]
	v_mfma_f32_16x16x32_bf16 v[12:15], v[166:169], v[174:177], v[12:15]
	v_mfma_f32_16x16x32_bf16 v[40:43], v[158:161], v[182:185], v[40:43]
	v_mfma_f32_16x16x32_bf16 v[8:11], v[166:169], v[182:185], v[8:11]
	v_mfma_f32_16x16x32_bf16 v[32:35], v[158:161], v[230:233], v[32:35]
	v_mfma_f32_16x16x32_bf16 v[4:7], v[166:169], v[230:233], v[4:7]
	v_mfma_f32_16x16x32_bf16 v[28:31], v[158:161], v[238:241], v[28:31]
	v_mfma_f32_16x16x32_bf16 v[0:3], v[166:169], v[238:241], v[0:3]
	s_barrier
	s_add_i32 s67, s67, 2
	s_add_u32 s65, s65, 0x100
	s_addc_u32 s66, s66, 0
	s_cmp_gt_u32 s67, 41
	s_mov_b64 s[22:23], s[24:25]
	s_cbranch_scc0 .LBB0_1993
	s_setprio 0
	s_and_b64 vcc, exec, s[14:15]
	s_cbranch_vccz .LBB0_1996
	s_barrier
